# v102 + K-loop load segments re-ordered: the LDS fragment reads are interleaved between the m0 writes and the LDS-DMA issues (no s_nop separators), waits merged into one s_waitcnt
# baseline (speedup 1.0000x reference)
; #define PG8_STAGE(bufoff, gbase, voff) do { _Pragma("unroll") for (int _i = 0; _i < 2; ++_i) \
;         __builtin_amdgcn_global_load_lds((const unsigned*)((const char*)(gbase) + (voff)[_i]), (PG8_LAS unsigned*)(lds + (bufoff) + ldsw + _i * 8192), 16, 0, 0); } while (0)
; #define PG8_LDA(dst, b, h) do { _Pragma("unroll") for (int m = 0; m < 4; ++m) _Pragma("unroll") for (int k = 0; k < 2; ++k) dst[m][k] = *(const PG8_LAS bf16x8*)(lds + PG8_SA(b, h) + aoff + m * 2048 + k * 1024); } while (0)
; #define PG8_LDB(dst, b, h) do { _Pragma("unroll") for (int n = 0; n < 2; ++n) _Pragma("unroll") for (int k = 0; k < 2; ++k) dst[n][k] = *(const PG8_LAS bf16x8*)(lds + PG8_SB(b, h) + boff + n * 2048 + k * 1024); } while (0)
; #define PG8_MMA(ai, bj, At, Bt) do { __builtin_amdgcn_s_setprio(1); _Pragma("unroll") for (int m = 0; m < 4; ++m) _Pragma("unroll") for (int n = 0; n < 2; ++n) _Pragma("unroll") for (int k = 0; k < 2; ++k) \
;         acc[ai][bj][m][n] = __builtin_amdgcn_mfma_f32_16x16x32_bf16(Bt[n][k], At[m][k], acc[ai][bj][m][n], 0, 0, 0); __builtin_amdgcn_s_setprio(0); } while (0)
; #define PG8_WAIT_V(n) asm volatile("s_waitcnt vmcnt(" #n ")" ::: "memory")
; #define PG8_WAIT_L(n) asm volatile("s_waitcnt lgkmcnt(" #n ")" ::: "memory")
; template <class Epi, class Sched, bool ALIGN_EPI = false, bool SP2 = false>
; __device__ __forceinline__ void gemm_phase(PG8_LAS unsigned char* lds, const Gemm g, const Sched& S, const Epi& E) {
;     ...
;             const bool last = (t == nt - 2);
;             const char* a1 = cA + (size_t)(t + 1) * kstep;
;             const char* a2 = last ? nA : cA + (size_t)(t + 2) * kstep; const char* b2 = last ? nB : cB + (size_t)(t + 2) * kstep;
;             const char* a3 = a2 + kstep; const char* b3 = b2 + kstep;
;             if (last && has_next) S.a_ready(nxt);
;             if constexpr (SP2) {
;             PG8_LDB(B0, 0, 0); PG8_LDB(B1, 0, 1); PG8_SCHED; PG8_LDA(At, 0, 0); PG8_STAGE(PG8_SA(1, 1), a1 + hstep, voffA);
;             PG8_WAIT_V(8); PG8_WAIT_L(0); PG8_BAR; PG8_MMA(0, 0, At, B0); PG8_MMA(0, 1, At, B1); PG8_BAR; PG8_SCHED;
;             PG8_LDA(At, 0, 1); PG8_STAGE(PG8_SB(0, 0), b2, voffB); PG8_STAGE(PG8_SB(0, 1), b2 + hstep, voffB); PG8_STAGE(PG8_SA(0, 0), a2, voffA);
;             PG8_WAIT_V(8); PG8_WAIT_L(0); PG8_BAR; PG8_MMA(1, 0, At, B0); PG8_MMA(1, 1, At, B1); PG8_BAR; PG8_SCHED;
.Labo_peel:
	s_add_u32 s2, s0, 0xfffc0080
	s_addc_u32 s3, s1, -1
	s_cmp_eq_u32 s56, 12
	s_cselect_b32 s5, s27, s3
	s_cselect_b32 s4, s52, s2
	s_cselect_b32 s3, s25, s55
	s_cselect_b32 s2, s53, s54
	s_add_i32 m0, s29, 0xc000
	ds_read_b128 v[68:71], v254
	ds_read_b128 v[72:75], v254 offset:1024
	ds_read_b128 v[76:79], v254 offset:2048
	ds_read_b128 v[80:83], v254 offset:3072
	ds_read_b128 v[174:177], v254 offset:16384
	ds_read_b128 v[182:185], v254 offset:17408
	ds_read_b128 v[186:189], v254 offset:18432
	ds_read_b128 v[210:213], v254 offset:19456
	global_load_lds_dwordx4 v170, s[0:1]
	s_add_i32 m0, s29, 0xe000
	ds_read_b128 v[214:217], v179
	ds_read_b128 v[218:221], v179 offset:1024
	ds_read_b128 v[222:225], v179 offset:2048
	ds_read_b128 v[226:229], v179 offset:3072
	ds_read_b128 v[230:233], v179 offset:4096
	ds_read_b128 v[234:237], v179 offset:5120
	ds_read_b128 v[238:241], v179 offset:6144
	ds_read_b128 v[242:245], v179 offset:7168
	global_load_lds_dwordx4 v172, s[0:1]
	s_waitcnt vmcnt(8) lgkmcnt(0)
	s_barrier
	s_setprio 1
	v_mfma_f32_16x16x32_bf16 v[140:143], v[68:71], v[214:217], 0
	v_mfma_f32_16x16x32_bf16 v[140:143], v[72:75], v[218:221], v[140:143]
	v_mfma_f32_16x16x32_bf16 v[124:127], v[68:71], v[222:225], 0
	v_mfma_f32_16x16x32_bf16 v[124:127], v[72:75], v[226:229], v[124:127]
	v_mfma_f32_16x16x32_bf16 v[108:111], v[68:71], v[230:233], 0
	v_mfma_f32_16x16x32_bf16 v[108:111], v[72:75], v[234:237], v[108:111]
	v_mfma_f32_16x16x32_bf16 v[92:95], v[68:71], v[238:241], 0
	v_mfma_f32_16x16x32_bf16 v[92:95], v[72:75], v[242:245], v[92:95]
	v_mfma_f32_16x16x32_bf16 v[136:139], v[76:79], v[214:217], 0
	v_mfma_f32_16x16x32_bf16 v[136:139], v[80:83], v[218:221], v[136:139]
	v_mfma_f32_16x16x32_bf16 v[120:123], v[76:79], v[222:225], 0
	v_mfma_f32_16x16x32_bf16 v[120:123], v[80:83], v[226:229], v[120:123]
	v_mfma_f32_16x16x32_bf16 v[104:107], v[76:79], v[230:233], 0
	v_mfma_f32_16x16x32_bf16 v[104:107], v[80:83], v[234:237], v[104:107]
	v_mfma_f32_16x16x32_bf16 v[88:91], v[76:79], v[238:241], 0
	v_mfma_f32_16x16x32_bf16 v[88:91], v[80:83], v[242:245], v[88:91]
	v_mfma_f32_16x16x32_bf16 v[132:135], v[174:177], v[214:217], 0
	v_mfma_f32_16x16x32_bf16 v[132:135], v[182:185], v[218:221], v[132:135]
	v_mfma_f32_16x16x32_bf16 v[116:119], v[174:177], v[222:225], 0
	v_mfma_f32_16x16x32_bf16 v[116:119], v[182:185], v[226:229], v[116:119]
	v_mfma_f32_16x16x32_bf16 v[100:103], v[174:177], v[230:233], 0
	v_mfma_f32_16x16x32_bf16 v[100:103], v[182:185], v[234:237], v[100:103]
	v_mfma_f32_16x16x32_bf16 v[84:87], v[174:177], v[238:241], 0
	v_mfma_f32_16x16x32_bf16 v[84:87], v[182:185], v[242:245], v[84:87]
	v_mfma_f32_16x16x32_bf16 v[128:131], v[186:189], v[214:217], 0
	v_mfma_f32_16x16x32_bf16 v[128:131], v[210:213], v[218:221], v[128:131]
	v_mfma_f32_16x16x32_bf16 v[112:115], v[186:189], v[222:225], 0
	v_mfma_f32_16x16x32_bf16 v[112:115], v[210:213], v[226:229], v[112:115]
	v_mfma_f32_16x16x32_bf16 v[96:99], v[186:189], v[230:233], 0
	v_mfma_f32_16x16x32_bf16 v[96:99], v[210:213], v[234:237], v[96:99]
	v_mfma_f32_16x16x32_bf16 v[64:67], v[186:189], v[238:241], 0
	v_mfma_f32_16x16x32_bf16 v[64:67], v[210:213], v[242:245], v[64:67]
	s_setprio 0
	s_barrier
	s_mov_b32 m0, s30
	s_add_u32 s58, s2, 0x40000
	s_addc_u32 s59, s3, 0
	ds_read_b128 v[214:217], v179 offset:16384
	ds_read_b128 v[218:221], v179 offset:17408
	global_load_lds_dwordx4 v166, s[2:3]
	s_mov_b32 m0, s31
	ds_read_b128 v[222:225], v179 offset:18432
	ds_read_b128 v[226:229], v179 offset:19456
	global_load_lds_dwordx4 v162, s[2:3]
	s_mov_b32 m0, s33
	ds_read_b128 v[230:233], v179 offset:20480
	global_load_lds_dwordx4 v166, s[58:59]
	s_mov_b32 m0, s34
	ds_read_b128 v[234:237], v179 offset:21504
	global_load_lds_dwordx4 v162, s[58:59]
	s_mov_b32 m0, s29
	ds_read_b128 v[238:241], v179 offset:22528
	global_load_lds_dwordx4 v168, s[4:5]
	s_mov_b32 m0, s35
	ds_read_b128 v[242:245], v179 offset:23552
	global_load_lds_dwordx4 v164, s[4:5]
	s_waitcnt vmcnt(8) lgkmcnt(0)
	s_barrier
	s_setprio 1
	v_mfma_f32_16x16x32_bf16 v[60:63], v[68:71], v[214:217], 0
	v_mfma_f32_16x16x32_bf16 v[60:63], v[72:75], v[218:221], v[60:63]
	v_mfma_f32_16x16x32_bf16 v[44:47], v[68:71], v[222:225], 0
	v_mfma_f32_16x16x32_bf16 v[44:47], v[72:75], v[226:229], v[44:47]
	v_mfma_f32_16x16x32_bf16 v[28:31], v[68:71], v[230:233], 0
	v_mfma_f32_16x16x32_bf16 v[28:31], v[72:75], v[234:237], v[28:31]
	v_mfma_f32_16x16x32_bf16 v[12:15], v[68:71], v[238:241], 0
	v_mfma_f32_16x16x32_bf16 v[12:15], v[72:75], v[242:245], v[12:15]
	v_mfma_f32_16x16x32_bf16 v[56:59], v[76:79], v[214:217], 0
	v_mfma_f32_16x16x32_bf16 v[56:59], v[80:83], v[218:221], v[56:59]
	v_mfma_f32_16x16x32_bf16 v[40:43], v[76:79], v[222:225], 0
	v_mfma_f32_16x16x32_bf16 v[40:43], v[80:83], v[226:229], v[40:43]
	v_mfma_f32_16x16x32_bf16 v[24:27], v[76:79], v[230:233], 0
	v_mfma_f32_16x16x32_bf16 v[24:27], v[80:83], v[234:237], v[24:27]
	v_mfma_f32_16x16x32_bf16 v[8:11], v[76:79], v[238:241], 0
	v_mfma_f32_16x16x32_bf16 v[8:11], v[80:83], v[242:245], v[8:11]
	v_mfma_f32_16x16x32_bf16 v[52:55], v[174:177], v[214:217], 0
	v_mfma_f32_16x16x32_bf16 v[52:55], v[182:185], v[218:221], v[52:55]
	v_mfma_f32_16x16x32_bf16 v[36:39], v[174:177], v[222:225], 0
	v_mfma_f32_16x16x32_bf16 v[36:39], v[182:185], v[226:229], v[36:39]
	v_mfma_f32_16x16x32_bf16 v[20:23], v[174:177], v[230:233], 0
	v_mfma_f32_16x16x32_bf16 v[20:23], v[182:185], v[234:237], v[20:23]
	v_mfma_f32_16x16x32_bf16 v[4:7], v[174:177], v[238:241], 0
	v_mfma_f32_16x16x32_bf16 v[4:7], v[182:185], v[242:245], v[4:7]
	v_mfma_f32_16x16x32_bf16 v[48:51], v[186:189], v[214:217], 0
	v_mfma_f32_16x16x32_bf16 v[48:51], v[210:213], v[218:221], v[48:51]
	v_mfma_f32_16x16x32_bf16 v[32:35], v[186:189], v[222:225], 0
	v_mfma_f32_16x16x32_bf16 v[32:35], v[210:213], v[226:229], v[32:35]
	v_mfma_f32_16x16x32_bf16 v[16:19], v[186:189], v[230:233], 0
	v_mfma_f32_16x16x32_bf16 v[16:19], v[210:213], v[234:237], v[16:19]
	v_mfma_f32_16x16x32_bf16 v[0:3], v[186:189], v[238:241], 0
	v_mfma_f32_16x16x32_bf16 v[0:3], v[210:213], v[242:245], v[0:3]
	s_setprio 0
	s_barrier
; #define PG8_STAGE(bufoff, gbase, voff) do { _Pragma("unroll") for (int _i = 0; _i < 2; ++_i) \
;         __builtin_amdgcn_global_load_lds((const unsigned*)((const char*)(gbase) + (voff)[_i]), (PG8_LAS unsigned*)(lds + (bufoff) + ldsw + _i * 8192), 16, 0, 0); } while (0)
; #define PG8_LDA(dst, b, h) do { _Pragma("unroll") for (int m = 0; m < 4; ++m) _Pragma("unroll") for (int k = 0; k < 2; ++k) dst[m][k] = *(const PG8_LAS bf16x8*)(lds + PG8_SA(b, h) + aoff + m * 2048 + k * 1024); } while (0)
; #define PG8_LDB(dst, b, h) do { _Pragma("unroll") for (int n = 0; n < 2; ++n) _Pragma("unroll") for (int k = 0; k < 2; ++k) dst[n][k] = *(const PG8_LAS bf16x8*)(lds + PG8_SB(b, h) + boff + n * 2048 + k * 1024); } while (0)
; #define PG8_MMA(ai, bj, At, Bt) do { __builtin_amdgcn_s_setprio(1); _Pragma("unroll") for (int m = 0; m < 4; ++m) _Pragma("unroll") for (int n = 0; n < 2; ++n) _Pragma("unroll") for (int k = 0; k < 2; ++k) \
;         acc[ai][bj][m][n] = __builtin_amdgcn_mfma_f32_16x16x32_bf16(Bt[n][k], At[m][k], acc[ai][bj][m][n], 0, 0, 0); __builtin_amdgcn_s_setprio(0); } while (0)
; #define PG8_WAIT_V(n) asm volatile("s_waitcnt vmcnt(" #n ")" ::: "memory")
; #define PG8_WAIT_L(n) asm volatile("s_waitcnt lgkmcnt(" #n ")" ::: "memory")
; #define PG8_BAR __builtin_amdgcn_s_barrier()
; #define PG8_SCHED __builtin_amdgcn_sched_barrier(0)
; template <class Epi, class Sched, bool ALIGN_EPI = false, bool SP2 = false>
; __device__ __forceinline__ void gemm_phase(PG8_LAS unsigned char* lds, const Gemm g, const Sched& S, const Epi& E) {
;     ...
;             PG8_LDB(B0, 1, 0); PG8_LDB(B1, 1, 1); PG8_SCHED; PG8_LDA(At, 1, 0); PG8_STAGE(PG8_SA(0, 1), a2 + hstep, voffA);
;             PG8_WAIT_V(8); PG8_WAIT_L(0); PG8_BAR; PG8_MMA(0, 0, At, B0); PG8_MMA(0, 1, At, B1); PG8_BAR; PG8_SCHED;
;             PG8_LDA(At, 1, 1); PG8_STAGE(PG8_SB(1, 0), b3, voffB); PG8_STAGE(PG8_SB(1, 1), b3 + hstep, voffB); PG8_STAGE(PG8_SA(1, 0), a3, voffA);
;             PG8_WAIT_V(8); PG8_WAIT_L(0); PG8_BAR; PG8_MMA(1, 0, At, B0); PG8_MMA(1, 1, At, B1); PG8_BAR; PG8_SCHED;
	s_add_u32 s4, s4, 0x40000
	s_addc_u32 s5, s5, 0
	s_mov_b32 m0, s40
	ds_read_b128 v[68:71], v254 offset:32768
	ds_read_b128 v[72:75], v254 offset:33792
	ds_read_b128 v[76:79], v254 offset:34816
	ds_read_b128 v[80:83], v254 offset:35840
	ds_read_b128 v[174:177], v254 offset:49152
	ds_read_b128 v[182:185], v254 offset:50176
	ds_read_b128 v[186:189], v254 offset:51200
	ds_read_b128 v[210:213], v254 offset:52224
	global_load_lds_dwordx4 v168, s[4:5]
	s_mov_b32 m0, s41
	ds_read_b128 v[214:217], v179 offset:32768
	ds_read_b128 v[218:221], v179 offset:33792
	ds_read_b128 v[222:225], v179 offset:34816
	ds_read_b128 v[226:229], v179 offset:35840
	ds_read_b128 v[230:233], v179 offset:36864
	ds_read_b128 v[234:237], v179 offset:37888
	ds_read_b128 v[238:241], v179 offset:38912
	ds_read_b128 v[242:245], v179 offset:39936
	global_load_lds_dwordx4 v164, s[4:5]
	s_waitcnt vmcnt(8) lgkmcnt(0)
	s_barrier
	s_setprio 1
	v_mfma_f32_16x16x32_bf16 v[140:143], v[68:71], v[214:217], v[140:143]
	v_mfma_f32_16x16x32_bf16 v[140:143], v[72:75], v[218:221], v[140:143]
	v_mfma_f32_16x16x32_bf16 v[124:127], v[68:71], v[222:225], v[124:127]
	v_mfma_f32_16x16x32_bf16 v[124:127], v[72:75], v[226:229], v[124:127]
	v_mfma_f32_16x16x32_bf16 v[108:111], v[68:71], v[230:233], v[108:111]
	v_mfma_f32_16x16x32_bf16 v[108:111], v[72:75], v[234:237], v[108:111]
	v_mfma_f32_16x16x32_bf16 v[92:95], v[68:71], v[238:241], v[92:95]
	v_mfma_f32_16x16x32_bf16 v[92:95], v[72:75], v[242:245], v[92:95]
	v_mfma_f32_16x16x32_bf16 v[136:139], v[76:79], v[214:217], v[136:139]
	v_mfma_f32_16x16x32_bf16 v[136:139], v[80:83], v[218:221], v[136:139]
	v_mfma_f32_16x16x32_bf16 v[120:123], v[76:79], v[222:225], v[120:123]
	v_mfma_f32_16x16x32_bf16 v[120:123], v[80:83], v[226:229], v[120:123]
	v_mfma_f32_16x16x32_bf16 v[104:107], v[76:79], v[230:233], v[104:107]
	v_mfma_f32_16x16x32_bf16 v[104:107], v[80:83], v[234:237], v[104:107]
	v_mfma_f32_16x16x32_bf16 v[88:91], v[76:79], v[238:241], v[88:91]
	v_mfma_f32_16x16x32_bf16 v[88:91], v[80:83], v[242:245], v[88:91]
	v_mfma_f32_16x16x32_bf16 v[132:135], v[174:177], v[214:217], v[132:135]
	v_mfma_f32_16x16x32_bf16 v[132:135], v[182:185], v[218:221], v[132:135]
	v_mfma_f32_16x16x32_bf16 v[116:119], v[174:177], v[222:225], v[116:119]
	v_mfma_f32_16x16x32_bf16 v[116:119], v[182:185], v[226:229], v[116:119]
	v_mfma_f32_16x16x32_bf16 v[100:103], v[174:177], v[230:233], v[100:103]
	v_mfma_f32_16x16x32_bf16 v[100:103], v[182:185], v[234:237], v[100:103]
	v_mfma_f32_16x16x32_bf16 v[84:87], v[174:177], v[238:241], v[84:87]
	v_mfma_f32_16x16x32_bf16 v[84:87], v[182:185], v[242:245], v[84:87]
	v_mfma_f32_16x16x32_bf16 v[128:131], v[186:189], v[214:217], v[128:131]
	v_mfma_f32_16x16x32_bf16 v[128:131], v[210:213], v[218:221], v[128:131]
	v_mfma_f32_16x16x32_bf16 v[112:115], v[186:189], v[222:225], v[112:115]
	v_mfma_f32_16x16x32_bf16 v[112:115], v[210:213], v[226:229], v[112:115]
	v_mfma_f32_16x16x32_bf16 v[96:99], v[186:189], v[230:233], v[96:99]
	v_mfma_f32_16x16x32_bf16 v[96:99], v[210:213], v[234:237], v[96:99]
	v_mfma_f32_16x16x32_bf16 v[64:67], v[186:189], v[238:241], v[64:67]
	v_mfma_f32_16x16x32_bf16 v[64:67], v[210:213], v[242:245], v[64:67]
	s_setprio 0
	s_barrier
	s_mov_b32 m0, s45
	s_add_u32 s2, s2, 0x40080
	s_addc_u32 s3, s3, 0
	s_add_u32 s98, s2, 0xfffc0000
	s_addc_u32 s99, s3, -1
	ds_read_b128 v[214:217], v179 offset:49152
	ds_read_b128 v[218:221], v179 offset:50176
	global_load_lds_dwordx4 v166, s[98:99]
	s_mov_b32 m0, s46
	ds_read_b128 v[222:225], v179 offset:51200
	ds_read_b128 v[226:229], v179 offset:52224
	global_load_lds_dwordx4 v162, s[98:99]
	s_mov_b32 m0, s49
	ds_read_b128 v[230:233], v179 offset:53248
	global_load_lds_dwordx4 v166, s[2:3]
	s_mov_b32 m0, s50
	ds_read_b128 v[234:237], v179 offset:54272
	global_load_lds_dwordx4 v162, s[2:3]
	s_mov_b32 m0, s47
	s_add_u32 s100, s4, 0xfffc0080
	s_addc_u32 s101, s5, -1
	ds_read_b128 v[238:241], v179 offset:55296
	global_load_lds_dwordx4 v168, s[100:101]
	s_mov_b32 m0, s48
	ds_read_b128 v[242:245], v179 offset:56320
	global_load_lds_dwordx4 v164, s[100:101]
	s_waitcnt vmcnt(8) lgkmcnt(0)
	s_barrier
	s_setprio 1
	v_mfma_f32_16x16x32_bf16 v[60:63], v[68:71], v[214:217], v[60:63]
	v_mfma_f32_16x16x32_bf16 v[60:63], v[72:75], v[218:221], v[60:63]
	v_mfma_f32_16x16x32_bf16 v[44:47], v[68:71], v[222:225], v[44:47]
	v_mfma_f32_16x16x32_bf16 v[44:47], v[72:75], v[226:229], v[44:47]
	v_mfma_f32_16x16x32_bf16 v[28:31], v[68:71], v[230:233], v[28:31]
	v_mfma_f32_16x16x32_bf16 v[28:31], v[72:75], v[234:237], v[28:31]
	v_mfma_f32_16x16x32_bf16 v[12:15], v[68:71], v[238:241], v[12:15]
	v_mfma_f32_16x16x32_bf16 v[12:15], v[72:75], v[242:245], v[12:15]
	v_mfma_f32_16x16x32_bf16 v[56:59], v[76:79], v[214:217], v[56:59]
	v_mfma_f32_16x16x32_bf16 v[56:59], v[80:83], v[218:221], v[56:59]
	v_mfma_f32_16x16x32_bf16 v[40:43], v[76:79], v[222:225], v[40:43]
	v_mfma_f32_16x16x32_bf16 v[40:43], v[80:83], v[226:229], v[40:43]
	v_mfma_f32_16x16x32_bf16 v[24:27], v[76:79], v[230:233], v[24:27]
	v_mfma_f32_16x16x32_bf16 v[24:27], v[80:83], v[234:237], v[24:27]
	v_mfma_f32_16x16x32_bf16 v[8:11], v[76:79], v[238:241], v[8:11]
	v_mfma_f32_16x16x32_bf16 v[8:11], v[80:83], v[242:245], v[8:11]
	v_mfma_f32_16x16x32_bf16 v[52:55], v[174:177], v[214:217], v[52:55]
	v_mfma_f32_16x16x32_bf16 v[52:55], v[182:185], v[218:221], v[52:55]
	v_mfma_f32_16x16x32_bf16 v[36:39], v[174:177], v[222:225], v[36:39]
	v_mfma_f32_16x16x32_bf16 v[36:39], v[182:185], v[226:229], v[36:39]
	v_mfma_f32_16x16x32_bf16 v[20:23], v[174:177], v[230:233], v[20:23]
	v_mfma_f32_16x16x32_bf16 v[20:23], v[182:185], v[234:237], v[20:23]
	v_mfma_f32_16x16x32_bf16 v[4:7], v[174:177], v[238:241], v[4:7]
	v_mfma_f32_16x16x32_bf16 v[4:7], v[182:185], v[242:245], v[4:7]
	v_mfma_f32_16x16x32_bf16 v[48:51], v[186:189], v[214:217], v[48:51]
	v_mfma_f32_16x16x32_bf16 v[48:51], v[210:213], v[218:221], v[48:51]
	v_mfma_f32_16x16x32_bf16 v[32:35], v[186:189], v[222:225], v[32:35]
	v_mfma_f32_16x16x32_bf16 v[32:35], v[210:213], v[226:229], v[32:35]
	v_mfma_f32_16x16x32_bf16 v[16:19], v[186:189], v[230:233], v[16:19]
	v_mfma_f32_16x16x32_bf16 v[16:19], v[210:213], v[234:237], v[16:19]
	v_mfma_f32_16x16x32_bf16 v[0:3], v[186:189], v[238:241], v[0:3]
	v_mfma_f32_16x16x32_bf16 v[0:3], v[210:213], v[242:245], v[0:3]
	s_setprio 0
	s_barrier
	s_add_i32 s56, s56, 2
	s_add_u32 s0, s0, 0x100
	s_addc_u32 s1, s1, 0
	s_add_u32 s54, s54, 0x100
	s_addc_u32 s55, s55, 0
	s_cmp_gt_u32 s56, 13
; #define PG8_STAGE(bufoff, gbase, voff) do { _Pragma("unroll") for (int _i = 0; _i < 2; ++_i) \
;         __builtin_amdgcn_global_load_lds((const unsigned*)((const char*)(gbase) + (voff)[_i]), (PG8_LAS unsigned*)(lds + (bufoff) + ldsw + _i * 8192), 16, 0, 0); } while (0)
; #define PG8_LDA(dst, b, h) do { _Pragma("unroll") for (int m = 0; m < 4; ++m) _Pragma("unroll") for (int k = 0; k < 2; ++k) dst[m][k] = *(const PG8_LAS bf16x8*)(lds + PG8_SA(b, h) + aoff + m * 2048 + k * 1024); } while (0)
; #define PG8_LDB(dst, b, h) do { _Pragma("unroll") for (int n = 0; n < 2; ++n) _Pragma("unroll") for (int k = 0; k < 2; ++k) dst[n][k] = *(const PG8_LAS bf16x8*)(lds + PG8_SB(b, h) + boff + n * 2048 + k * 1024); } while (0)
; #define PG8_MMA(ai, bj, At, Bt) do { __builtin_amdgcn_s_setprio(1); _Pragma("unroll") for (int m = 0; m < 4; ++m) _Pragma("unroll") for (int n = 0; n < 2; ++n) _Pragma("unroll") for (int k = 0; k < 2; ++k) \
;         acc[ai][bj][m][n] = __builtin_amdgcn_mfma_f32_16x16x32_bf16(Bt[n][k], At[m][k], acc[ai][bj][m][n], 0, 0, 0); __builtin_amdgcn_s_setprio(0); } while (0)
; #define PG8_WAIT_V(n) asm volatile("s_waitcnt vmcnt(" #n ")" ::: "memory")
; #define PG8_BAR __builtin_amdgcn_s_barrier()
; template <class Epi, class Sched, bool ALIGN_EPI = false, bool SP2 = false>
; __device__ __forceinline__ void gemm_phase(PG8_LAS unsigned char* lds, const Gemm g, const Sched& S, const Epi& E) {
;     ...
;         for (int t = 0; t < nt; t += 2) {
;             const bool last = (t == nt - 2);
;             const char* a1 = cA + (size_t)(t + 1) * kstep;
;             const char* a2 = last ? nA : cA + (size_t)(t + 2) * kstep; const char* b2 = last ? nB : cB + (size_t)(t + 2) * kstep;
;             const char* a3 = a2 + kstep; const char* b3 = b2 + kstep;
;             if (last && has_next) S.a_ready(nxt);
;             if constexpr (SP2) {
;             PG8_LDB(B0, 0, 0); PG8_LDB(B1, 0, 1); PG8_SCHED; PG8_LDA(At, 0, 0); PG8_STAGE(PG8_SA(1, 1), a1 + hstep, voffA);
;             PG8_WAIT_V(8); PG8_WAIT_L(0); PG8_BAR; PG8_MMA(0, 0, At, B0); PG8_MMA(0, 1, At, B1); PG8_BAR; PG8_SCHED;
;             PG8_LDA(At, 0, 1); PG8_STAGE(PG8_SB(0, 0), b2, voffB); PG8_STAGE(PG8_SB(0, 1), b2 + hstep, voffB); PG8_STAGE(PG8_SA(0, 0), a2, voffA);
;             PG8_WAIT_V(8); PG8_WAIT_L(0); PG8_BAR; PG8_MMA(1, 0, At, B0); PG8_MMA(1, 1, At, B1); PG8_BAR; PG8_SCHED;
.LBB0_327:
	s_add_u32 s2, s0, 0xfffc0080
	s_addc_u32 s3, s1, -1
	s_cmp_eq_u32 s56, 12
	s_cselect_b32 s5, s27, s3
	s_cselect_b32 s4, s52, s2
	s_cselect_b32 s3, s25, s55
	s_cselect_b32 s2, s53, s54
	s_add_i32 m0, s29, 0xc000
	ds_read_b128 v[68:71], v254
	ds_read_b128 v[72:75], v254 offset:1024
	ds_read_b128 v[76:79], v254 offset:2048
	ds_read_b128 v[80:83], v254 offset:3072
	ds_read_b128 v[174:177], v254 offset:16384
	ds_read_b128 v[182:185], v254 offset:17408
	ds_read_b128 v[186:189], v254 offset:18432
	ds_read_b128 v[210:213], v254 offset:19456
	global_load_lds_dwordx4 v170, s[0:1]
	s_add_i32 m0, s29, 0xe000
	ds_read_b128 v[214:217], v179
	ds_read_b128 v[218:221], v179 offset:1024
	ds_read_b128 v[222:225], v179 offset:2048
	ds_read_b128 v[226:229], v179 offset:3072
	ds_read_b128 v[230:233], v179 offset:4096
	ds_read_b128 v[234:237], v179 offset:5120
	ds_read_b128 v[238:241], v179 offset:6144
	ds_read_b128 v[242:245], v179 offset:7168
	global_load_lds_dwordx4 v172, s[0:1]
	s_waitcnt vmcnt(8) lgkmcnt(0)
	s_barrier
	s_setprio 1
	v_mfma_f32_16x16x32_bf16 v[140:143], v[68:71], v[214:217], v[140:143]
	v_mfma_f32_16x16x32_bf16 v[140:143], v[72:75], v[218:221], v[140:143]
	v_mfma_f32_16x16x32_bf16 v[124:127], v[68:71], v[222:225], v[124:127]
	v_mfma_f32_16x16x32_bf16 v[124:127], v[72:75], v[226:229], v[124:127]
	v_mfma_f32_16x16x32_bf16 v[108:111], v[68:71], v[230:233], v[108:111]
	v_mfma_f32_16x16x32_bf16 v[108:111], v[72:75], v[234:237], v[108:111]
	v_mfma_f32_16x16x32_bf16 v[92:95], v[68:71], v[238:241], v[92:95]
	v_mfma_f32_16x16x32_bf16 v[92:95], v[72:75], v[242:245], v[92:95]
	v_mfma_f32_16x16x32_bf16 v[136:139], v[76:79], v[214:217], v[136:139]
	v_mfma_f32_16x16x32_bf16 v[136:139], v[80:83], v[218:221], v[136:139]
	v_mfma_f32_16x16x32_bf16 v[120:123], v[76:79], v[222:225], v[120:123]
	v_mfma_f32_16x16x32_bf16 v[120:123], v[80:83], v[226:229], v[120:123]
	v_mfma_f32_16x16x32_bf16 v[104:107], v[76:79], v[230:233], v[104:107]
	v_mfma_f32_16x16x32_bf16 v[104:107], v[80:83], v[234:237], v[104:107]
	v_mfma_f32_16x16x32_bf16 v[88:91], v[76:79], v[238:241], v[88:91]
	v_mfma_f32_16x16x32_bf16 v[88:91], v[80:83], v[242:245], v[88:91]
	v_mfma_f32_16x16x32_bf16 v[132:135], v[174:177], v[214:217], v[132:135]
	v_mfma_f32_16x16x32_bf16 v[132:135], v[182:185], v[218:221], v[132:135]
	v_mfma_f32_16x16x32_bf16 v[116:119], v[174:177], v[222:225], v[116:119]
	v_mfma_f32_16x16x32_bf16 v[116:119], v[182:185], v[226:229], v[116:119]
	v_mfma_f32_16x16x32_bf16 v[100:103], v[174:177], v[230:233], v[100:103]
	v_mfma_f32_16x16x32_bf16 v[100:103], v[182:185], v[234:237], v[100:103]
	v_mfma_f32_16x16x32_bf16 v[84:87], v[174:177], v[238:241], v[84:87]
	v_mfma_f32_16x16x32_bf16 v[84:87], v[182:185], v[242:245], v[84:87]
	v_mfma_f32_16x16x32_bf16 v[128:131], v[186:189], v[214:217], v[128:131]
	v_mfma_f32_16x16x32_bf16 v[128:131], v[210:213], v[218:221], v[128:131]
	v_mfma_f32_16x16x32_bf16 v[112:115], v[186:189], v[222:225], v[112:115]
	v_mfma_f32_16x16x32_bf16 v[112:115], v[210:213], v[226:229], v[112:115]
	v_mfma_f32_16x16x32_bf16 v[96:99], v[186:189], v[230:233], v[96:99]
	v_mfma_f32_16x16x32_bf16 v[96:99], v[210:213], v[234:237], v[96:99]
	v_mfma_f32_16x16x32_bf16 v[64:67], v[186:189], v[238:241], v[64:67]
	v_mfma_f32_16x16x32_bf16 v[64:67], v[210:213], v[242:245], v[64:67]
	s_setprio 0
	s_barrier
	s_mov_b32 m0, s30
	s_add_u32 s58, s2, 0x40000
	s_addc_u32 s59, s3, 0
	ds_read_b128 v[214:217], v179 offset:16384
	ds_read_b128 v[218:221], v179 offset:17408
	global_load_lds_dwordx4 v166, s[2:3]
	s_mov_b32 m0, s31
	ds_read_b128 v[222:225], v179 offset:18432
	ds_read_b128 v[226:229], v179 offset:19456
	global_load_lds_dwordx4 v162, s[2:3]
	s_mov_b32 m0, s33
	ds_read_b128 v[230:233], v179 offset:20480
	global_load_lds_dwordx4 v166, s[58:59]
	s_mov_b32 m0, s34
	ds_read_b128 v[234:237], v179 offset:21504
	global_load_lds_dwordx4 v162, s[58:59]
	s_mov_b32 m0, s29
	ds_read_b128 v[238:241], v179 offset:22528
	global_load_lds_dwordx4 v168, s[4:5]
	s_mov_b32 m0, s35
	ds_read_b128 v[242:245], v179 offset:23552
	global_load_lds_dwordx4 v164, s[4:5]
	s_waitcnt vmcnt(8) lgkmcnt(0)
	s_barrier
	s_setprio 1
	v_mfma_f32_16x16x32_bf16 v[60:63], v[68:71], v[214:217], v[60:63]
	v_mfma_f32_16x16x32_bf16 v[60:63], v[72:75], v[218:221], v[60:63]
	v_mfma_f32_16x16x32_bf16 v[44:47], v[68:71], v[222:225], v[44:47]
	v_mfma_f32_16x16x32_bf16 v[44:47], v[72:75], v[226:229], v[44:47]
	v_mfma_f32_16x16x32_bf16 v[28:31], v[68:71], v[230:233], v[28:31]
	v_mfma_f32_16x16x32_bf16 v[28:31], v[72:75], v[234:237], v[28:31]
	v_mfma_f32_16x16x32_bf16 v[12:15], v[68:71], v[238:241], v[12:15]
	v_mfma_f32_16x16x32_bf16 v[12:15], v[72:75], v[242:245], v[12:15]
	v_mfma_f32_16x16x32_bf16 v[56:59], v[76:79], v[214:217], v[56:59]
	v_mfma_f32_16x16x32_bf16 v[56:59], v[80:83], v[218:221], v[56:59]
	v_mfma_f32_16x16x32_bf16 v[40:43], v[76:79], v[222:225], v[40:43]
	v_mfma_f32_16x16x32_bf16 v[40:43], v[80:83], v[226:229], v[40:43]
	v_mfma_f32_16x16x32_bf16 v[24:27], v[76:79], v[230:233], v[24:27]
	v_mfma_f32_16x16x32_bf16 v[24:27], v[80:83], v[234:237], v[24:27]
	v_mfma_f32_16x16x32_bf16 v[8:11], v[76:79], v[238:241], v[8:11]
	v_mfma_f32_16x16x32_bf16 v[8:11], v[80:83], v[242:245], v[8:11]
	v_mfma_f32_16x16x32_bf16 v[52:55], v[174:177], v[214:217], v[52:55]
	v_mfma_f32_16x16x32_bf16 v[52:55], v[182:185], v[218:221], v[52:55]
	v_mfma_f32_16x16x32_bf16 v[36:39], v[174:177], v[222:225], v[36:39]
	v_mfma_f32_16x16x32_bf16 v[36:39], v[182:185], v[226:229], v[36:39]
	v_mfma_f32_16x16x32_bf16 v[20:23], v[174:177], v[230:233], v[20:23]
	v_mfma_f32_16x16x32_bf16 v[20:23], v[182:185], v[234:237], v[20:23]
	v_mfma_f32_16x16x32_bf16 v[4:7], v[174:177], v[238:241], v[4:7]
	v_mfma_f32_16x16x32_bf16 v[4:7], v[182:185], v[242:245], v[4:7]
	v_mfma_f32_16x16x32_bf16 v[48:51], v[186:189], v[214:217], v[48:51]
	v_mfma_f32_16x16x32_bf16 v[48:51], v[210:213], v[218:221], v[48:51]
	v_mfma_f32_16x16x32_bf16 v[32:35], v[186:189], v[222:225], v[32:35]
	v_mfma_f32_16x16x32_bf16 v[32:35], v[210:213], v[226:229], v[32:35]
	v_mfma_f32_16x16x32_bf16 v[16:19], v[186:189], v[230:233], v[16:19]
	v_mfma_f32_16x16x32_bf16 v[16:19], v[210:213], v[234:237], v[16:19]
	v_mfma_f32_16x16x32_bf16 v[0:3], v[186:189], v[238:241], v[0:3]
	v_mfma_f32_16x16x32_bf16 v[0:3], v[210:213], v[242:245], v[0:3]
	s_setprio 0
	s_barrier
; #define PG8_STAGE(bufoff, gbase, voff) do { _Pragma("unroll") for (int _i = 0; _i < 2; ++_i) \
;         __builtin_amdgcn_global_load_lds((const unsigned*)((const char*)(gbase) + (voff)[_i]), (PG8_LAS unsigned*)(lds + (bufoff) + ldsw + _i * 8192), 16, 0, 0); } while (0)
; #define PG8_LDA(dst, b, h) do { _Pragma("unroll") for (int m = 0; m < 4; ++m) _Pragma("unroll") for (int k = 0; k < 2; ++k) dst[m][k] = *(const PG8_LAS bf16x8*)(lds + PG8_SA(b, h) + aoff + m * 2048 + k * 1024); } while (0)
; #define PG8_LDB(dst, b, h) do { _Pragma("unroll") for (int n = 0; n < 2; ++n) _Pragma("unroll") for (int k = 0; k < 2; ++k) dst[n][k] = *(const PG8_LAS bf16x8*)(lds + PG8_SB(b, h) + boff + n * 2048 + k * 1024); } while (0)
; #define PG8_MMA(ai, bj, At, Bt) do { __builtin_amdgcn_s_setprio(1); _Pragma("unroll") for (int m = 0; m < 4; ++m) _Pragma("unroll") for (int n = 0; n < 2; ++n) _Pragma("unroll") for (int k = 0; k < 2; ++k) \
;         acc[ai][bj][m][n] = __builtin_amdgcn_mfma_f32_16x16x32_bf16(Bt[n][k], At[m][k], acc[ai][bj][m][n], 0, 0, 0); __builtin_amdgcn_s_setprio(0); } while (0)
; #define PG8_WAIT_V(n) asm volatile("s_waitcnt vmcnt(" #n ")" ::: "memory")
; #define PG8_WAIT_L(n) asm volatile("s_waitcnt lgkmcnt(" #n ")" ::: "memory")
; #define PG8_BAR __builtin_amdgcn_s_barrier()
; #define PG8_SCHED __builtin_amdgcn_sched_barrier(0)
; template <class Epi, class Sched, bool ALIGN_EPI = false, bool SP2 = false>
; __device__ __forceinline__ void gemm_phase(PG8_LAS unsigned char* lds, const Gemm g, const Sched& S, const Epi& E) {
;     ...
;             PG8_LDB(B0, 1, 0); PG8_LDB(B1, 1, 1); PG8_SCHED; PG8_LDA(At, 1, 0); PG8_STAGE(PG8_SA(0, 1), a2 + hstep, voffA);
;             PG8_WAIT_V(8); PG8_WAIT_L(0); PG8_BAR; PG8_MMA(0, 0, At, B0); PG8_MMA(0, 1, At, B1); PG8_BAR; PG8_SCHED;
;             PG8_LDA(At, 1, 1); PG8_STAGE(PG8_SB(1, 0), b3, voffB); PG8_STAGE(PG8_SB(1, 1), b3 + hstep, voffB); PG8_STAGE(PG8_SA(1, 0), a3, voffA);
;             PG8_WAIT_V(8); PG8_WAIT_L(0); PG8_BAR; PG8_MMA(1, 0, At, B0); PG8_MMA(1, 1, At, B1); PG8_BAR; PG8_SCHED;
;     ...
;         if constexpr (ALIGN_EPI) { if (wr == 0) PG8_BAR; }
	s_add_u32 s4, s4, 0x40000
	s_addc_u32 s5, s5, 0
	s_mov_b32 m0, s40
	ds_read_b128 v[68:71], v254 offset:32768
	ds_read_b128 v[72:75], v254 offset:33792
	ds_read_b128 v[76:79], v254 offset:34816
	ds_read_b128 v[80:83], v254 offset:35840
	ds_read_b128 v[174:177], v254 offset:49152
	ds_read_b128 v[182:185], v254 offset:50176
	ds_read_b128 v[186:189], v254 offset:51200
	ds_read_b128 v[210:213], v254 offset:52224
	global_load_lds_dwordx4 v168, s[4:5]
	s_mov_b32 m0, s41
	ds_read_b128 v[214:217], v179 offset:32768
	ds_read_b128 v[218:221], v179 offset:33792
	ds_read_b128 v[222:225], v179 offset:34816
	ds_read_b128 v[226:229], v179 offset:35840
	ds_read_b128 v[230:233], v179 offset:36864
	ds_read_b128 v[234:237], v179 offset:37888
	ds_read_b128 v[238:241], v179 offset:38912
	ds_read_b128 v[242:245], v179 offset:39936
	global_load_lds_dwordx4 v164, s[4:5]
	s_waitcnt vmcnt(8) lgkmcnt(0)
	s_barrier
	s_setprio 1
	v_mfma_f32_16x16x32_bf16 v[140:143], v[68:71], v[214:217], v[140:143]
	v_mfma_f32_16x16x32_bf16 v[140:143], v[72:75], v[218:221], v[140:143]
	v_mfma_f32_16x16x32_bf16 v[124:127], v[68:71], v[222:225], v[124:127]
	v_mfma_f32_16x16x32_bf16 v[124:127], v[72:75], v[226:229], v[124:127]
	v_mfma_f32_16x16x32_bf16 v[108:111], v[68:71], v[230:233], v[108:111]
	v_mfma_f32_16x16x32_bf16 v[108:111], v[72:75], v[234:237], v[108:111]
	v_mfma_f32_16x16x32_bf16 v[92:95], v[68:71], v[238:241], v[92:95]
	v_mfma_f32_16x16x32_bf16 v[92:95], v[72:75], v[242:245], v[92:95]
	v_mfma_f32_16x16x32_bf16 v[136:139], v[76:79], v[214:217], v[136:139]
	v_mfma_f32_16x16x32_bf16 v[136:139], v[80:83], v[218:221], v[136:139]
	v_mfma_f32_16x16x32_bf16 v[120:123], v[76:79], v[222:225], v[120:123]
	v_mfma_f32_16x16x32_bf16 v[120:123], v[80:83], v[226:229], v[120:123]
	v_mfma_f32_16x16x32_bf16 v[104:107], v[76:79], v[230:233], v[104:107]
	v_mfma_f32_16x16x32_bf16 v[104:107], v[80:83], v[234:237], v[104:107]
	v_mfma_f32_16x16x32_bf16 v[88:91], v[76:79], v[238:241], v[88:91]
	v_mfma_f32_16x16x32_bf16 v[88:91], v[80:83], v[242:245], v[88:91]
	v_mfma_f32_16x16x32_bf16 v[132:135], v[174:177], v[214:217], v[132:135]
	v_mfma_f32_16x16x32_bf16 v[132:135], v[182:185], v[218:221], v[132:135]
	v_mfma_f32_16x16x32_bf16 v[116:119], v[174:177], v[222:225], v[116:119]
	v_mfma_f32_16x16x32_bf16 v[116:119], v[182:185], v[226:229], v[116:119]
	v_mfma_f32_16x16x32_bf16 v[100:103], v[174:177], v[230:233], v[100:103]
	v_mfma_f32_16x16x32_bf16 v[100:103], v[182:185], v[234:237], v[100:103]
	v_mfma_f32_16x16x32_bf16 v[84:87], v[174:177], v[238:241], v[84:87]
	v_mfma_f32_16x16x32_bf16 v[84:87], v[182:185], v[242:245], v[84:87]
	v_mfma_f32_16x16x32_bf16 v[128:131], v[186:189], v[214:217], v[128:131]
	v_mfma_f32_16x16x32_bf16 v[128:131], v[210:213], v[218:221], v[128:131]
	v_mfma_f32_16x16x32_bf16 v[112:115], v[186:189], v[222:225], v[112:115]
	v_mfma_f32_16x16x32_bf16 v[112:115], v[210:213], v[226:229], v[112:115]
	v_mfma_f32_16x16x32_bf16 v[96:99], v[186:189], v[230:233], v[96:99]
	v_mfma_f32_16x16x32_bf16 v[96:99], v[210:213], v[234:237], v[96:99]
	v_mfma_f32_16x16x32_bf16 v[64:67], v[186:189], v[238:241], v[64:67]
	v_mfma_f32_16x16x32_bf16 v[64:67], v[210:213], v[242:245], v[64:67]
	s_setprio 0
	s_barrier
	s_mov_b32 m0, s45
	s_add_u32 s2, s2, 0x40080
	s_addc_u32 s3, s3, 0
	s_add_u32 s98, s2, 0xfffc0000
	s_addc_u32 s99, s3, -1
	ds_read_b128 v[214:217], v179 offset:49152
	ds_read_b128 v[218:221], v179 offset:50176
	global_load_lds_dwordx4 v166, s[98:99]
	s_mov_b32 m0, s46
	ds_read_b128 v[222:225], v179 offset:51200
	ds_read_b128 v[226:229], v179 offset:52224
	global_load_lds_dwordx4 v162, s[98:99]
	s_mov_b32 m0, s49
	ds_read_b128 v[230:233], v179 offset:53248
	global_load_lds_dwordx4 v166, s[2:3]
	s_mov_b32 m0, s50
	ds_read_b128 v[234:237], v179 offset:54272
	global_load_lds_dwordx4 v162, s[2:3]
	s_mov_b32 m0, s47
	s_add_u32 s100, s4, 0xfffc0080
	s_addc_u32 s101, s5, -1
	ds_read_b128 v[238:241], v179 offset:55296
	global_load_lds_dwordx4 v168, s[100:101]
	s_mov_b32 m0, s48
	ds_read_b128 v[242:245], v179 offset:56320
	global_load_lds_dwordx4 v164, s[100:101]
	s_waitcnt vmcnt(8) lgkmcnt(0)
	s_barrier
	s_setprio 1
	v_mfma_f32_16x16x32_bf16 v[60:63], v[68:71], v[214:217], v[60:63]
	v_mfma_f32_16x16x32_bf16 v[60:63], v[72:75], v[218:221], v[60:63]
	v_mfma_f32_16x16x32_bf16 v[44:47], v[68:71], v[222:225], v[44:47]
	v_mfma_f32_16x16x32_bf16 v[44:47], v[72:75], v[226:229], v[44:47]
	v_mfma_f32_16x16x32_bf16 v[28:31], v[68:71], v[230:233], v[28:31]
	v_mfma_f32_16x16x32_bf16 v[28:31], v[72:75], v[234:237], v[28:31]
	v_mfma_f32_16x16x32_bf16 v[12:15], v[68:71], v[238:241], v[12:15]
	v_mfma_f32_16x16x32_bf16 v[12:15], v[72:75], v[242:245], v[12:15]
	v_mfma_f32_16x16x32_bf16 v[56:59], v[76:79], v[214:217], v[56:59]
	v_mfma_f32_16x16x32_bf16 v[56:59], v[80:83], v[218:221], v[56:59]
	v_mfma_f32_16x16x32_bf16 v[40:43], v[76:79], v[222:225], v[40:43]
	v_mfma_f32_16x16x32_bf16 v[40:43], v[80:83], v[226:229], v[40:43]
	v_mfma_f32_16x16x32_bf16 v[24:27], v[76:79], v[230:233], v[24:27]
	v_mfma_f32_16x16x32_bf16 v[24:27], v[80:83], v[234:237], v[24:27]
	v_mfma_f32_16x16x32_bf16 v[8:11], v[76:79], v[238:241], v[8:11]
	v_mfma_f32_16x16x32_bf16 v[8:11], v[80:83], v[242:245], v[8:11]
	v_mfma_f32_16x16x32_bf16 v[52:55], v[174:177], v[214:217], v[52:55]
	v_mfma_f32_16x16x32_bf16 v[52:55], v[182:185], v[218:221], v[52:55]
	v_mfma_f32_16x16x32_bf16 v[36:39], v[174:177], v[222:225], v[36:39]
	v_mfma_f32_16x16x32_bf16 v[36:39], v[182:185], v[226:229], v[36:39]
	v_mfma_f32_16x16x32_bf16 v[20:23], v[174:177], v[230:233], v[20:23]
	v_mfma_f32_16x16x32_bf16 v[20:23], v[182:185], v[234:237], v[20:23]
	v_mfma_f32_16x16x32_bf16 v[4:7], v[174:177], v[238:241], v[4:7]
	v_mfma_f32_16x16x32_bf16 v[4:7], v[182:185], v[242:245], v[4:7]
	v_mfma_f32_16x16x32_bf16 v[48:51], v[186:189], v[214:217], v[48:51]
	v_mfma_f32_16x16x32_bf16 v[48:51], v[210:213], v[218:221], v[48:51]
	v_mfma_f32_16x16x32_bf16 v[32:35], v[186:189], v[222:225], v[32:35]
	v_mfma_f32_16x16x32_bf16 v[32:35], v[210:213], v[226:229], v[32:35]
	v_mfma_f32_16x16x32_bf16 v[16:19], v[186:189], v[230:233], v[16:19]
	v_mfma_f32_16x16x32_bf16 v[16:19], v[210:213], v[234:237], v[16:19]
	v_mfma_f32_16x16x32_bf16 v[0:3], v[186:189], v[238:241], v[0:3]
	v_mfma_f32_16x16x32_bf16 v[0:3], v[210:213], v[242:245], v[0:3]
	s_setprio 0
	s_barrier
	s_add_i32 s56, s56, 2
	s_add_u32 s0, s0, 0x100
	s_addc_u32 s1, s1, 0
	s_add_u32 s54, s54, 0x100
	s_addc_u32 s55, s55, 0
	s_cmp_gt_u32 s56, 13
	s_cbranch_scc0 .LBB0_327
	s_and_b64 vcc, exec, s[22:23]
	s_cbranch_vccz .LBB0_330
	s_barrier

; #define PG8_STAGE(bufoff, gbase, voff) do { _Pragma("unroll") for (int _i = 0; _i < 2; ++_i) \
;         __builtin_amdgcn_global_load_lds((const unsigned*)((const char*)(gbase) + (voff)[_i]), (PG8_LAS unsigned*)(lds + (bufoff) + ldsw + _i * 8192), 16, 0, 0); } while (0)
; #define PG8_LDA(dst, b, h) do { _Pragma("unroll") for (int m = 0; m < 4; ++m) _Pragma("unroll") for (int k = 0; k < 2; ++k) dst[m][k] = *(const PG8_LAS bf16x8*)(lds + PG8_SA(b, h) + aoff + m * 2048 + k * 1024); } while (0)
; #define PG8_LDB(dst, b, h) do { _Pragma("unroll") for (int n = 0; n < 2; ++n) _Pragma("unroll") for (int k = 0; k < 2; ++k) dst[n][k] = *(const PG8_LAS bf16x8*)(lds + PG8_SB(b, h) + boff + n * 2048 + k * 1024); } while (0)
; #define PG8_MMA(ai, bj, At, Bt) do { __builtin_amdgcn_s_setprio(1); _Pragma("unroll") for (int m = 0; m < 4; ++m) _Pragma("unroll") for (int n = 0; n < 2; ++n) _Pragma("unroll") for (int k = 0; k < 2; ++k) \
;         acc[ai][bj][m][n] = __builtin_amdgcn_mfma_f32_16x16x32_bf16(Bt[n][k], At[m][k], acc[ai][bj][m][n], 0, 0, 0); __builtin_amdgcn_s_setprio(0); } while (0)
; #define PG8_WAIT_V(n) asm volatile("s_waitcnt vmcnt(" #n ")" ::: "memory")
; #define PG8_WAIT_L(n) asm volatile("s_waitcnt lgkmcnt(" #n ")" ::: "memory")
; template <class Epi, class Sched, bool ALIGN_EPI = false, bool SP2 = false>
; __device__ __forceinline__ void gemm_phase(PG8_LAS unsigned char* lds, const Gemm g, const Sched& S, const Epi& E) {
;     ...
;             const bool last = (t == nt - 2);
;             const char* a1 = cA + (size_t)(t + 1) * kstep;
;             const char* a2 = last ? nA : cA + (size_t)(t + 2) * kstep; const char* b2 = last ? nB : cB + (size_t)(t + 2) * kstep;
;             const char* a3 = a2 + kstep; const char* b3 = b2 + kstep;
;             if (last && has_next) S.a_ready(nxt);
;             if constexpr (SP2) {
;             PG8_LDB(B0, 0, 0); PG8_LDB(B1, 0, 1); PG8_SCHED; PG8_LDA(At, 0, 0); PG8_STAGE(PG8_SA(1, 1), a1 + hstep, voffA);
;             PG8_WAIT_V(8); PG8_WAIT_L(0); PG8_BAR; PG8_MMA(0, 0, At, B0); PG8_MMA(0, 1, At, B1); PG8_BAR; PG8_SCHED;
;             PG8_LDA(At, 0, 1); PG8_STAGE(PG8_SB(0, 0), b2, voffB); PG8_STAGE(PG8_SB(0, 1), b2 + hstep, voffB); PG8_STAGE(PG8_SA(0, 0), a2, voffA);
;             PG8_WAIT_V(8); PG8_WAIT_L(0); PG8_BAR; PG8_MMA(1, 0, At, B0); PG8_MMA(1, 1, At, B1); PG8_BAR; PG8_SCHED;
.Lup_peel:
	s_add_u32 s16, s14, 0xfffc0080
	s_addc_u32 s17, s15, -1
	s_cmp_eq_u32 s53, 12
	s_cselect_b32 s19, s7, s17
	s_cselect_b32 s18, s49, s16
	s_cselect_b32 s17, s5, s52
	s_cselect_b32 s16, s50, s51
	s_mov_b32 m0, s43
	ds_read_b128 v[140:143], v254
	ds_read_b128 v[168:171], v254 offset:1024
	ds_read_b128 v[172:175], v254 offset:2048
	ds_read_b128 v[176:179], v254 offset:3072
	ds_read_b128 v[180:183], v254 offset:16384
	ds_read_b128 v[184:187], v254 offset:17408
	ds_read_b128 v[188:191], v254 offset:18432
	ds_read_b128 v[210:213], v254 offset:19456
	global_load_lds_dwordx4 v136, s[14:15]
	s_mov_b32 m0, s44
	ds_read_b128 v[214:217], v165
	ds_read_b128 v[218:221], v165 offset:1024
	ds_read_b128 v[222:225], v165 offset:2048
	ds_read_b128 v[226:229], v165 offset:3072
	ds_read_b128 v[230:233], v165 offset:4096
	ds_read_b128 v[234:237], v165 offset:5120
	ds_read_b128 v[238:241], v165 offset:6144
	ds_read_b128 v[242:245], v165 offset:7168
	global_load_lds_dwordx4 v138, s[14:15]
	s_waitcnt vmcnt(8) lgkmcnt(0)
	s_barrier
	s_setprio 1
	v_mfma_f32_16x16x32_bf16 v[124:127], v[140:143], v[214:217], 0
	v_mfma_f32_16x16x32_bf16 v[124:127], v[168:171], v[218:221], v[124:127]
	v_mfma_f32_16x16x32_bf16 v[108:111], v[140:143], v[222:225], 0
	v_mfma_f32_16x16x32_bf16 v[108:111], v[168:171], v[226:229], v[108:111]
	v_mfma_f32_16x16x32_bf16 v[92:95], v[140:143], v[230:233], 0
	v_mfma_f32_16x16x32_bf16 v[92:95], v[168:171], v[234:237], v[92:95]
	v_mfma_f32_16x16x32_bf16 v[76:79], v[140:143], v[238:241], 0
	v_mfma_f32_16x16x32_bf16 v[76:79], v[168:171], v[242:245], v[76:79]
	v_mfma_f32_16x16x32_bf16 v[116:119], v[172:175], v[214:217], 0
	v_mfma_f32_16x16x32_bf16 v[116:119], v[176:179], v[218:221], v[116:119]
	v_mfma_f32_16x16x32_bf16 v[100:103], v[172:175], v[222:225], 0
	v_mfma_f32_16x16x32_bf16 v[100:103], v[176:179], v[226:229], v[100:103]
	v_mfma_f32_16x16x32_bf16 v[84:87], v[172:175], v[230:233], 0
	v_mfma_f32_16x16x32_bf16 v[84:87], v[176:179], v[234:237], v[84:87]
	v_mfma_f32_16x16x32_bf16 v[68:71], v[172:175], v[238:241], 0
	v_mfma_f32_16x16x32_bf16 v[68:71], v[176:179], v[242:245], v[68:71]
	v_mfma_f32_16x16x32_bf16 v[120:123], v[180:183], v[214:217], 0
	v_mfma_f32_16x16x32_bf16 v[120:123], v[184:187], v[218:221], v[120:123]
	v_mfma_f32_16x16x32_bf16 v[104:107], v[180:183], v[222:225], 0
	v_mfma_f32_16x16x32_bf16 v[104:107], v[184:187], v[226:229], v[104:107]
	v_mfma_f32_16x16x32_bf16 v[88:91], v[180:183], v[230:233], 0
	v_mfma_f32_16x16x32_bf16 v[88:91], v[184:187], v[234:237], v[88:91]
	v_mfma_f32_16x16x32_bf16 v[72:75], v[180:183], v[238:241], 0
	v_mfma_f32_16x16x32_bf16 v[72:75], v[184:187], v[242:245], v[72:75]
	v_mfma_f32_16x16x32_bf16 v[112:115], v[188:191], v[214:217], 0
	v_mfma_f32_16x16x32_bf16 v[112:115], v[210:213], v[218:221], v[112:115]
	v_mfma_f32_16x16x32_bf16 v[96:99], v[188:191], v[222:225], 0
	v_mfma_f32_16x16x32_bf16 v[96:99], v[210:213], v[226:229], v[96:99]
	v_mfma_f32_16x16x32_bf16 v[80:83], v[188:191], v[230:233], 0
	v_mfma_f32_16x16x32_bf16 v[80:83], v[210:213], v[234:237], v[80:83]
	v_mfma_f32_16x16x32_bf16 v[64:67], v[188:191], v[238:241], 0
	v_mfma_f32_16x16x32_bf16 v[64:67], v[210:213], v[242:245], v[64:67]
	s_setprio 0
	s_barrier
	s_mov_b32 m0, s27
	s_add_u32 s54, s16, 0x40000
	s_addc_u32 s55, s17, 0
	ds_read_b128 v[214:217], v165 offset:16384
	ds_read_b128 v[218:221], v165 offset:17408
	global_load_lds_dwordx4 v132, s[16:17]
	s_mov_b32 m0, s28
	ds_read_b128 v[222:225], v165 offset:18432
	ds_read_b128 v[226:229], v165 offset:19456
	global_load_lds_dwordx4 v128, s[16:17]
	s_mov_b32 m0, s29
	ds_read_b128 v[230:233], v165 offset:20480
	global_load_lds_dwordx4 v132, s[54:55]
	s_mov_b32 m0, s30
	ds_read_b128 v[234:237], v165 offset:21504
	global_load_lds_dwordx4 v128, s[54:55]
	s_mov_b32 m0, s22
	ds_read_b128 v[238:241], v165 offset:22528
	global_load_lds_dwordx4 v134, s[18:19]
	s_mov_b32 m0, s31
	ds_read_b128 v[242:245], v165 offset:23552
	global_load_lds_dwordx4 v130, s[18:19]
	s_waitcnt vmcnt(8) lgkmcnt(0)
	s_barrier
	s_setprio 1
	v_mfma_f32_16x16x32_bf16 v[60:63], v[140:143], v[214:217], 0
	v_mfma_f32_16x16x32_bf16 v[60:63], v[168:171], v[218:221], v[60:63]
	v_mfma_f32_16x16x32_bf16 v[44:47], v[140:143], v[222:225], 0
	v_mfma_f32_16x16x32_bf16 v[44:47], v[168:171], v[226:229], v[44:47]
	v_mfma_f32_16x16x32_bf16 v[28:31], v[140:143], v[230:233], 0
	v_mfma_f32_16x16x32_bf16 v[28:31], v[168:171], v[234:237], v[28:31]
	v_mfma_f32_16x16x32_bf16 v[12:15], v[140:143], v[238:241], 0
	v_mfma_f32_16x16x32_bf16 v[12:15], v[168:171], v[242:245], v[12:15]
	v_mfma_f32_16x16x32_bf16 v[52:55], v[172:175], v[214:217], 0
	v_mfma_f32_16x16x32_bf16 v[52:55], v[176:179], v[218:221], v[52:55]
	v_mfma_f32_16x16x32_bf16 v[36:39], v[172:175], v[222:225], 0
	v_mfma_f32_16x16x32_bf16 v[36:39], v[176:179], v[226:229], v[36:39]
	v_mfma_f32_16x16x32_bf16 v[20:23], v[172:175], v[230:233], 0
	v_mfma_f32_16x16x32_bf16 v[20:23], v[176:179], v[234:237], v[20:23]
	v_mfma_f32_16x16x32_bf16 v[4:7], v[172:175], v[238:241], 0
	v_mfma_f32_16x16x32_bf16 v[4:7], v[176:179], v[242:245], v[4:7]
	v_mfma_f32_16x16x32_bf16 v[56:59], v[180:183], v[214:217], 0
	v_mfma_f32_16x16x32_bf16 v[56:59], v[184:187], v[218:221], v[56:59]
	v_mfma_f32_16x16x32_bf16 v[40:43], v[180:183], v[222:225], 0
	v_mfma_f32_16x16x32_bf16 v[40:43], v[184:187], v[226:229], v[40:43]
	v_mfma_f32_16x16x32_bf16 v[24:27], v[180:183], v[230:233], 0
	v_mfma_f32_16x16x32_bf16 v[24:27], v[184:187], v[234:237], v[24:27]
	v_mfma_f32_16x16x32_bf16 v[8:11], v[180:183], v[238:241], 0
	v_mfma_f32_16x16x32_bf16 v[8:11], v[184:187], v[242:245], v[8:11]
	v_mfma_f32_16x16x32_bf16 v[48:51], v[188:191], v[214:217], 0
	v_mfma_f32_16x16x32_bf16 v[48:51], v[210:213], v[218:221], v[48:51]
	v_mfma_f32_16x16x32_bf16 v[32:35], v[188:191], v[222:225], 0
	v_mfma_f32_16x16x32_bf16 v[32:35], v[210:213], v[226:229], v[32:35]
	v_mfma_f32_16x16x32_bf16 v[16:19], v[188:191], v[230:233], 0
	v_mfma_f32_16x16x32_bf16 v[16:19], v[210:213], v[234:237], v[16:19]
	v_mfma_f32_16x16x32_bf16 v[0:3], v[188:191], v[238:241], 0
	v_mfma_f32_16x16x32_bf16 v[0:3], v[210:213], v[242:245], v[0:3]
	s_setprio 0
	s_barrier
; #define PG8_STAGE(bufoff, gbase, voff) do { _Pragma("unroll") for (int _i = 0; _i < 2; ++_i) \
;         __builtin_amdgcn_global_load_lds((const unsigned*)((const char*)(gbase) + (voff)[_i]), (PG8_LAS unsigned*)(lds + (bufoff) + ldsw + _i * 8192), 16, 0, 0); } while (0)
; #define PG8_LDA(dst, b, h) do { _Pragma("unroll") for (int m = 0; m < 4; ++m) _Pragma("unroll") for (int k = 0; k < 2; ++k) dst[m][k] = *(const PG8_LAS bf16x8*)(lds + PG8_SA(b, h) + aoff + m * 2048 + k * 1024); } while (0)
; #define PG8_LDB(dst, b, h) do { _Pragma("unroll") for (int n = 0; n < 2; ++n) _Pragma("unroll") for (int k = 0; k < 2; ++k) dst[n][k] = *(const PG8_LAS bf16x8*)(lds + PG8_SB(b, h) + boff + n * 2048 + k * 1024); } while (0)
; #define PG8_MMA(ai, bj, At, Bt) do { __builtin_amdgcn_s_setprio(1); _Pragma("unroll") for (int m = 0; m < 4; ++m) _Pragma("unroll") for (int n = 0; n < 2; ++n) _Pragma("unroll") for (int k = 0; k < 2; ++k) \
;         acc[ai][bj][m][n] = __builtin_amdgcn_mfma_f32_16x16x32_bf16(Bt[n][k], At[m][k], acc[ai][bj][m][n], 0, 0, 0); __builtin_amdgcn_s_setprio(0); } while (0)
; #define PG8_WAIT_V(n) asm volatile("s_waitcnt vmcnt(" #n ")" ::: "memory")
; #define PG8_WAIT_L(n) asm volatile("s_waitcnt lgkmcnt(" #n ")" ::: "memory")
; #define PG8_BAR __builtin_amdgcn_s_barrier()
; #define PG8_SCHED __builtin_amdgcn_sched_barrier(0)
; template <class Epi, class Sched, bool ALIGN_EPI = false, bool SP2 = false>
; __device__ __forceinline__ void gemm_phase(PG8_LAS unsigned char* lds, const Gemm g, const Sched& S, const Epi& E) {
;     ...
;             PG8_LDB(B0, 1, 0); PG8_LDB(B1, 1, 1); PG8_SCHED; PG8_LDA(At, 1, 0); PG8_STAGE(PG8_SA(0, 1), a2 + hstep, voffA);
;             PG8_WAIT_V(8); PG8_WAIT_L(0); PG8_BAR; PG8_MMA(0, 0, At, B0); PG8_MMA(0, 1, At, B1); PG8_BAR; PG8_SCHED;
;             PG8_LDA(At, 1, 1); PG8_STAGE(PG8_SB(1, 0), b3, voffB); PG8_STAGE(PG8_SB(1, 1), b3 + hstep, voffB); PG8_STAGE(PG8_SA(1, 0), a3, voffA);
;             PG8_WAIT_V(8); PG8_WAIT_L(0); PG8_BAR; PG8_MMA(1, 0, At, B0); PG8_MMA(1, 1, At, B1); PG8_BAR; PG8_SCHED;
	s_add_u32 s18, s18, 0x40000
	s_addc_u32 s19, s19, 0
	s_mov_b32 m0, s33
	ds_read_b128 v[140:143], v254 offset:32768
	ds_read_b128 v[168:171], v254 offset:33792
	ds_read_b128 v[172:175], v254 offset:34816
	ds_read_b128 v[176:179], v254 offset:35840
	ds_read_b128 v[180:183], v254 offset:49152
	ds_read_b128 v[184:187], v254 offset:50176
	ds_read_b128 v[188:191], v254 offset:51200
	ds_read_b128 v[210:213], v254 offset:52224
	global_load_lds_dwordx4 v134, s[18:19]
	s_mov_b32 m0, s34
	ds_read_b128 v[214:217], v165 offset:32768
	ds_read_b128 v[218:221], v165 offset:33792
	ds_read_b128 v[222:225], v165 offset:34816
	ds_read_b128 v[226:229], v165 offset:35840
	ds_read_b128 v[230:233], v165 offset:36864
	ds_read_b128 v[234:237], v165 offset:37888
	ds_read_b128 v[238:241], v165 offset:38912
	ds_read_b128 v[242:245], v165 offset:39936
	global_load_lds_dwordx4 v130, s[18:19]
	s_waitcnt vmcnt(8) lgkmcnt(0)
	s_barrier
	s_setprio 1
	v_mfma_f32_16x16x32_bf16 v[124:127], v[140:143], v[214:217], v[124:127]
	v_mfma_f32_16x16x32_bf16 v[124:127], v[168:171], v[218:221], v[124:127]
	v_mfma_f32_16x16x32_bf16 v[108:111], v[140:143], v[222:225], v[108:111]
	v_mfma_f32_16x16x32_bf16 v[108:111], v[168:171], v[226:229], v[108:111]
	v_mfma_f32_16x16x32_bf16 v[92:95], v[140:143], v[230:233], v[92:95]
	v_mfma_f32_16x16x32_bf16 v[92:95], v[168:171], v[234:237], v[92:95]
	v_mfma_f32_16x16x32_bf16 v[76:79], v[140:143], v[238:241], v[76:79]
	v_mfma_f32_16x16x32_bf16 v[76:79], v[168:171], v[242:245], v[76:79]
	v_mfma_f32_16x16x32_bf16 v[116:119], v[172:175], v[214:217], v[116:119]
	v_mfma_f32_16x16x32_bf16 v[116:119], v[176:179], v[218:221], v[116:119]
	v_mfma_f32_16x16x32_bf16 v[100:103], v[172:175], v[222:225], v[100:103]
	v_mfma_f32_16x16x32_bf16 v[100:103], v[176:179], v[226:229], v[100:103]
	v_mfma_f32_16x16x32_bf16 v[84:87], v[172:175], v[230:233], v[84:87]
	v_mfma_f32_16x16x32_bf16 v[84:87], v[176:179], v[234:237], v[84:87]
	v_mfma_f32_16x16x32_bf16 v[68:71], v[172:175], v[238:241], v[68:71]
	v_mfma_f32_16x16x32_bf16 v[68:71], v[176:179], v[242:245], v[68:71]
	v_mfma_f32_16x16x32_bf16 v[120:123], v[180:183], v[214:217], v[120:123]
	v_mfma_f32_16x16x32_bf16 v[120:123], v[184:187], v[218:221], v[120:123]
	v_mfma_f32_16x16x32_bf16 v[104:107], v[180:183], v[222:225], v[104:107]
	v_mfma_f32_16x16x32_bf16 v[104:107], v[184:187], v[226:229], v[104:107]
	v_mfma_f32_16x16x32_bf16 v[88:91], v[180:183], v[230:233], v[88:91]
	v_mfma_f32_16x16x32_bf16 v[88:91], v[184:187], v[234:237], v[88:91]
	v_mfma_f32_16x16x32_bf16 v[72:75], v[180:183], v[238:241], v[72:75]
	v_mfma_f32_16x16x32_bf16 v[72:75], v[184:187], v[242:245], v[72:75]
	v_mfma_f32_16x16x32_bf16 v[112:115], v[188:191], v[214:217], v[112:115]
	v_mfma_f32_16x16x32_bf16 v[112:115], v[210:213], v[218:221], v[112:115]
	v_mfma_f32_16x16x32_bf16 v[96:99], v[188:191], v[222:225], v[96:99]
	v_mfma_f32_16x16x32_bf16 v[96:99], v[210:213], v[226:229], v[96:99]
	v_mfma_f32_16x16x32_bf16 v[80:83], v[188:191], v[230:233], v[80:83]
	v_mfma_f32_16x16x32_bf16 v[80:83], v[210:213], v[234:237], v[80:83]
	v_mfma_f32_16x16x32_bf16 v[64:67], v[188:191], v[238:241], v[64:67]
	v_mfma_f32_16x16x32_bf16 v[64:67], v[210:213], v[242:245], v[64:67]
	s_setprio 0
	s_barrier
	s_mov_b32 m0, s37
	s_add_u32 s16, s16, 0x40080
	s_addc_u32 s17, s17, 0
	s_add_u32 s98, s16, 0xfffc0000
	s_addc_u32 s99, s17, -1
	ds_read_b128 v[214:217], v165 offset:49152
	ds_read_b128 v[218:221], v165 offset:50176
	global_load_lds_dwordx4 v132, s[98:99]
	s_mov_b32 m0, s38
	ds_read_b128 v[222:225], v165 offset:51200
	ds_read_b128 v[226:229], v165 offset:52224
	global_load_lds_dwordx4 v128, s[98:99]
	s_mov_b32 m0, s41
	ds_read_b128 v[230:233], v165 offset:53248
	global_load_lds_dwordx4 v132, s[16:17]
	s_mov_b32 m0, s42
	ds_read_b128 v[234:237], v165 offset:54272
	global_load_lds_dwordx4 v128, s[16:17]
	s_mov_b32 m0, s39
	s_add_u32 s100, s18, 0xfffc0080
	s_addc_u32 s101, s19, -1
	ds_read_b128 v[238:241], v165 offset:55296
	global_load_lds_dwordx4 v134, s[100:101]
	s_mov_b32 m0, s40
	ds_read_b128 v[242:245], v165 offset:56320
	global_load_lds_dwordx4 v130, s[100:101]
	s_waitcnt vmcnt(8) lgkmcnt(0)
	s_barrier
	s_setprio 1
	v_mfma_f32_16x16x32_bf16 v[60:63], v[140:143], v[214:217], v[60:63]
	v_mfma_f32_16x16x32_bf16 v[60:63], v[168:171], v[218:221], v[60:63]
	v_mfma_f32_16x16x32_bf16 v[44:47], v[140:143], v[222:225], v[44:47]
	v_mfma_f32_16x16x32_bf16 v[44:47], v[168:171], v[226:229], v[44:47]
	v_mfma_f32_16x16x32_bf16 v[28:31], v[140:143], v[230:233], v[28:31]
	v_mfma_f32_16x16x32_bf16 v[28:31], v[168:171], v[234:237], v[28:31]
	v_mfma_f32_16x16x32_bf16 v[12:15], v[140:143], v[238:241], v[12:15]
	v_mfma_f32_16x16x32_bf16 v[12:15], v[168:171], v[242:245], v[12:15]
	v_mfma_f32_16x16x32_bf16 v[52:55], v[172:175], v[214:217], v[52:55]
	v_mfma_f32_16x16x32_bf16 v[52:55], v[176:179], v[218:221], v[52:55]
	v_mfma_f32_16x16x32_bf16 v[36:39], v[172:175], v[222:225], v[36:39]
	v_mfma_f32_16x16x32_bf16 v[36:39], v[176:179], v[226:229], v[36:39]
	v_mfma_f32_16x16x32_bf16 v[20:23], v[172:175], v[230:233], v[20:23]
	v_mfma_f32_16x16x32_bf16 v[20:23], v[176:179], v[234:237], v[20:23]
	v_mfma_f32_16x16x32_bf16 v[4:7], v[172:175], v[238:241], v[4:7]
	v_mfma_f32_16x16x32_bf16 v[4:7], v[176:179], v[242:245], v[4:7]
	v_mfma_f32_16x16x32_bf16 v[56:59], v[180:183], v[214:217], v[56:59]
	v_mfma_f32_16x16x32_bf16 v[56:59], v[184:187], v[218:221], v[56:59]
	v_mfma_f32_16x16x32_bf16 v[40:43], v[180:183], v[222:225], v[40:43]
	v_mfma_f32_16x16x32_bf16 v[40:43], v[184:187], v[226:229], v[40:43]
	v_mfma_f32_16x16x32_bf16 v[24:27], v[180:183], v[230:233], v[24:27]
	v_mfma_f32_16x16x32_bf16 v[24:27], v[184:187], v[234:237], v[24:27]
	v_mfma_f32_16x16x32_bf16 v[8:11], v[180:183], v[238:241], v[8:11]
	v_mfma_f32_16x16x32_bf16 v[8:11], v[184:187], v[242:245], v[8:11]
	v_mfma_f32_16x16x32_bf16 v[48:51], v[188:191], v[214:217], v[48:51]
	v_mfma_f32_16x16x32_bf16 v[48:51], v[210:213], v[218:221], v[48:51]
	v_mfma_f32_16x16x32_bf16 v[32:35], v[188:191], v[222:225], v[32:35]
	v_mfma_f32_16x16x32_bf16 v[32:35], v[210:213], v[226:229], v[32:35]
	v_mfma_f32_16x16x32_bf16 v[16:19], v[188:191], v[230:233], v[16:19]
	v_mfma_f32_16x16x32_bf16 v[16:19], v[210:213], v[234:237], v[16:19]
	v_mfma_f32_16x16x32_bf16 v[0:3], v[188:191], v[238:241], v[0:3]
	v_mfma_f32_16x16x32_bf16 v[0:3], v[210:213], v[242:245], v[0:3]
	s_setprio 0
	s_barrier
	s_add_i32 s53, s53, 2
	s_add_u32 s14, s14, 0x100
	s_addc_u32 s15, s15, 0
	s_add_u32 s51, s51, 0x100
	s_addc_u32 s52, s52, 0
	s_cmp_gt_u32 s53, 13
; #define PG8_STAGE(bufoff, gbase, voff) do { _Pragma("unroll") for (int _i = 0; _i < 2; ++_i) \
;         __builtin_amdgcn_global_load_lds((const unsigned*)((const char*)(gbase) + (voff)[_i]), (PG8_LAS unsigned*)(lds + (bufoff) + ldsw + _i * 8192), 16, 0, 0); } while (0)
; #define PG8_LDA(dst, b, h) do { _Pragma("unroll") for (int m = 0; m < 4; ++m) _Pragma("unroll") for (int k = 0; k < 2; ++k) dst[m][k] = *(const PG8_LAS bf16x8*)(lds + PG8_SA(b, h) + aoff + m * 2048 + k * 1024); } while (0)
; #define PG8_LDB(dst, b, h) do { _Pragma("unroll") for (int n = 0; n < 2; ++n) _Pragma("unroll") for (int k = 0; k < 2; ++k) dst[n][k] = *(const PG8_LAS bf16x8*)(lds + PG8_SB(b, h) + boff + n * 2048 + k * 1024); } while (0)
; #define PG8_MMA(ai, bj, At, Bt) do { __builtin_amdgcn_s_setprio(1); _Pragma("unroll") for (int m = 0; m < 4; ++m) _Pragma("unroll") for (int n = 0; n < 2; ++n) _Pragma("unroll") for (int k = 0; k < 2; ++k) \
;         acc[ai][bj][m][n] = __builtin_amdgcn_mfma_f32_16x16x32_bf16(Bt[n][k], At[m][k], acc[ai][bj][m][n], 0, 0, 0); __builtin_amdgcn_s_setprio(0); } while (0)
; #define PG8_WAIT_V(n) asm volatile("s_waitcnt vmcnt(" #n ")" ::: "memory")
; #define PG8_BAR __builtin_amdgcn_s_barrier()
; template <class Epi, class Sched, bool ALIGN_EPI = false, bool SP2 = false>
; __device__ __forceinline__ void gemm_phase(PG8_LAS unsigned char* lds, const Gemm g, const Sched& S, const Epi& E) {
;     ...
;         for (int t = 0; t < nt; t += 2) {
;             const bool last = (t == nt - 2);
;             const char* a1 = cA + (size_t)(t + 1) * kstep;
;             const char* a2 = last ? nA : cA + (size_t)(t + 2) * kstep; const char* b2 = last ? nB : cB + (size_t)(t + 2) * kstep;
;             const char* a3 = a2 + kstep; const char* b3 = b2 + kstep;
;             if (last && has_next) S.a_ready(nxt);
;             if constexpr (SP2) {
;             PG8_LDB(B0, 0, 0); PG8_LDB(B1, 0, 1); PG8_SCHED; PG8_LDA(At, 0, 0); PG8_STAGE(PG8_SA(1, 1), a1 + hstep, voffA);
;             PG8_WAIT_V(8); PG8_WAIT_L(0); PG8_BAR; PG8_MMA(0, 0, At, B0); PG8_MMA(0, 1, At, B1); PG8_BAR; PG8_SCHED;
;             PG8_LDA(At, 0, 1); PG8_STAGE(PG8_SB(0, 0), b2, voffB); PG8_STAGE(PG8_SB(0, 1), b2 + hstep, voffB); PG8_STAGE(PG8_SA(0, 0), a2, voffA);
;             PG8_WAIT_V(8); PG8_WAIT_L(0); PG8_BAR; PG8_MMA(1, 0, At, B0); PG8_MMA(1, 1, At, B1); PG8_BAR; PG8_SCHED;
.LBB0_446:
	s_add_u32 s16, s14, 0xfffc0080
	s_addc_u32 s17, s15, -1
	s_cmp_eq_u32 s53, 12
	s_cselect_b32 s19, s7, s17
	s_cselect_b32 s18, s49, s16
	s_cselect_b32 s17, s5, s52
	s_cselect_b32 s16, s50, s51
	s_mov_b32 m0, s43
	ds_read_b128 v[140:143], v254
	ds_read_b128 v[168:171], v254 offset:1024
	ds_read_b128 v[172:175], v254 offset:2048
	ds_read_b128 v[176:179], v254 offset:3072
	ds_read_b128 v[180:183], v254 offset:16384
	ds_read_b128 v[184:187], v254 offset:17408
	ds_read_b128 v[188:191], v254 offset:18432
	ds_read_b128 v[210:213], v254 offset:19456
	global_load_lds_dwordx4 v136, s[14:15]
	s_mov_b32 m0, s44
	ds_read_b128 v[214:217], v165
	ds_read_b128 v[218:221], v165 offset:1024
	ds_read_b128 v[222:225], v165 offset:2048
	ds_read_b128 v[226:229], v165 offset:3072
	ds_read_b128 v[230:233], v165 offset:4096
	ds_read_b128 v[234:237], v165 offset:5120
	ds_read_b128 v[238:241], v165 offset:6144
	ds_read_b128 v[242:245], v165 offset:7168
	global_load_lds_dwordx4 v138, s[14:15]
	s_waitcnt vmcnt(8) lgkmcnt(0)
	s_barrier
	s_setprio 1
	v_mfma_f32_16x16x32_bf16 v[124:127], v[140:143], v[214:217], v[124:127]
	v_mfma_f32_16x16x32_bf16 v[124:127], v[168:171], v[218:221], v[124:127]
	v_mfma_f32_16x16x32_bf16 v[108:111], v[140:143], v[222:225], v[108:111]
	v_mfma_f32_16x16x32_bf16 v[108:111], v[168:171], v[226:229], v[108:111]
	v_mfma_f32_16x16x32_bf16 v[92:95], v[140:143], v[230:233], v[92:95]
	v_mfma_f32_16x16x32_bf16 v[92:95], v[168:171], v[234:237], v[92:95]
	v_mfma_f32_16x16x32_bf16 v[76:79], v[140:143], v[238:241], v[76:79]
	v_mfma_f32_16x16x32_bf16 v[76:79], v[168:171], v[242:245], v[76:79]
	v_mfma_f32_16x16x32_bf16 v[116:119], v[172:175], v[214:217], v[116:119]
	v_mfma_f32_16x16x32_bf16 v[116:119], v[176:179], v[218:221], v[116:119]
	v_mfma_f32_16x16x32_bf16 v[100:103], v[172:175], v[222:225], v[100:103]
	v_mfma_f32_16x16x32_bf16 v[100:103], v[176:179], v[226:229], v[100:103]
	v_mfma_f32_16x16x32_bf16 v[84:87], v[172:175], v[230:233], v[84:87]
	v_mfma_f32_16x16x32_bf16 v[84:87], v[176:179], v[234:237], v[84:87]
	v_mfma_f32_16x16x32_bf16 v[68:71], v[172:175], v[238:241], v[68:71]
	v_mfma_f32_16x16x32_bf16 v[68:71], v[176:179], v[242:245], v[68:71]
	v_mfma_f32_16x16x32_bf16 v[120:123], v[180:183], v[214:217], v[120:123]
	v_mfma_f32_16x16x32_bf16 v[120:123], v[184:187], v[218:221], v[120:123]
	v_mfma_f32_16x16x32_bf16 v[104:107], v[180:183], v[222:225], v[104:107]
	v_mfma_f32_16x16x32_bf16 v[104:107], v[184:187], v[226:229], v[104:107]
	v_mfma_f32_16x16x32_bf16 v[88:91], v[180:183], v[230:233], v[88:91]
	v_mfma_f32_16x16x32_bf16 v[88:91], v[184:187], v[234:237], v[88:91]
	v_mfma_f32_16x16x32_bf16 v[72:75], v[180:183], v[238:241], v[72:75]
	v_mfma_f32_16x16x32_bf16 v[72:75], v[184:187], v[242:245], v[72:75]
	v_mfma_f32_16x16x32_bf16 v[112:115], v[188:191], v[214:217], v[112:115]
	v_mfma_f32_16x16x32_bf16 v[112:115], v[210:213], v[218:221], v[112:115]
	v_mfma_f32_16x16x32_bf16 v[96:99], v[188:191], v[222:225], v[96:99]
	v_mfma_f32_16x16x32_bf16 v[96:99], v[210:213], v[226:229], v[96:99]
	v_mfma_f32_16x16x32_bf16 v[80:83], v[188:191], v[230:233], v[80:83]
	v_mfma_f32_16x16x32_bf16 v[80:83], v[210:213], v[234:237], v[80:83]
	v_mfma_f32_16x16x32_bf16 v[64:67], v[188:191], v[238:241], v[64:67]
	v_mfma_f32_16x16x32_bf16 v[64:67], v[210:213], v[242:245], v[64:67]
	s_setprio 0
	s_barrier
	s_mov_b32 m0, s27
	s_add_u32 s54, s16, 0x40000
	s_addc_u32 s55, s17, 0
	ds_read_b128 v[214:217], v165 offset:16384
	ds_read_b128 v[218:221], v165 offset:17408
	global_load_lds_dwordx4 v132, s[16:17]
	s_mov_b32 m0, s28
	ds_read_b128 v[222:225], v165 offset:18432
	ds_read_b128 v[226:229], v165 offset:19456
	global_load_lds_dwordx4 v128, s[16:17]
	s_mov_b32 m0, s29
	ds_read_b128 v[230:233], v165 offset:20480
	global_load_lds_dwordx4 v132, s[54:55]
	s_mov_b32 m0, s30
	ds_read_b128 v[234:237], v165 offset:21504
	global_load_lds_dwordx4 v128, s[54:55]
	s_mov_b32 m0, s22
	ds_read_b128 v[238:241], v165 offset:22528
	global_load_lds_dwordx4 v134, s[18:19]
	s_mov_b32 m0, s31
	ds_read_b128 v[242:245], v165 offset:23552
	global_load_lds_dwordx4 v130, s[18:19]
	s_waitcnt vmcnt(8) lgkmcnt(0)
	s_barrier
	s_setprio 1
	v_mfma_f32_16x16x32_bf16 v[60:63], v[140:143], v[214:217], v[60:63]
	v_mfma_f32_16x16x32_bf16 v[60:63], v[168:171], v[218:221], v[60:63]
	v_mfma_f32_16x16x32_bf16 v[44:47], v[140:143], v[222:225], v[44:47]
	v_mfma_f32_16x16x32_bf16 v[44:47], v[168:171], v[226:229], v[44:47]
	v_mfma_f32_16x16x32_bf16 v[28:31], v[140:143], v[230:233], v[28:31]
	v_mfma_f32_16x16x32_bf16 v[28:31], v[168:171], v[234:237], v[28:31]
	v_mfma_f32_16x16x32_bf16 v[12:15], v[140:143], v[238:241], v[12:15]
	v_mfma_f32_16x16x32_bf16 v[12:15], v[168:171], v[242:245], v[12:15]
	v_mfma_f32_16x16x32_bf16 v[52:55], v[172:175], v[214:217], v[52:55]
	v_mfma_f32_16x16x32_bf16 v[52:55], v[176:179], v[218:221], v[52:55]
	v_mfma_f32_16x16x32_bf16 v[36:39], v[172:175], v[222:225], v[36:39]
	v_mfma_f32_16x16x32_bf16 v[36:39], v[176:179], v[226:229], v[36:39]
	v_mfma_f32_16x16x32_bf16 v[20:23], v[172:175], v[230:233], v[20:23]
	v_mfma_f32_16x16x32_bf16 v[20:23], v[176:179], v[234:237], v[20:23]
	v_mfma_f32_16x16x32_bf16 v[4:7], v[172:175], v[238:241], v[4:7]
	v_mfma_f32_16x16x32_bf16 v[4:7], v[176:179], v[242:245], v[4:7]
	v_mfma_f32_16x16x32_bf16 v[56:59], v[180:183], v[214:217], v[56:59]
	v_mfma_f32_16x16x32_bf16 v[56:59], v[184:187], v[218:221], v[56:59]
	v_mfma_f32_16x16x32_bf16 v[40:43], v[180:183], v[222:225], v[40:43]
	v_mfma_f32_16x16x32_bf16 v[40:43], v[184:187], v[226:229], v[40:43]
	v_mfma_f32_16x16x32_bf16 v[24:27], v[180:183], v[230:233], v[24:27]
	v_mfma_f32_16x16x32_bf16 v[24:27], v[184:187], v[234:237], v[24:27]
	v_mfma_f32_16x16x32_bf16 v[8:11], v[180:183], v[238:241], v[8:11]
	v_mfma_f32_16x16x32_bf16 v[8:11], v[184:187], v[242:245], v[8:11]
	v_mfma_f32_16x16x32_bf16 v[48:51], v[188:191], v[214:217], v[48:51]
	v_mfma_f32_16x16x32_bf16 v[48:51], v[210:213], v[218:221], v[48:51]
	v_mfma_f32_16x16x32_bf16 v[32:35], v[188:191], v[222:225], v[32:35]
	v_mfma_f32_16x16x32_bf16 v[32:35], v[210:213], v[226:229], v[32:35]
	v_mfma_f32_16x16x32_bf16 v[16:19], v[188:191], v[230:233], v[16:19]
	v_mfma_f32_16x16x32_bf16 v[16:19], v[210:213], v[234:237], v[16:19]
	v_mfma_f32_16x16x32_bf16 v[0:3], v[188:191], v[238:241], v[0:3]
	v_mfma_f32_16x16x32_bf16 v[0:3], v[210:213], v[242:245], v[0:3]
	s_setprio 0
	s_barrier
; #define PG8_STAGE(bufoff, gbase, voff) do { _Pragma("unroll") for (int _i = 0; _i < 2; ++_i) \
;         __builtin_amdgcn_global_load_lds((const unsigned*)((const char*)(gbase) + (voff)[_i]), (PG8_LAS unsigned*)(lds + (bufoff) + ldsw + _i * 8192), 16, 0, 0); } while (0)
; #define PG8_LDA(dst, b, h) do { _Pragma("unroll") for (int m = 0; m < 4; ++m) _Pragma("unroll") for (int k = 0; k < 2; ++k) dst[m][k] = *(const PG8_LAS bf16x8*)(lds + PG8_SA(b, h) + aoff + m * 2048 + k * 1024); } while (0)
; #define PG8_LDB(dst, b, h) do { _Pragma("unroll") for (int n = 0; n < 2; ++n) _Pragma("unroll") for (int k = 0; k < 2; ++k) dst[n][k] = *(const PG8_LAS bf16x8*)(lds + PG8_SB(b, h) + boff + n * 2048 + k * 1024); } while (0)
; #define PG8_MMA(ai, bj, At, Bt) do { __builtin_amdgcn_s_setprio(1); _Pragma("unroll") for (int m = 0; m < 4; ++m) _Pragma("unroll") for (int n = 0; n < 2; ++n) _Pragma("unroll") for (int k = 0; k < 2; ++k) \
;         acc[ai][bj][m][n] = __builtin_amdgcn_mfma_f32_16x16x32_bf16(Bt[n][k], At[m][k], acc[ai][bj][m][n], 0, 0, 0); __builtin_amdgcn_s_setprio(0); } while (0)
; #define PG8_WAIT_V(n) asm volatile("s_waitcnt vmcnt(" #n ")" ::: "memory")
; #define PG8_WAIT_L(n) asm volatile("s_waitcnt lgkmcnt(" #n ")" ::: "memory")
; #define PG8_BAR __builtin_amdgcn_s_barrier()
; #define PG8_SCHED __builtin_amdgcn_sched_barrier(0)
; template <class Epi, class Sched, bool ALIGN_EPI = false, bool SP2 = false>
; __device__ __forceinline__ void gemm_phase(PG8_LAS unsigned char* lds, const Gemm g, const Sched& S, const Epi& E) {
;     ...
;         for (int t = 0; t < nt; t += 2) {
;             const bool last = (t == nt - 2);
;     ...
;             PG8_LDB(B0, 1, 0); PG8_LDB(B1, 1, 1); PG8_SCHED; PG8_LDA(At, 1, 0); PG8_STAGE(PG8_SA(0, 1), a2 + hstep, voffA);
;             PG8_WAIT_V(8); PG8_WAIT_L(0); PG8_BAR; PG8_MMA(0, 0, At, B0); PG8_MMA(0, 1, At, B1); PG8_BAR; PG8_SCHED;
;             PG8_LDA(At, 1, 1); PG8_STAGE(PG8_SB(1, 0), b3, voffB); PG8_STAGE(PG8_SB(1, 1), b3 + hstep, voffB); PG8_STAGE(PG8_SA(1, 0), a3, voffA);
;             PG8_WAIT_V(8); PG8_WAIT_L(0); PG8_BAR; PG8_MMA(1, 0, At, B0); PG8_MMA(1, 1, At, B1); PG8_BAR; PG8_SCHED;
	s_add_u32 s18, s18, 0x40000
	s_addc_u32 s19, s19, 0
	s_mov_b32 m0, s33
	ds_read_b128 v[140:143], v254 offset:32768
	ds_read_b128 v[168:171], v254 offset:33792
	ds_read_b128 v[172:175], v254 offset:34816
	ds_read_b128 v[176:179], v254 offset:35840
	ds_read_b128 v[180:183], v254 offset:49152
	ds_read_b128 v[184:187], v254 offset:50176
	ds_read_b128 v[188:191], v254 offset:51200
	ds_read_b128 v[210:213], v254 offset:52224
	global_load_lds_dwordx4 v134, s[18:19]
	s_mov_b32 m0, s34
	ds_read_b128 v[214:217], v165 offset:32768
	ds_read_b128 v[218:221], v165 offset:33792
	ds_read_b128 v[222:225], v165 offset:34816
	ds_read_b128 v[226:229], v165 offset:35840
	ds_read_b128 v[230:233], v165 offset:36864
	ds_read_b128 v[234:237], v165 offset:37888
	ds_read_b128 v[238:241], v165 offset:38912
	ds_read_b128 v[242:245], v165 offset:39936
	global_load_lds_dwordx4 v130, s[18:19]
	s_waitcnt vmcnt(8) lgkmcnt(0)
	s_barrier
	s_setprio 1
	v_mfma_f32_16x16x32_bf16 v[124:127], v[140:143], v[214:217], v[124:127]
	v_mfma_f32_16x16x32_bf16 v[124:127], v[168:171], v[218:221], v[124:127]
	v_mfma_f32_16x16x32_bf16 v[108:111], v[140:143], v[222:225], v[108:111]
	v_mfma_f32_16x16x32_bf16 v[108:111], v[168:171], v[226:229], v[108:111]
	v_mfma_f32_16x16x32_bf16 v[92:95], v[140:143], v[230:233], v[92:95]
	v_mfma_f32_16x16x32_bf16 v[92:95], v[168:171], v[234:237], v[92:95]
	v_mfma_f32_16x16x32_bf16 v[76:79], v[140:143], v[238:241], v[76:79]
	v_mfma_f32_16x16x32_bf16 v[76:79], v[168:171], v[242:245], v[76:79]
	v_mfma_f32_16x16x32_bf16 v[116:119], v[172:175], v[214:217], v[116:119]
	v_mfma_f32_16x16x32_bf16 v[116:119], v[176:179], v[218:221], v[116:119]
	v_mfma_f32_16x16x32_bf16 v[100:103], v[172:175], v[222:225], v[100:103]
	v_mfma_f32_16x16x32_bf16 v[100:103], v[176:179], v[226:229], v[100:103]
	v_mfma_f32_16x16x32_bf16 v[84:87], v[172:175], v[230:233], v[84:87]
	v_mfma_f32_16x16x32_bf16 v[84:87], v[176:179], v[234:237], v[84:87]
	v_mfma_f32_16x16x32_bf16 v[68:71], v[172:175], v[238:241], v[68:71]
	v_mfma_f32_16x16x32_bf16 v[68:71], v[176:179], v[242:245], v[68:71]
	v_mfma_f32_16x16x32_bf16 v[120:123], v[180:183], v[214:217], v[120:123]
	v_mfma_f32_16x16x32_bf16 v[120:123], v[184:187], v[218:221], v[120:123]
	v_mfma_f32_16x16x32_bf16 v[104:107], v[180:183], v[222:225], v[104:107]
	v_mfma_f32_16x16x32_bf16 v[104:107], v[184:187], v[226:229], v[104:107]
	v_mfma_f32_16x16x32_bf16 v[88:91], v[180:183], v[230:233], v[88:91]
	v_mfma_f32_16x16x32_bf16 v[88:91], v[184:187], v[234:237], v[88:91]
	v_mfma_f32_16x16x32_bf16 v[72:75], v[180:183], v[238:241], v[72:75]
	v_mfma_f32_16x16x32_bf16 v[72:75], v[184:187], v[242:245], v[72:75]
	v_mfma_f32_16x16x32_bf16 v[112:115], v[188:191], v[214:217], v[112:115]
	v_mfma_f32_16x16x32_bf16 v[112:115], v[210:213], v[218:221], v[112:115]
	v_mfma_f32_16x16x32_bf16 v[96:99], v[188:191], v[222:225], v[96:99]
	v_mfma_f32_16x16x32_bf16 v[96:99], v[210:213], v[226:229], v[96:99]
	v_mfma_f32_16x16x32_bf16 v[80:83], v[188:191], v[230:233], v[80:83]
	v_mfma_f32_16x16x32_bf16 v[80:83], v[210:213], v[234:237], v[80:83]
	v_mfma_f32_16x16x32_bf16 v[64:67], v[188:191], v[238:241], v[64:67]
	v_mfma_f32_16x16x32_bf16 v[64:67], v[210:213], v[242:245], v[64:67]
	s_setprio 0
	s_barrier
	s_mov_b32 m0, s37
	s_add_u32 s16, s16, 0x40080
	s_addc_u32 s17, s17, 0
	s_add_u32 s98, s16, 0xfffc0000
	s_addc_u32 s99, s17, -1
	ds_read_b128 v[214:217], v165 offset:49152
	ds_read_b128 v[218:221], v165 offset:50176
	global_load_lds_dwordx4 v132, s[98:99]
	s_mov_b32 m0, s38
	ds_read_b128 v[222:225], v165 offset:51200
	ds_read_b128 v[226:229], v165 offset:52224
	global_load_lds_dwordx4 v128, s[98:99]
	s_mov_b32 m0, s41
	ds_read_b128 v[230:233], v165 offset:53248
	global_load_lds_dwordx4 v132, s[16:17]
	s_mov_b32 m0, s42
	ds_read_b128 v[234:237], v165 offset:54272
	global_load_lds_dwordx4 v128, s[16:17]
	s_mov_b32 m0, s39
	s_add_u32 s100, s18, 0xfffc0080
	s_addc_u32 s101, s19, -1
	ds_read_b128 v[238:241], v165 offset:55296
	global_load_lds_dwordx4 v134, s[100:101]
	s_mov_b32 m0, s40
	ds_read_b128 v[242:245], v165 offset:56320
	global_load_lds_dwordx4 v130, s[100:101]
	s_waitcnt vmcnt(8) lgkmcnt(0)
	s_barrier
	s_setprio 1
	v_mfma_f32_16x16x32_bf16 v[60:63], v[140:143], v[214:217], v[60:63]
	v_mfma_f32_16x16x32_bf16 v[60:63], v[168:171], v[218:221], v[60:63]
	v_mfma_f32_16x16x32_bf16 v[44:47], v[140:143], v[222:225], v[44:47]
	v_mfma_f32_16x16x32_bf16 v[44:47], v[168:171], v[226:229], v[44:47]
	v_mfma_f32_16x16x32_bf16 v[28:31], v[140:143], v[230:233], v[28:31]
	v_mfma_f32_16x16x32_bf16 v[28:31], v[168:171], v[234:237], v[28:31]
	v_mfma_f32_16x16x32_bf16 v[12:15], v[140:143], v[238:241], v[12:15]
	v_mfma_f32_16x16x32_bf16 v[12:15], v[168:171], v[242:245], v[12:15]
	v_mfma_f32_16x16x32_bf16 v[52:55], v[172:175], v[214:217], v[52:55]
	v_mfma_f32_16x16x32_bf16 v[52:55], v[176:179], v[218:221], v[52:55]
	v_mfma_f32_16x16x32_bf16 v[36:39], v[172:175], v[222:225], v[36:39]
	v_mfma_f32_16x16x32_bf16 v[36:39], v[176:179], v[226:229], v[36:39]
	v_mfma_f32_16x16x32_bf16 v[20:23], v[172:175], v[230:233], v[20:23]
	v_mfma_f32_16x16x32_bf16 v[20:23], v[176:179], v[234:237], v[20:23]
	v_mfma_f32_16x16x32_bf16 v[4:7], v[172:175], v[238:241], v[4:7]
	v_mfma_f32_16x16x32_bf16 v[4:7], v[176:179], v[242:245], v[4:7]
	v_mfma_f32_16x16x32_bf16 v[56:59], v[180:183], v[214:217], v[56:59]
	v_mfma_f32_16x16x32_bf16 v[56:59], v[184:187], v[218:221], v[56:59]
	v_mfma_f32_16x16x32_bf16 v[40:43], v[180:183], v[222:225], v[40:43]
	v_mfma_f32_16x16x32_bf16 v[40:43], v[184:187], v[226:229], v[40:43]
	v_mfma_f32_16x16x32_bf16 v[24:27], v[180:183], v[230:233], v[24:27]
	v_mfma_f32_16x16x32_bf16 v[24:27], v[184:187], v[234:237], v[24:27]
	v_mfma_f32_16x16x32_bf16 v[8:11], v[180:183], v[238:241], v[8:11]
	v_mfma_f32_16x16x32_bf16 v[8:11], v[184:187], v[242:245], v[8:11]
	v_mfma_f32_16x16x32_bf16 v[48:51], v[188:191], v[214:217], v[48:51]
	v_mfma_f32_16x16x32_bf16 v[48:51], v[210:213], v[218:221], v[48:51]
	v_mfma_f32_16x16x32_bf16 v[32:35], v[188:191], v[222:225], v[32:35]
	v_mfma_f32_16x16x32_bf16 v[32:35], v[210:213], v[226:229], v[32:35]
	v_mfma_f32_16x16x32_bf16 v[16:19], v[188:191], v[230:233], v[16:19]
	v_mfma_f32_16x16x32_bf16 v[16:19], v[210:213], v[234:237], v[16:19]
	v_mfma_f32_16x16x32_bf16 v[0:3], v[188:191], v[238:241], v[0:3]
	v_mfma_f32_16x16x32_bf16 v[0:3], v[210:213], v[242:245], v[0:3]
	s_setprio 0
	s_barrier
	s_add_i32 s53, s53, 2
	s_add_u32 s14, s14, 0x100
	s_addc_u32 s15, s15, 0
	s_add_u32 s51, s51, 0x100
	s_addc_u32 s52, s52, 0
	s_cmp_gt_u32 s53, 13
	s_cbranch_scc0 .LBB0_446
	s_and_b64 vcc, exec, s[2:3]
	s_cbranch_vccz .LBB0_449
	s_barrier

; #define PG8_STAGE(bufoff, gbase, voff) do { _Pragma("unroll") for (int _i = 0; _i < 2; ++_i) \
;         __builtin_amdgcn_global_load_lds((const unsigned*)((const char*)(gbase) + (voff)[_i]), (PG8_LAS unsigned*)(lds + (bufoff) + ldsw + _i * 8192), 16, 0, 0); } while (0)
; #define PG8_LDA(dst, b, h) do { _Pragma("unroll") for (int m = 0; m < 4; ++m) _Pragma("unroll") for (int k = 0; k < 2; ++k) dst[m][k] = *(const PG8_LAS bf16x8*)(lds + PG8_SA(b, h) + aoff + m * 2048 + k * 1024); } while (0)
; #define PG8_LDB(dst, b, h) do { _Pragma("unroll") for (int n = 0; n < 2; ++n) _Pragma("unroll") for (int k = 0; k < 2; ++k) dst[n][k] = *(const PG8_LAS bf16x8*)(lds + PG8_SB(b, h) + boff + n * 2048 + k * 1024); } while (0)
; #define PG8_MMA(ai, bj, At, Bt) do { __builtin_amdgcn_s_setprio(1); _Pragma("unroll") for (int m = 0; m < 4; ++m) _Pragma("unroll") for (int n = 0; n < 2; ++n) _Pragma("unroll") for (int k = 0; k < 2; ++k) \
;         acc[ai][bj][m][n] = __builtin_amdgcn_mfma_f32_16x16x32_bf16(Bt[n][k], At[m][k], acc[ai][bj][m][n], 0, 0, 0); __builtin_amdgcn_s_setprio(0); } while (0)
; #define PG8_WAIT_V(n) asm volatile("s_waitcnt vmcnt(" #n ")" ::: "memory")
; #define PG8_WAIT_L(n) asm volatile("s_waitcnt lgkmcnt(" #n ")" ::: "memory")
; template <class Epi, class Sched, bool ALIGN_EPI = false, bool SP2 = false>
; __device__ __forceinline__ void gemm_phase(PG8_LAS unsigned char* lds, const Gemm g, const Sched& S, const Epi& E) {
;     ...
;             const bool last = (t == nt - 2);
;             const char* a1 = cA + (size_t)(t + 1) * kstep;
;             const char* a2 = last ? nA : cA + (size_t)(t + 2) * kstep; const char* b2 = last ? nB : cB + (size_t)(t + 2) * kstep;
;             const char* a3 = a2 + kstep; const char* b3 = b2 + kstep;
;             if (last && has_next) S.a_ready(nxt);
;             if constexpr (SP2) {
;             PG8_LDB(B0, 0, 0); PG8_LDB(B1, 0, 1); PG8_SCHED; PG8_LDA(At, 0, 0); PG8_STAGE(PG8_SA(1, 1), a1 + hstep, voffA);
;             PG8_WAIT_V(8); PG8_WAIT_L(0); PG8_BAR; PG8_MMA(0, 0, At, B0); PG8_MMA(0, 1, At, B1); PG8_BAR; PG8_SCHED;
;             PG8_LDA(At, 0, 1); PG8_STAGE(PG8_SB(0, 0), b2, voffB); PG8_STAGE(PG8_SB(0, 1), b2 + hstep, voffB); PG8_STAGE(PG8_SA(0, 0), a2, voffA);
;             PG8_WAIT_V(8); PG8_WAIT_L(0); PG8_BAR; PG8_MMA(1, 0, At, B0); PG8_MMA(1, 1, At, B1); PG8_BAR; PG8_SCHED;
.Ldn_peel:
	s_add_u32 s2, s0, 0x100
	s_addc_u32 s3, s1, 0
	s_cmp_eq_u32 s13, 40
	s_cselect_b32 s7, s27, s3
	s_cselect_b32 s6, s26, s2
	s_cselect_b32 s5, s37, s11
	s_cselect_b32 s4, s36, s10
	s_add_i32 m0, s29, 0xc000
	ds_read_b128 v[128:131], v254
	ds_read_b128 v[132:135], v254 offset:1024
	ds_read_b128 v[136:139], v254 offset:2048
	ds_read_b128 v[140:143], v254 offset:3072
	ds_read_b128 v[174:177], v254 offset:16384
	ds_read_b128 v[184:187], v254 offset:17408
	ds_read_b128 v[188:191], v254 offset:18432
	ds_read_b128 v[210:213], v254 offset:19456
	global_load_lds_dwordx4 v170, s[0:1]
	s_add_i32 m0, s29, 0xe000
	ds_read_b128 v[214:217], v181
	ds_read_b128 v[218:221], v181 offset:1024
	ds_read_b128 v[222:225], v181 offset:2048
	ds_read_b128 v[226:229], v181 offset:3072
	ds_read_b128 v[230:233], v181 offset:4096
	ds_read_b128 v[234:237], v181 offset:5120
	ds_read_b128 v[238:241], v181 offset:6144
	ds_read_b128 v[242:245], v181 offset:7168
	global_load_lds_dwordx4 v172, s[0:1]
	s_waitcnt vmcnt(8) lgkmcnt(0)
	s_barrier
	s_setprio 1
	v_mfma_f32_16x16x32_bf16 v[124:127], v[128:131], v[214:217], 0
	v_mfma_f32_16x16x32_bf16 v[124:127], v[132:135], v[218:221], v[124:127]
	v_mfma_f32_16x16x32_bf16 v[108:111], v[128:131], v[222:225], 0
	v_mfma_f32_16x16x32_bf16 v[108:111], v[132:135], v[226:229], v[108:111]
	v_mfma_f32_16x16x32_bf16 v[92:95], v[128:131], v[230:233], 0
	v_mfma_f32_16x16x32_bf16 v[92:95], v[132:135], v[234:237], v[92:95]
	v_mfma_f32_16x16x32_bf16 v[76:79], v[128:131], v[238:241], 0
	v_mfma_f32_16x16x32_bf16 v[76:79], v[132:135], v[242:245], v[76:79]
	v_mfma_f32_16x16x32_bf16 v[120:123], v[136:139], v[214:217], 0
	v_mfma_f32_16x16x32_bf16 v[120:123], v[140:143], v[218:221], v[120:123]
	v_mfma_f32_16x16x32_bf16 v[104:107], v[136:139], v[222:225], 0
	v_mfma_f32_16x16x32_bf16 v[104:107], v[140:143], v[226:229], v[104:107]
	v_mfma_f32_16x16x32_bf16 v[88:91], v[136:139], v[230:233], 0
	v_mfma_f32_16x16x32_bf16 v[88:91], v[140:143], v[234:237], v[88:91]
	v_mfma_f32_16x16x32_bf16 v[72:75], v[136:139], v[238:241], 0
	v_mfma_f32_16x16x32_bf16 v[72:75], v[140:143], v[242:245], v[72:75]
	v_mfma_f32_16x16x32_bf16 v[116:119], v[174:177], v[214:217], 0
	v_mfma_f32_16x16x32_bf16 v[116:119], v[184:187], v[218:221], v[116:119]
	v_mfma_f32_16x16x32_bf16 v[100:103], v[174:177], v[222:225], 0
	v_mfma_f32_16x16x32_bf16 v[100:103], v[184:187], v[226:229], v[100:103]
	v_mfma_f32_16x16x32_bf16 v[84:87], v[174:177], v[230:233], 0
	v_mfma_f32_16x16x32_bf16 v[84:87], v[184:187], v[234:237], v[84:87]
	v_mfma_f32_16x16x32_bf16 v[68:71], v[174:177], v[238:241], 0
	v_mfma_f32_16x16x32_bf16 v[68:71], v[184:187], v[242:245], v[68:71]
	v_mfma_f32_16x16x32_bf16 v[112:115], v[188:191], v[214:217], 0
	v_mfma_f32_16x16x32_bf16 v[112:115], v[210:213], v[218:221], v[112:115]
	v_mfma_f32_16x16x32_bf16 v[96:99], v[188:191], v[222:225], 0
	v_mfma_f32_16x16x32_bf16 v[96:99], v[210:213], v[226:229], v[96:99]
	v_mfma_f32_16x16x32_bf16 v[80:83], v[188:191], v[230:233], 0
	v_mfma_f32_16x16x32_bf16 v[80:83], v[210:213], v[234:237], v[80:83]
	v_mfma_f32_16x16x32_bf16 v[64:67], v[188:191], v[238:241], 0
	v_mfma_f32_16x16x32_bf16 v[64:67], v[210:213], v[242:245], v[64:67]
	s_setprio 0
	s_barrier
	s_mov_b32 m0, s35
	s_add_u32 s0, s4, 0xb0000
	s_addc_u32 s1, s5, 0
	ds_read_b128 v[214:217], v181 offset:16384
	ds_read_b128 v[218:221], v181 offset:17408
	global_load_lds_dwordx4 v166, s[4:5]
	s_mov_b32 m0, s38
	ds_read_b128 v[222:225], v181 offset:18432
	ds_read_b128 v[226:229], v181 offset:19456
	global_load_lds_dwordx4 v162, s[4:5]
	s_mov_b32 m0, s39
	ds_read_b128 v[230:233], v181 offset:20480
	global_load_lds_dwordx4 v166, s[0:1]
	s_mov_b32 m0, s40
	ds_read_b128 v[234:237], v181 offset:21504
	global_load_lds_dwordx4 v162, s[0:1]
	s_mov_b32 m0, s29
	ds_read_b128 v[238:241], v181 offset:22528
	global_load_lds_dwordx4 v168, s[6:7]
	s_mov_b32 m0, s41
	ds_read_b128 v[242:245], v181 offset:23552
	global_load_lds_dwordx4 v164, s[6:7]
	s_waitcnt vmcnt(8) lgkmcnt(0)
	s_barrier
	s_setprio 1
	v_mfma_f32_16x16x32_bf16 v[60:63], v[128:131], v[214:217], 0
	v_mfma_f32_16x16x32_bf16 v[60:63], v[132:135], v[218:221], v[60:63]
	v_mfma_f32_16x16x32_bf16 v[44:47], v[128:131], v[222:225], 0
	v_mfma_f32_16x16x32_bf16 v[44:47], v[132:135], v[226:229], v[44:47]
	v_mfma_f32_16x16x32_bf16 v[28:31], v[128:131], v[230:233], 0
	v_mfma_f32_16x16x32_bf16 v[28:31], v[132:135], v[234:237], v[28:31]
	v_mfma_f32_16x16x32_bf16 v[12:15], v[128:131], v[238:241], 0
	v_mfma_f32_16x16x32_bf16 v[12:15], v[132:135], v[242:245], v[12:15]
	v_mfma_f32_16x16x32_bf16 v[56:59], v[136:139], v[214:217], 0
	v_mfma_f32_16x16x32_bf16 v[56:59], v[140:143], v[218:221], v[56:59]
	v_mfma_f32_16x16x32_bf16 v[40:43], v[136:139], v[222:225], 0
	v_mfma_f32_16x16x32_bf16 v[40:43], v[140:143], v[226:229], v[40:43]
	v_mfma_f32_16x16x32_bf16 v[24:27], v[136:139], v[230:233], 0
	v_mfma_f32_16x16x32_bf16 v[24:27], v[140:143], v[234:237], v[24:27]
	v_mfma_f32_16x16x32_bf16 v[8:11], v[136:139], v[238:241], 0
	v_mfma_f32_16x16x32_bf16 v[8:11], v[140:143], v[242:245], v[8:11]
	v_mfma_f32_16x16x32_bf16 v[52:55], v[174:177], v[214:217], 0
	v_mfma_f32_16x16x32_bf16 v[52:55], v[184:187], v[218:221], v[52:55]
	v_mfma_f32_16x16x32_bf16 v[36:39], v[174:177], v[222:225], 0
	v_mfma_f32_16x16x32_bf16 v[36:39], v[184:187], v[226:229], v[36:39]
	v_mfma_f32_16x16x32_bf16 v[20:23], v[174:177], v[230:233], 0
	v_mfma_f32_16x16x32_bf16 v[20:23], v[184:187], v[234:237], v[20:23]
	v_mfma_f32_16x16x32_bf16 v[4:7], v[174:177], v[238:241], 0
	v_mfma_f32_16x16x32_bf16 v[4:7], v[184:187], v[242:245], v[4:7]
	v_mfma_f32_16x16x32_bf16 v[48:51], v[188:191], v[214:217], 0
	v_mfma_f32_16x16x32_bf16 v[48:51], v[210:213], v[218:221], v[48:51]
	v_mfma_f32_16x16x32_bf16 v[32:35], v[188:191], v[222:225], 0
	v_mfma_f32_16x16x32_bf16 v[32:35], v[210:213], v[226:229], v[32:35]
	v_mfma_f32_16x16x32_bf16 v[16:19], v[188:191], v[230:233], 0
	v_mfma_f32_16x16x32_bf16 v[16:19], v[210:213], v[234:237], v[16:19]
	v_mfma_f32_16x16x32_bf16 v[0:3], v[188:191], v[238:241], 0
	v_mfma_f32_16x16x32_bf16 v[0:3], v[210:213], v[242:245], v[0:3]
	s_setprio 0
	s_barrier
; #define PG8_STAGE(bufoff, gbase, voff) do { _Pragma("unroll") for (int _i = 0; _i < 2; ++_i) \
;         __builtin_amdgcn_global_load_lds((const unsigned*)((const char*)(gbase) + (voff)[_i]), (PG8_LAS unsigned*)(lds + (bufoff) + ldsw + _i * 8192), 16, 0, 0); } while (0)
; #define PG8_LDA(dst, b, h) do { _Pragma("unroll") for (int m = 0; m < 4; ++m) _Pragma("unroll") for (int k = 0; k < 2; ++k) dst[m][k] = *(const PG8_LAS bf16x8*)(lds + PG8_SA(b, h) + aoff + m * 2048 + k * 1024); } while (0)
; #define PG8_LDB(dst, b, h) do { _Pragma("unroll") for (int n = 0; n < 2; ++n) _Pragma("unroll") for (int k = 0; k < 2; ++k) dst[n][k] = *(const PG8_LAS bf16x8*)(lds + PG8_SB(b, h) + boff + n * 2048 + k * 1024); } while (0)
; #define PG8_MMA(ai, bj, At, Bt) do { __builtin_amdgcn_s_setprio(1); _Pragma("unroll") for (int m = 0; m < 4; ++m) _Pragma("unroll") for (int n = 0; n < 2; ++n) _Pragma("unroll") for (int k = 0; k < 2; ++k) \
;         acc[ai][bj][m][n] = __builtin_amdgcn_mfma_f32_16x16x32_bf16(Bt[n][k], At[m][k], acc[ai][bj][m][n], 0, 0, 0); __builtin_amdgcn_s_setprio(0); } while (0)
; #define PG8_WAIT_V(n) asm volatile("s_waitcnt vmcnt(" #n ")" ::: "memory")
; #define PG8_WAIT_L(n) asm volatile("s_waitcnt lgkmcnt(" #n ")" ::: "memory")
; #define PG8_BAR __builtin_amdgcn_s_barrier()
; #define PG8_SCHED __builtin_amdgcn_sched_barrier(0)
; template <class Epi, class Sched, bool ALIGN_EPI = false, bool SP2 = false>
; __device__ __forceinline__ void gemm_phase(PG8_LAS unsigned char* lds, const Gemm g, const Sched& S, const Epi& E) {
;     ...
;             PG8_LDB(B0, 1, 0); PG8_LDB(B1, 1, 1); PG8_SCHED; PG8_LDA(At, 1, 0); PG8_STAGE(PG8_SA(0, 1), a2 + hstep, voffA);
;             PG8_WAIT_V(8); PG8_WAIT_L(0); PG8_BAR; PG8_MMA(0, 0, At, B0); PG8_MMA(0, 1, At, B1); PG8_BAR; PG8_SCHED;
;             PG8_LDA(At, 1, 1); PG8_STAGE(PG8_SB(1, 0), b3, voffB); PG8_STAGE(PG8_SB(1, 1), b3 + hstep, voffB); PG8_STAGE(PG8_SA(1, 0), a3, voffA);
;             PG8_WAIT_V(8); PG8_WAIT_L(0); PG8_BAR; PG8_MMA(1, 0, At, B0); PG8_MMA(1, 1, At, B1); PG8_BAR; PG8_SCHED;
	s_add_u32 s0, s6, 0xb0000
	s_addc_u32 s1, s7, 0
	s_mov_b32 m0, s42
	ds_read_b128 v[128:131], v254 offset:32768
	ds_read_b128 v[132:135], v254 offset:33792
	ds_read_b128 v[136:139], v254 offset:34816
	ds_read_b128 v[140:143], v254 offset:35840
	ds_read_b128 v[174:177], v254 offset:49152
	ds_read_b128 v[184:187], v254 offset:50176
	ds_read_b128 v[188:191], v254 offset:51200
	ds_read_b128 v[210:213], v254 offset:52224
	global_load_lds_dwordx4 v168, s[0:1]
	s_mov_b32 m0, s43
	ds_read_b128 v[214:217], v181 offset:32768
	ds_read_b128 v[218:221], v181 offset:33792
	ds_read_b128 v[222:225], v181 offset:34816
	ds_read_b128 v[226:229], v181 offset:35840
	ds_read_b128 v[230:233], v181 offset:36864
	ds_read_b128 v[234:237], v181 offset:37888
	ds_read_b128 v[238:241], v181 offset:38912
	ds_read_b128 v[242:245], v181 offset:39936
	global_load_lds_dwordx4 v164, s[0:1]
	s_waitcnt vmcnt(8) lgkmcnt(0)
	s_barrier
	s_setprio 1
	v_mfma_f32_16x16x32_bf16 v[124:127], v[128:131], v[214:217], v[124:127]
	v_mfma_f32_16x16x32_bf16 v[124:127], v[132:135], v[218:221], v[124:127]
	v_mfma_f32_16x16x32_bf16 v[108:111], v[128:131], v[222:225], v[108:111]
	v_mfma_f32_16x16x32_bf16 v[108:111], v[132:135], v[226:229], v[108:111]
	v_mfma_f32_16x16x32_bf16 v[92:95], v[128:131], v[230:233], v[92:95]
	v_mfma_f32_16x16x32_bf16 v[92:95], v[132:135], v[234:237], v[92:95]
	v_mfma_f32_16x16x32_bf16 v[76:79], v[128:131], v[238:241], v[76:79]
	v_mfma_f32_16x16x32_bf16 v[76:79], v[132:135], v[242:245], v[76:79]
	v_mfma_f32_16x16x32_bf16 v[120:123], v[136:139], v[214:217], v[120:123]
	v_mfma_f32_16x16x32_bf16 v[120:123], v[140:143], v[218:221], v[120:123]
	v_mfma_f32_16x16x32_bf16 v[104:107], v[136:139], v[222:225], v[104:107]
	v_mfma_f32_16x16x32_bf16 v[104:107], v[140:143], v[226:229], v[104:107]
	v_mfma_f32_16x16x32_bf16 v[88:91], v[136:139], v[230:233], v[88:91]
	v_mfma_f32_16x16x32_bf16 v[88:91], v[140:143], v[234:237], v[88:91]
	v_mfma_f32_16x16x32_bf16 v[72:75], v[136:139], v[238:241], v[72:75]
	v_mfma_f32_16x16x32_bf16 v[72:75], v[140:143], v[242:245], v[72:75]
	v_mfma_f32_16x16x32_bf16 v[116:119], v[174:177], v[214:217], v[116:119]
	v_mfma_f32_16x16x32_bf16 v[116:119], v[184:187], v[218:221], v[116:119]
	v_mfma_f32_16x16x32_bf16 v[100:103], v[174:177], v[222:225], v[100:103]
	v_mfma_f32_16x16x32_bf16 v[100:103], v[184:187], v[226:229], v[100:103]
	v_mfma_f32_16x16x32_bf16 v[84:87], v[174:177], v[230:233], v[84:87]
	v_mfma_f32_16x16x32_bf16 v[84:87], v[184:187], v[234:237], v[84:87]
	v_mfma_f32_16x16x32_bf16 v[68:71], v[174:177], v[238:241], v[68:71]
	v_mfma_f32_16x16x32_bf16 v[68:71], v[184:187], v[242:245], v[68:71]
	v_mfma_f32_16x16x32_bf16 v[112:115], v[188:191], v[214:217], v[112:115]
	v_mfma_f32_16x16x32_bf16 v[112:115], v[210:213], v[218:221], v[112:115]
	v_mfma_f32_16x16x32_bf16 v[96:99], v[188:191], v[222:225], v[96:99]
	v_mfma_f32_16x16x32_bf16 v[96:99], v[210:213], v[226:229], v[96:99]
	v_mfma_f32_16x16x32_bf16 v[80:83], v[188:191], v[230:233], v[80:83]
	v_mfma_f32_16x16x32_bf16 v[80:83], v[210:213], v[234:237], v[80:83]
	v_mfma_f32_16x16x32_bf16 v[64:67], v[188:191], v[238:241], v[64:67]
	v_mfma_f32_16x16x32_bf16 v[64:67], v[210:213], v[242:245], v[64:67]
	s_setprio 0
	s_barrier
	s_mov_b32 m0, s47
	s_add_u32 s0, s4, 0xb0080
	s_addc_u32 s1, s5, 0
	s_add_u32 s98, s4, 0x80
	s_addc_u32 s99, s5, 0
	ds_read_b128 v[214:217], v181 offset:49152
	ds_read_b128 v[218:221], v181 offset:50176
	global_load_lds_dwordx4 v166, s[98:99]
	s_mov_b32 m0, s48
	ds_read_b128 v[222:225], v181 offset:51200
	ds_read_b128 v[226:229], v181 offset:52224
	global_load_lds_dwordx4 v162, s[98:99]
	s_mov_b32 m0, s51
	ds_read_b128 v[230:233], v181 offset:53248
	global_load_lds_dwordx4 v166, s[0:1]
	s_mov_b32 m0, s52
	ds_read_b128 v[234:237], v181 offset:54272
	global_load_lds_dwordx4 v162, s[0:1]
	s_mov_b32 m0, s49
	s_add_u32 s100, s6, 0x80
	s_addc_u32 s101, s7, 0
	ds_read_b128 v[238:241], v181 offset:55296
	global_load_lds_dwordx4 v168, s[100:101]
	s_mov_b32 m0, s50
	ds_read_b128 v[242:245], v181 offset:56320
	global_load_lds_dwordx4 v164, s[100:101]
	s_waitcnt vmcnt(8) lgkmcnt(0)
	s_barrier
	s_setprio 1
	v_mfma_f32_16x16x32_bf16 v[60:63], v[128:131], v[214:217], v[60:63]
	v_mfma_f32_16x16x32_bf16 v[60:63], v[132:135], v[218:221], v[60:63]
	v_mfma_f32_16x16x32_bf16 v[44:47], v[128:131], v[222:225], v[44:47]
	v_mfma_f32_16x16x32_bf16 v[44:47], v[132:135], v[226:229], v[44:47]
	v_mfma_f32_16x16x32_bf16 v[28:31], v[128:131], v[230:233], v[28:31]
	v_mfma_f32_16x16x32_bf16 v[28:31], v[132:135], v[234:237], v[28:31]
	v_mfma_f32_16x16x32_bf16 v[12:15], v[128:131], v[238:241], v[12:15]
	v_mfma_f32_16x16x32_bf16 v[12:15], v[132:135], v[242:245], v[12:15]
	v_mfma_f32_16x16x32_bf16 v[56:59], v[136:139], v[214:217], v[56:59]
	v_mfma_f32_16x16x32_bf16 v[56:59], v[140:143], v[218:221], v[56:59]
	v_mfma_f32_16x16x32_bf16 v[40:43], v[136:139], v[222:225], v[40:43]
	v_mfma_f32_16x16x32_bf16 v[40:43], v[140:143], v[226:229], v[40:43]
	v_mfma_f32_16x16x32_bf16 v[24:27], v[136:139], v[230:233], v[24:27]
	v_mfma_f32_16x16x32_bf16 v[24:27], v[140:143], v[234:237], v[24:27]
	v_mfma_f32_16x16x32_bf16 v[8:11], v[136:139], v[238:241], v[8:11]
	v_mfma_f32_16x16x32_bf16 v[8:11], v[140:143], v[242:245], v[8:11]
	v_mfma_f32_16x16x32_bf16 v[52:55], v[174:177], v[214:217], v[52:55]
	v_mfma_f32_16x16x32_bf16 v[52:55], v[184:187], v[218:221], v[52:55]
	v_mfma_f32_16x16x32_bf16 v[36:39], v[174:177], v[222:225], v[36:39]
	v_mfma_f32_16x16x32_bf16 v[36:39], v[184:187], v[226:229], v[36:39]
	v_mfma_f32_16x16x32_bf16 v[20:23], v[174:177], v[230:233], v[20:23]
	v_mfma_f32_16x16x32_bf16 v[20:23], v[184:187], v[234:237], v[20:23]
	v_mfma_f32_16x16x32_bf16 v[4:7], v[174:177], v[238:241], v[4:7]
	v_mfma_f32_16x16x32_bf16 v[4:7], v[184:187], v[242:245], v[4:7]
	v_mfma_f32_16x16x32_bf16 v[48:51], v[188:191], v[214:217], v[48:51]
	v_mfma_f32_16x16x32_bf16 v[48:51], v[210:213], v[218:221], v[48:51]
	v_mfma_f32_16x16x32_bf16 v[32:35], v[188:191], v[222:225], v[32:35]
	v_mfma_f32_16x16x32_bf16 v[32:35], v[210:213], v[226:229], v[32:35]
	v_mfma_f32_16x16x32_bf16 v[16:19], v[188:191], v[230:233], v[16:19]
	v_mfma_f32_16x16x32_bf16 v[16:19], v[210:213], v[234:237], v[16:19]
	v_mfma_f32_16x16x32_bf16 v[0:3], v[188:191], v[238:241], v[0:3]
	v_mfma_f32_16x16x32_bf16 v[0:3], v[210:213], v[242:245], v[0:3]
	s_setprio 0
	s_barrier
	s_add_i32 s13, s13, 2
	s_add_u32 s10, s10, 0x100
	s_addc_u32 s11, s11, 0
	s_cmp_gt_u32 s13, 41
	s_mov_b64 s[0:1], s[2:3]
; #define PG8_STAGE(bufoff, gbase, voff) do { _Pragma("unroll") for (int _i = 0; _i < 2; ++_i) \
;         __builtin_amdgcn_global_load_lds((const unsigned*)((const char*)(gbase) + (voff)[_i]), (PG8_LAS unsigned*)(lds + (bufoff) + ldsw + _i * 8192), 16, 0, 0); } while (0)
; #define PG8_LDA(dst, b, h) do { _Pragma("unroll") for (int m = 0; m < 4; ++m) _Pragma("unroll") for (int k = 0; k < 2; ++k) dst[m][k] = *(const PG8_LAS bf16x8*)(lds + PG8_SA(b, h) + aoff + m * 2048 + k * 1024); } while (0)
; #define PG8_LDB(dst, b, h) do { _Pragma("unroll") for (int n = 0; n < 2; ++n) _Pragma("unroll") for (int k = 0; k < 2; ++k) dst[n][k] = *(const PG8_LAS bf16x8*)(lds + PG8_SB(b, h) + boff + n * 2048 + k * 1024); } while (0)
; #define PG8_MMA(ai, bj, At, Bt) do { __builtin_amdgcn_s_setprio(1); _Pragma("unroll") for (int m = 0; m < 4; ++m) _Pragma("unroll") for (int n = 0; n < 2; ++n) _Pragma("unroll") for (int k = 0; k < 2; ++k) \
;         acc[ai][bj][m][n] = __builtin_amdgcn_mfma_f32_16x16x32_bf16(Bt[n][k], At[m][k], acc[ai][bj][m][n], 0, 0, 0); __builtin_amdgcn_s_setprio(0); } while (0)
; #define PG8_WAIT_V(n) asm volatile("s_waitcnt vmcnt(" #n ")" ::: "memory")
; #define PG8_BAR __builtin_amdgcn_s_barrier()
; template <class Epi, class Sched, bool ALIGN_EPI = false, bool SP2 = false>
; __device__ __forceinline__ void gemm_phase(PG8_LAS unsigned char* lds, const Gemm g, const Sched& S, const Epi& E) {
;     ...
;         for (int t = 0; t < nt; t += 2) {
;             const bool last = (t == nt - 2);
;             const char* a1 = cA + (size_t)(t + 1) * kstep;
;             const char* a2 = last ? nA : cA + (size_t)(t + 2) * kstep; const char* b2 = last ? nB : cB + (size_t)(t + 2) * kstep;
;             const char* a3 = a2 + kstep; const char* b3 = b2 + kstep;
;             if (last && has_next) S.a_ready(nxt);
;             if constexpr (SP2) {
;             PG8_LDB(B0, 0, 0); PG8_LDB(B1, 0, 1); PG8_SCHED; PG8_LDA(At, 0, 0); PG8_STAGE(PG8_SA(1, 1), a1 + hstep, voffA);
;             PG8_WAIT_V(8); PG8_WAIT_L(0); PG8_BAR; PG8_MMA(0, 0, At, B0); PG8_MMA(0, 1, At, B1); PG8_BAR; PG8_SCHED;
;             PG8_LDA(At, 0, 1); PG8_STAGE(PG8_SB(0, 0), b2, voffB); PG8_STAGE(PG8_SB(0, 1), b2 + hstep, voffB); PG8_STAGE(PG8_SA(0, 0), a2, voffA);
;             PG8_WAIT_V(8); PG8_WAIT_L(0); PG8_BAR; PG8_MMA(1, 0, At, B0); PG8_MMA(1, 1, At, B1); PG8_BAR; PG8_SCHED;
.LBB0_545:
	s_add_u32 s2, s0, 0x100
	s_addc_u32 s3, s1, 0
	s_cmp_eq_u32 s13, 40
	s_cselect_b32 s7, s27, s3
	s_cselect_b32 s6, s26, s2
	s_cselect_b32 s5, s37, s11
	s_cselect_b32 s4, s36, s10
	s_add_i32 m0, s29, 0xc000
	ds_read_b128 v[128:131], v254
	ds_read_b128 v[132:135], v254 offset:1024
	ds_read_b128 v[136:139], v254 offset:2048
	ds_read_b128 v[140:143], v254 offset:3072
	ds_read_b128 v[174:177], v254 offset:16384
	ds_read_b128 v[184:187], v254 offset:17408
	ds_read_b128 v[188:191], v254 offset:18432
	ds_read_b128 v[210:213], v254 offset:19456
	global_load_lds_dwordx4 v170, s[0:1]
	s_add_i32 m0, s29, 0xe000
	ds_read_b128 v[214:217], v181
	ds_read_b128 v[218:221], v181 offset:1024
	ds_read_b128 v[222:225], v181 offset:2048
	ds_read_b128 v[226:229], v181 offset:3072
	ds_read_b128 v[230:233], v181 offset:4096
	ds_read_b128 v[234:237], v181 offset:5120
	ds_read_b128 v[238:241], v181 offset:6144
	ds_read_b128 v[242:245], v181 offset:7168
	global_load_lds_dwordx4 v172, s[0:1]
	s_waitcnt vmcnt(8) lgkmcnt(0)
	s_barrier
	s_setprio 1
	v_mfma_f32_16x16x32_bf16 v[124:127], v[128:131], v[214:217], v[124:127]
	v_mfma_f32_16x16x32_bf16 v[124:127], v[132:135], v[218:221], v[124:127]
	v_mfma_f32_16x16x32_bf16 v[108:111], v[128:131], v[222:225], v[108:111]
	v_mfma_f32_16x16x32_bf16 v[108:111], v[132:135], v[226:229], v[108:111]
	v_mfma_f32_16x16x32_bf16 v[92:95], v[128:131], v[230:233], v[92:95]
	v_mfma_f32_16x16x32_bf16 v[92:95], v[132:135], v[234:237], v[92:95]
	v_mfma_f32_16x16x32_bf16 v[76:79], v[128:131], v[238:241], v[76:79]
	v_mfma_f32_16x16x32_bf16 v[76:79], v[132:135], v[242:245], v[76:79]
	v_mfma_f32_16x16x32_bf16 v[120:123], v[136:139], v[214:217], v[120:123]
	v_mfma_f32_16x16x32_bf16 v[120:123], v[140:143], v[218:221], v[120:123]
	v_mfma_f32_16x16x32_bf16 v[104:107], v[136:139], v[222:225], v[104:107]
	v_mfma_f32_16x16x32_bf16 v[104:107], v[140:143], v[226:229], v[104:107]
	v_mfma_f32_16x16x32_bf16 v[88:91], v[136:139], v[230:233], v[88:91]
	v_mfma_f32_16x16x32_bf16 v[88:91], v[140:143], v[234:237], v[88:91]
	v_mfma_f32_16x16x32_bf16 v[72:75], v[136:139], v[238:241], v[72:75]
	v_mfma_f32_16x16x32_bf16 v[72:75], v[140:143], v[242:245], v[72:75]
	v_mfma_f32_16x16x32_bf16 v[116:119], v[174:177], v[214:217], v[116:119]
	v_mfma_f32_16x16x32_bf16 v[116:119], v[184:187], v[218:221], v[116:119]
	v_mfma_f32_16x16x32_bf16 v[100:103], v[174:177], v[222:225], v[100:103]
	v_mfma_f32_16x16x32_bf16 v[100:103], v[184:187], v[226:229], v[100:103]
	v_mfma_f32_16x16x32_bf16 v[84:87], v[174:177], v[230:233], v[84:87]
	v_mfma_f32_16x16x32_bf16 v[84:87], v[184:187], v[234:237], v[84:87]
	v_mfma_f32_16x16x32_bf16 v[68:71], v[174:177], v[238:241], v[68:71]
	v_mfma_f32_16x16x32_bf16 v[68:71], v[184:187], v[242:245], v[68:71]
	v_mfma_f32_16x16x32_bf16 v[112:115], v[188:191], v[214:217], v[112:115]
	v_mfma_f32_16x16x32_bf16 v[112:115], v[210:213], v[218:221], v[112:115]
	v_mfma_f32_16x16x32_bf16 v[96:99], v[188:191], v[222:225], v[96:99]
	v_mfma_f32_16x16x32_bf16 v[96:99], v[210:213], v[226:229], v[96:99]
	v_mfma_f32_16x16x32_bf16 v[80:83], v[188:191], v[230:233], v[80:83]
	v_mfma_f32_16x16x32_bf16 v[80:83], v[210:213], v[234:237], v[80:83]
	v_mfma_f32_16x16x32_bf16 v[64:67], v[188:191], v[238:241], v[64:67]
	v_mfma_f32_16x16x32_bf16 v[64:67], v[210:213], v[242:245], v[64:67]
	s_setprio 0
	s_barrier
	s_mov_b32 m0, s35
	s_add_u32 s0, s4, 0xb0000
	s_addc_u32 s1, s5, 0
	ds_read_b128 v[214:217], v181 offset:16384
	ds_read_b128 v[218:221], v181 offset:17408
	global_load_lds_dwordx4 v166, s[4:5]
	s_mov_b32 m0, s38
	ds_read_b128 v[222:225], v181 offset:18432
	ds_read_b128 v[226:229], v181 offset:19456
	global_load_lds_dwordx4 v162, s[4:5]
	s_mov_b32 m0, s39
	ds_read_b128 v[230:233], v181 offset:20480
	global_load_lds_dwordx4 v166, s[0:1]
	s_mov_b32 m0, s40
	ds_read_b128 v[234:237], v181 offset:21504
	global_load_lds_dwordx4 v162, s[0:1]
	s_mov_b32 m0, s29
	ds_read_b128 v[238:241], v181 offset:22528
	global_load_lds_dwordx4 v168, s[6:7]
	s_mov_b32 m0, s41
	ds_read_b128 v[242:245], v181 offset:23552
	global_load_lds_dwordx4 v164, s[6:7]
	s_waitcnt vmcnt(8) lgkmcnt(0)
	s_barrier
	s_setprio 1
	v_mfma_f32_16x16x32_bf16 v[60:63], v[128:131], v[214:217], v[60:63]
	v_mfma_f32_16x16x32_bf16 v[60:63], v[132:135], v[218:221], v[60:63]
	v_mfma_f32_16x16x32_bf16 v[44:47], v[128:131], v[222:225], v[44:47]
	v_mfma_f32_16x16x32_bf16 v[44:47], v[132:135], v[226:229], v[44:47]
	v_mfma_f32_16x16x32_bf16 v[28:31], v[128:131], v[230:233], v[28:31]
	v_mfma_f32_16x16x32_bf16 v[28:31], v[132:135], v[234:237], v[28:31]
	v_mfma_f32_16x16x32_bf16 v[12:15], v[128:131], v[238:241], v[12:15]
	v_mfma_f32_16x16x32_bf16 v[12:15], v[132:135], v[242:245], v[12:15]
	v_mfma_f32_16x16x32_bf16 v[56:59], v[136:139], v[214:217], v[56:59]
	v_mfma_f32_16x16x32_bf16 v[56:59], v[140:143], v[218:221], v[56:59]
	v_mfma_f32_16x16x32_bf16 v[40:43], v[136:139], v[222:225], v[40:43]
	v_mfma_f32_16x16x32_bf16 v[40:43], v[140:143], v[226:229], v[40:43]
	v_mfma_f32_16x16x32_bf16 v[24:27], v[136:139], v[230:233], v[24:27]
	v_mfma_f32_16x16x32_bf16 v[24:27], v[140:143], v[234:237], v[24:27]
	v_mfma_f32_16x16x32_bf16 v[8:11], v[136:139], v[238:241], v[8:11]
	v_mfma_f32_16x16x32_bf16 v[8:11], v[140:143], v[242:245], v[8:11]
	v_mfma_f32_16x16x32_bf16 v[52:55], v[174:177], v[214:217], v[52:55]
	v_mfma_f32_16x16x32_bf16 v[52:55], v[184:187], v[218:221], v[52:55]
	v_mfma_f32_16x16x32_bf16 v[36:39], v[174:177], v[222:225], v[36:39]
	v_mfma_f32_16x16x32_bf16 v[36:39], v[184:187], v[226:229], v[36:39]
	v_mfma_f32_16x16x32_bf16 v[20:23], v[174:177], v[230:233], v[20:23]
	v_mfma_f32_16x16x32_bf16 v[20:23], v[184:187], v[234:237], v[20:23]
	v_mfma_f32_16x16x32_bf16 v[4:7], v[174:177], v[238:241], v[4:7]
	v_mfma_f32_16x16x32_bf16 v[4:7], v[184:187], v[242:245], v[4:7]
	v_mfma_f32_16x16x32_bf16 v[48:51], v[188:191], v[214:217], v[48:51]
	v_mfma_f32_16x16x32_bf16 v[48:51], v[210:213], v[218:221], v[48:51]
	v_mfma_f32_16x16x32_bf16 v[32:35], v[188:191], v[222:225], v[32:35]
	v_mfma_f32_16x16x32_bf16 v[32:35], v[210:213], v[226:229], v[32:35]
	v_mfma_f32_16x16x32_bf16 v[16:19], v[188:191], v[230:233], v[16:19]
	v_mfma_f32_16x16x32_bf16 v[16:19], v[210:213], v[234:237], v[16:19]
	v_mfma_f32_16x16x32_bf16 v[0:3], v[188:191], v[238:241], v[0:3]
	v_mfma_f32_16x16x32_bf16 v[0:3], v[210:213], v[242:245], v[0:3]
	s_setprio 0
	s_barrier
; #define PG8_STAGE(bufoff, gbase, voff) do { _Pragma("unroll") for (int _i = 0; _i < 2; ++_i) \
;         __builtin_amdgcn_global_load_lds((const unsigned*)((const char*)(gbase) + (voff)[_i]), (PG8_LAS unsigned*)(lds + (bufoff) + ldsw + _i * 8192), 16, 0, 0); } while (0)
; #define PG8_LDA(dst, b, h) do { _Pragma("unroll") for (int m = 0; m < 4; ++m) _Pragma("unroll") for (int k = 0; k < 2; ++k) dst[m][k] = *(const PG8_LAS bf16x8*)(lds + PG8_SA(b, h) + aoff + m * 2048 + k * 1024); } while (0)
; #define PG8_LDB(dst, b, h) do { _Pragma("unroll") for (int n = 0; n < 2; ++n) _Pragma("unroll") for (int k = 0; k < 2; ++k) dst[n][k] = *(const PG8_LAS bf16x8*)(lds + PG8_SB(b, h) + boff + n * 2048 + k * 1024); } while (0)
; #define PG8_MMA(ai, bj, At, Bt) do { __builtin_amdgcn_s_setprio(1); _Pragma("unroll") for (int m = 0; m < 4; ++m) _Pragma("unroll") for (int n = 0; n < 2; ++n) _Pragma("unroll") for (int k = 0; k < 2; ++k) \
;         acc[ai][bj][m][n] = __builtin_amdgcn_mfma_f32_16x16x32_bf16(Bt[n][k], At[m][k], acc[ai][bj][m][n], 0, 0, 0); __builtin_amdgcn_s_setprio(0); } while (0)
; #define PG8_WAIT_V(n) asm volatile("s_waitcnt vmcnt(" #n ")" ::: "memory")
; #define PG8_WAIT_L(n) asm volatile("s_waitcnt lgkmcnt(" #n ")" ::: "memory")
; #define PG8_BAR __builtin_amdgcn_s_barrier()
; #define PG8_SCHED __builtin_amdgcn_sched_barrier(0)
; template <class Epi, class Sched, bool ALIGN_EPI = false, bool SP2 = false>
; __device__ __forceinline__ void gemm_phase(PG8_LAS unsigned char* lds, const Gemm g, const Sched& S, const Epi& E) {
;     ...
;         for (int t = 0; t < nt; t += 2) {
;     ...
;             PG8_LDB(B0, 1, 0); PG8_LDB(B1, 1, 1); PG8_SCHED; PG8_LDA(At, 1, 0); PG8_STAGE(PG8_SA(0, 1), a2 + hstep, voffA);
;             PG8_WAIT_V(8); PG8_WAIT_L(0); PG8_BAR; PG8_MMA(0, 0, At, B0); PG8_MMA(0, 1, At, B1); PG8_BAR; PG8_SCHED;
;             PG8_LDA(At, 1, 1); PG8_STAGE(PG8_SB(1, 0), b3, voffB); PG8_STAGE(PG8_SB(1, 1), b3 + hstep, voffB); PG8_STAGE(PG8_SA(1, 0), a3, voffA);
;             PG8_WAIT_V(8); PG8_WAIT_L(0); PG8_BAR; PG8_MMA(1, 0, At, B0); PG8_MMA(1, 1, At, B1); PG8_BAR; PG8_SCHED;
	s_add_u32 s0, s6, 0xb0000
	s_addc_u32 s1, s7, 0
	s_mov_b32 m0, s42
	ds_read_b128 v[128:131], v254 offset:32768
	ds_read_b128 v[132:135], v254 offset:33792
	ds_read_b128 v[136:139], v254 offset:34816
	ds_read_b128 v[140:143], v254 offset:35840
	ds_read_b128 v[174:177], v254 offset:49152
	ds_read_b128 v[184:187], v254 offset:50176
	ds_read_b128 v[188:191], v254 offset:51200
	ds_read_b128 v[210:213], v254 offset:52224
	global_load_lds_dwordx4 v168, s[0:1]
	s_mov_b32 m0, s43
	ds_read_b128 v[214:217], v181 offset:32768
	ds_read_b128 v[218:221], v181 offset:33792
	ds_read_b128 v[222:225], v181 offset:34816
	ds_read_b128 v[226:229], v181 offset:35840
	ds_read_b128 v[230:233], v181 offset:36864
	ds_read_b128 v[234:237], v181 offset:37888
	ds_read_b128 v[238:241], v181 offset:38912
	ds_read_b128 v[242:245], v181 offset:39936
	global_load_lds_dwordx4 v164, s[0:1]
	s_waitcnt vmcnt(8) lgkmcnt(0)
	s_barrier
	s_setprio 1
	v_mfma_f32_16x16x32_bf16 v[124:127], v[128:131], v[214:217], v[124:127]
	v_mfma_f32_16x16x32_bf16 v[124:127], v[132:135], v[218:221], v[124:127]
	v_mfma_f32_16x16x32_bf16 v[108:111], v[128:131], v[222:225], v[108:111]
	v_mfma_f32_16x16x32_bf16 v[108:111], v[132:135], v[226:229], v[108:111]
	v_mfma_f32_16x16x32_bf16 v[92:95], v[128:131], v[230:233], v[92:95]
	v_mfma_f32_16x16x32_bf16 v[92:95], v[132:135], v[234:237], v[92:95]
	v_mfma_f32_16x16x32_bf16 v[76:79], v[128:131], v[238:241], v[76:79]
	v_mfma_f32_16x16x32_bf16 v[76:79], v[132:135], v[242:245], v[76:79]
	v_mfma_f32_16x16x32_bf16 v[120:123], v[136:139], v[214:217], v[120:123]
	v_mfma_f32_16x16x32_bf16 v[120:123], v[140:143], v[218:221], v[120:123]
	v_mfma_f32_16x16x32_bf16 v[104:107], v[136:139], v[222:225], v[104:107]
	v_mfma_f32_16x16x32_bf16 v[104:107], v[140:143], v[226:229], v[104:107]
	v_mfma_f32_16x16x32_bf16 v[88:91], v[136:139], v[230:233], v[88:91]
	v_mfma_f32_16x16x32_bf16 v[88:91], v[140:143], v[234:237], v[88:91]
	v_mfma_f32_16x16x32_bf16 v[72:75], v[136:139], v[238:241], v[72:75]
	v_mfma_f32_16x16x32_bf16 v[72:75], v[140:143], v[242:245], v[72:75]
	v_mfma_f32_16x16x32_bf16 v[116:119], v[174:177], v[214:217], v[116:119]
	v_mfma_f32_16x16x32_bf16 v[116:119], v[184:187], v[218:221], v[116:119]
	v_mfma_f32_16x16x32_bf16 v[100:103], v[174:177], v[222:225], v[100:103]
	v_mfma_f32_16x16x32_bf16 v[100:103], v[184:187], v[226:229], v[100:103]
	v_mfma_f32_16x16x32_bf16 v[84:87], v[174:177], v[230:233], v[84:87]
	v_mfma_f32_16x16x32_bf16 v[84:87], v[184:187], v[234:237], v[84:87]
	v_mfma_f32_16x16x32_bf16 v[68:71], v[174:177], v[238:241], v[68:71]
	v_mfma_f32_16x16x32_bf16 v[68:71], v[184:187], v[242:245], v[68:71]
	v_mfma_f32_16x16x32_bf16 v[112:115], v[188:191], v[214:217], v[112:115]
	v_mfma_f32_16x16x32_bf16 v[112:115], v[210:213], v[218:221], v[112:115]
	v_mfma_f32_16x16x32_bf16 v[96:99], v[188:191], v[222:225], v[96:99]
	v_mfma_f32_16x16x32_bf16 v[96:99], v[210:213], v[226:229], v[96:99]
	v_mfma_f32_16x16x32_bf16 v[80:83], v[188:191], v[230:233], v[80:83]
	v_mfma_f32_16x16x32_bf16 v[80:83], v[210:213], v[234:237], v[80:83]
	v_mfma_f32_16x16x32_bf16 v[64:67], v[188:191], v[238:241], v[64:67]
	v_mfma_f32_16x16x32_bf16 v[64:67], v[210:213], v[242:245], v[64:67]
	s_setprio 0
	s_barrier
	s_mov_b32 m0, s47
	s_add_u32 s0, s4, 0xb0080
	s_addc_u32 s1, s5, 0
	s_add_u32 s98, s4, 0x80
	s_addc_u32 s99, s5, 0
	ds_read_b128 v[214:217], v181 offset:49152
	ds_read_b128 v[218:221], v181 offset:50176
	global_load_lds_dwordx4 v166, s[98:99]
	s_mov_b32 m0, s48
	ds_read_b128 v[222:225], v181 offset:51200
	ds_read_b128 v[226:229], v181 offset:52224
	global_load_lds_dwordx4 v162, s[98:99]
	s_mov_b32 m0, s51
	ds_read_b128 v[230:233], v181 offset:53248
	global_load_lds_dwordx4 v166, s[0:1]
	s_mov_b32 m0, s52
	ds_read_b128 v[234:237], v181 offset:54272
	global_load_lds_dwordx4 v162, s[0:1]
	s_mov_b32 m0, s49
	s_add_u32 s100, s6, 0x80
	s_addc_u32 s101, s7, 0
	ds_read_b128 v[238:241], v181 offset:55296
	global_load_lds_dwordx4 v168, s[100:101]
	s_mov_b32 m0, s50
	ds_read_b128 v[242:245], v181 offset:56320
	global_load_lds_dwordx4 v164, s[100:101]
	s_waitcnt vmcnt(8) lgkmcnt(0)
	s_barrier
	s_setprio 1
	v_mfma_f32_16x16x32_bf16 v[60:63], v[128:131], v[214:217], v[60:63]
	v_mfma_f32_16x16x32_bf16 v[60:63], v[132:135], v[218:221], v[60:63]
	v_mfma_f32_16x16x32_bf16 v[44:47], v[128:131], v[222:225], v[44:47]
	v_mfma_f32_16x16x32_bf16 v[44:47], v[132:135], v[226:229], v[44:47]
	v_mfma_f32_16x16x32_bf16 v[28:31], v[128:131], v[230:233], v[28:31]
	v_mfma_f32_16x16x32_bf16 v[28:31], v[132:135], v[234:237], v[28:31]
	v_mfma_f32_16x16x32_bf16 v[12:15], v[128:131], v[238:241], v[12:15]
	v_mfma_f32_16x16x32_bf16 v[12:15], v[132:135], v[242:245], v[12:15]
	v_mfma_f32_16x16x32_bf16 v[56:59], v[136:139], v[214:217], v[56:59]
	v_mfma_f32_16x16x32_bf16 v[56:59], v[140:143], v[218:221], v[56:59]
	v_mfma_f32_16x16x32_bf16 v[40:43], v[136:139], v[222:225], v[40:43]
	v_mfma_f32_16x16x32_bf16 v[40:43], v[140:143], v[226:229], v[40:43]
	v_mfma_f32_16x16x32_bf16 v[24:27], v[136:139], v[230:233], v[24:27]
	v_mfma_f32_16x16x32_bf16 v[24:27], v[140:143], v[234:237], v[24:27]
	v_mfma_f32_16x16x32_bf16 v[8:11], v[136:139], v[238:241], v[8:11]
	v_mfma_f32_16x16x32_bf16 v[8:11], v[140:143], v[242:245], v[8:11]
	v_mfma_f32_16x16x32_bf16 v[52:55], v[174:177], v[214:217], v[52:55]
	v_mfma_f32_16x16x32_bf16 v[52:55], v[184:187], v[218:221], v[52:55]
	v_mfma_f32_16x16x32_bf16 v[36:39], v[174:177], v[222:225], v[36:39]
	v_mfma_f32_16x16x32_bf16 v[36:39], v[184:187], v[226:229], v[36:39]
	v_mfma_f32_16x16x32_bf16 v[20:23], v[174:177], v[230:233], v[20:23]
	v_mfma_f32_16x16x32_bf16 v[20:23], v[184:187], v[234:237], v[20:23]
	v_mfma_f32_16x16x32_bf16 v[4:7], v[174:177], v[238:241], v[4:7]
	v_mfma_f32_16x16x32_bf16 v[4:7], v[184:187], v[242:245], v[4:7]
	v_mfma_f32_16x16x32_bf16 v[48:51], v[188:191], v[214:217], v[48:51]
	v_mfma_f32_16x16x32_bf16 v[48:51], v[210:213], v[218:221], v[48:51]
	v_mfma_f32_16x16x32_bf16 v[32:35], v[188:191], v[222:225], v[32:35]
	v_mfma_f32_16x16x32_bf16 v[32:35], v[210:213], v[226:229], v[32:35]
	v_mfma_f32_16x16x32_bf16 v[16:19], v[188:191], v[230:233], v[16:19]
	v_mfma_f32_16x16x32_bf16 v[16:19], v[210:213], v[234:237], v[16:19]
	v_mfma_f32_16x16x32_bf16 v[0:3], v[188:191], v[238:241], v[0:3]
	v_mfma_f32_16x16x32_bf16 v[0:3], v[210:213], v[242:245], v[0:3]
	s_setprio 0
	s_barrier
	s_add_i32 s13, s13, 2
	s_add_u32 s10, s10, 0x100
	s_addc_u32 s11, s11, 0
	s_cmp_gt_u32 s13, 41
	s_mov_b64 s[0:1], s[2:3]
	s_cbranch_scc0 .LBB0_545
	s_and_b64 vcc, exec, s[22:23]
	s_cbranch_vccz .LBB0_548
	s_barrier

; #define PG8_STAGE(bufoff, gbase, voff) do { _Pragma("unroll") for (int _i = 0; _i < 2; ++_i) \
;         __builtin_amdgcn_global_load_lds((const unsigned*)((const char*)(gbase) + (voff)[_i]), (PG8_LAS unsigned*)(lds + (bufoff) + ldsw + _i * 8192), 16, 0, 0); } while (0)
; #define PG8_LDA(dst, b, h) do { _Pragma("unroll") for (int m = 0; m < 4; ++m) _Pragma("unroll") for (int k = 0; k < 2; ++k) dst[m][k] = *(const PG8_LAS bf16x8*)(lds + PG8_SA(b, h) + aoff + m * 2048 + k * 1024); } while (0)
; #define PG8_LDB(dst, b, h) do { _Pragma("unroll") for (int n = 0; n < 2; ++n) _Pragma("unroll") for (int k = 0; k < 2; ++k) dst[n][k] = *(const PG8_LAS bf16x8*)(lds + PG8_SB(b, h) + boff + n * 2048 + k * 1024); } while (0)
; #define PG8_MMA(ai, bj, At, Bt) do { __builtin_amdgcn_s_setprio(1); _Pragma("unroll") for (int m = 0; m < 4; ++m) _Pragma("unroll") for (int n = 0; n < 2; ++n) _Pragma("unroll") for (int k = 0; k < 2; ++k) \
;         acc[ai][bj][m][n] = __builtin_amdgcn_mfma_f32_16x16x32_bf16(Bt[n][k], At[m][k], acc[ai][bj][m][n], 0, 0, 0); __builtin_amdgcn_s_setprio(0); } while (0)
; #define PG8_WAIT_V(n) asm volatile("s_waitcnt vmcnt(" #n ")" ::: "memory")
; #define PG8_WAIT_L(n) asm volatile("s_waitcnt lgkmcnt(" #n ")" ::: "memory")
; template <class Epi, class Sched, bool ALIGN_EPI = false, bool SP2 = false>
; __device__ __forceinline__ void gemm_phase(PG8_LAS unsigned char* lds, const Gemm g, const Sched& S, const Epi& E) {
;     ...
;             const bool last = (t == nt - 2);
;             const char* a1 = cA + (size_t)(t + 1) * kstep;
;             const char* a2 = last ? nA : cA + (size_t)(t + 2) * kstep; const char* b2 = last ? nB : cB + (size_t)(t + 2) * kstep;
;             const char* a3 = a2 + kstep; const char* b3 = b2 + kstep;
;             if (last && has_next) S.a_ready(nxt);
;             if constexpr (SP2) {
;             PG8_LDB(B0, 0, 0); PG8_LDB(B1, 0, 1); PG8_SCHED; PG8_LDA(At, 0, 0); PG8_STAGE(PG8_SA(1, 1), a1 + hstep, voffA);
;             PG8_WAIT_V(8); PG8_WAIT_L(0); PG8_BAR; PG8_MMA(0, 0, At, B0); PG8_MMA(0, 1, At, B1); PG8_BAR; PG8_SCHED;
;             PG8_LDA(At, 0, 1); PG8_STAGE(PG8_SB(0, 0), b2, voffB); PG8_STAGE(PG8_SB(0, 1), b2 + hstep, voffB); PG8_STAGE(PG8_SA(0, 0), a2, voffA);
;             PG8_WAIT_V(8); PG8_WAIT_L(0); PG8_BAR; PG8_MMA(1, 0, At, B0); PG8_MMA(1, 1, At, B1); PG8_BAR; PG8_SCHED;
.Lsgi_peel:
	s_add_u32 s2, s0, 0xfffc0080
	s_addc_u32 s3, s1, -1
	s_cmp_eq_u32 s55, 12
	s_cselect_b32 s5, s13, s3
	s_cselect_b32 s4, s25, s2
	s_cselect_b32 s3, s23, s39
	s_cselect_b32 s2, s33, s38
	s_add_i32 m0, s6, 0xc000
	ds_read_b128 v[140:143], v254
	ds_read_b128 v[162:165], v254 offset:1024
	ds_read_b128 v[166:169], v254 offset:2048
	ds_read_b128 v[170:173], v254 offset:3072
	ds_read_b128 v[180:183], v254 offset:16384
	ds_read_b128 v[184:187], v254 offset:17408
	ds_read_b128 v[188:191], v254 offset:18432
	ds_read_b128 v[210:213], v254 offset:19456
	global_load_lds_dwordx4 v136, s[0:1]
	s_add_i32 m0, s6, 0xe000
	ds_read_b128 v[214:217], v178
	ds_read_b128 v[218:221], v178 offset:1024
	ds_read_b128 v[222:225], v178 offset:2048
	ds_read_b128 v[226:229], v178 offset:3072
	ds_read_b128 v[230:233], v178 offset:4096
	ds_read_b128 v[234:237], v178 offset:5120
	ds_read_b128 v[238:241], v178 offset:6144
	ds_read_b128 v[242:245], v178 offset:7168
	global_load_lds_dwordx4 v138, s[0:1]
	s_waitcnt vmcnt(8) lgkmcnt(0)
	s_barrier
	s_setprio 1
	v_mfma_f32_16x16x32_bf16 v[124:127], v[140:143], v[214:217], 0
	v_mfma_f32_16x16x32_bf16 v[124:127], v[162:165], v[218:221], v[124:127]
	v_mfma_f32_16x16x32_bf16 v[108:111], v[140:143], v[222:225], 0
	v_mfma_f32_16x16x32_bf16 v[108:111], v[162:165], v[226:229], v[108:111]
	v_mfma_f32_16x16x32_bf16 v[92:95], v[140:143], v[230:233], 0
	v_mfma_f32_16x16x32_bf16 v[92:95], v[162:165], v[234:237], v[92:95]
	v_mfma_f32_16x16x32_bf16 v[76:79], v[140:143], v[238:241], 0
	v_mfma_f32_16x16x32_bf16 v[76:79], v[162:165], v[242:245], v[76:79]
	v_mfma_f32_16x16x32_bf16 v[120:123], v[166:169], v[214:217], 0
	v_mfma_f32_16x16x32_bf16 v[120:123], v[170:173], v[218:221], v[120:123]
	v_mfma_f32_16x16x32_bf16 v[104:107], v[166:169], v[222:225], 0
	v_mfma_f32_16x16x32_bf16 v[104:107], v[170:173], v[226:229], v[104:107]
	v_mfma_f32_16x16x32_bf16 v[88:91], v[166:169], v[230:233], 0
	v_mfma_f32_16x16x32_bf16 v[88:91], v[170:173], v[234:237], v[88:91]
	v_mfma_f32_16x16x32_bf16 v[72:75], v[166:169], v[238:241], 0
	v_mfma_f32_16x16x32_bf16 v[72:75], v[170:173], v[242:245], v[72:75]
	v_mfma_f32_16x16x32_bf16 v[116:119], v[180:183], v[214:217], 0
	v_mfma_f32_16x16x32_bf16 v[116:119], v[184:187], v[218:221], v[116:119]
	v_mfma_f32_16x16x32_bf16 v[100:103], v[180:183], v[222:225], 0
	v_mfma_f32_16x16x32_bf16 v[100:103], v[184:187], v[226:229], v[100:103]
	v_mfma_f32_16x16x32_bf16 v[84:87], v[180:183], v[230:233], 0
	v_mfma_f32_16x16x32_bf16 v[84:87], v[184:187], v[234:237], v[84:87]
	v_mfma_f32_16x16x32_bf16 v[68:71], v[180:183], v[238:241], 0
	v_mfma_f32_16x16x32_bf16 v[68:71], v[184:187], v[242:245], v[68:71]
	v_mfma_f32_16x16x32_bf16 v[112:115], v[188:191], v[214:217], 0
	v_mfma_f32_16x16x32_bf16 v[112:115], v[210:213], v[218:221], v[112:115]
	v_mfma_f32_16x16x32_bf16 v[96:99], v[188:191], v[222:225], 0
	v_mfma_f32_16x16x32_bf16 v[96:99], v[210:213], v[226:229], v[96:99]
	v_mfma_f32_16x16x32_bf16 v[80:83], v[188:191], v[230:233], 0
	v_mfma_f32_16x16x32_bf16 v[80:83], v[210:213], v[234:237], v[80:83]
	v_mfma_f32_16x16x32_bf16 v[64:67], v[188:191], v[238:241], 0
	v_mfma_f32_16x16x32_bf16 v[64:67], v[210:213], v[242:245], v[64:67]
	s_setprio 0
	s_barrier
	s_mov_b32 m0, s31
	s_add_u32 s56, s2, 0x40000
	s_addc_u32 s57, s3, 0
	ds_read_b128 v[214:217], v178 offset:16384
	ds_read_b128 v[218:221], v178 offset:17408
	global_load_lds_dwordx4 v132, s[2:3]
	s_mov_b32 m0, s34
	ds_read_b128 v[222:225], v178 offset:18432
	ds_read_b128 v[226:229], v178 offset:19456
	global_load_lds_dwordx4 v128, s[2:3]
	s_mov_b32 m0, s35
	ds_read_b128 v[230:233], v178 offset:20480
	global_load_lds_dwordx4 v132, s[56:57]
	s_mov_b32 m0, s40
	ds_read_b128 v[234:237], v178 offset:21504
	global_load_lds_dwordx4 v128, s[56:57]
	s_mov_b32 m0, s6
	ds_read_b128 v[238:241], v178 offset:22528
	global_load_lds_dwordx4 v134, s[4:5]
	s_mov_b32 m0, s41
	ds_read_b128 v[242:245], v178 offset:23552
	global_load_lds_dwordx4 v130, s[4:5]
	s_waitcnt vmcnt(8) lgkmcnt(0)
	s_barrier
	s_setprio 1
	v_mfma_f32_16x16x32_bf16 v[60:63], v[140:143], v[214:217], 0
	v_mfma_f32_16x16x32_bf16 v[60:63], v[162:165], v[218:221], v[60:63]
	v_mfma_f32_16x16x32_bf16 v[44:47], v[140:143], v[222:225], 0
	v_mfma_f32_16x16x32_bf16 v[44:47], v[162:165], v[226:229], v[44:47]
	v_mfma_f32_16x16x32_bf16 v[28:31], v[140:143], v[230:233], 0
	v_mfma_f32_16x16x32_bf16 v[28:31], v[162:165], v[234:237], v[28:31]
	v_mfma_f32_16x16x32_bf16 v[12:15], v[140:143], v[238:241], 0
	v_mfma_f32_16x16x32_bf16 v[12:15], v[162:165], v[242:245], v[12:15]
	v_mfma_f32_16x16x32_bf16 v[56:59], v[166:169], v[214:217], 0
	v_mfma_f32_16x16x32_bf16 v[56:59], v[170:173], v[218:221], v[56:59]
	v_mfma_f32_16x16x32_bf16 v[40:43], v[166:169], v[222:225], 0
	v_mfma_f32_16x16x32_bf16 v[40:43], v[170:173], v[226:229], v[40:43]
	v_mfma_f32_16x16x32_bf16 v[24:27], v[166:169], v[230:233], 0
	v_mfma_f32_16x16x32_bf16 v[24:27], v[170:173], v[234:237], v[24:27]
	v_mfma_f32_16x16x32_bf16 v[8:11], v[166:169], v[238:241], 0
	v_mfma_f32_16x16x32_bf16 v[8:11], v[170:173], v[242:245], v[8:11]
	v_mfma_f32_16x16x32_bf16 v[52:55], v[180:183], v[214:217], 0
	v_mfma_f32_16x16x32_bf16 v[52:55], v[184:187], v[218:221], v[52:55]
	v_mfma_f32_16x16x32_bf16 v[36:39], v[180:183], v[222:225], 0
	v_mfma_f32_16x16x32_bf16 v[36:39], v[184:187], v[226:229], v[36:39]
	v_mfma_f32_16x16x32_bf16 v[20:23], v[180:183], v[230:233], 0
	v_mfma_f32_16x16x32_bf16 v[20:23], v[184:187], v[234:237], v[20:23]
	v_mfma_f32_16x16x32_bf16 v[4:7], v[180:183], v[238:241], 0
	v_mfma_f32_16x16x32_bf16 v[4:7], v[184:187], v[242:245], v[4:7]
	v_mfma_f32_16x16x32_bf16 v[48:51], v[188:191], v[214:217], 0
	v_mfma_f32_16x16x32_bf16 v[48:51], v[210:213], v[218:221], v[48:51]
	v_mfma_f32_16x16x32_bf16 v[32:35], v[188:191], v[222:225], 0
	v_mfma_f32_16x16x32_bf16 v[32:35], v[210:213], v[226:229], v[32:35]
	v_mfma_f32_16x16x32_bf16 v[16:19], v[188:191], v[230:233], 0
	v_mfma_f32_16x16x32_bf16 v[16:19], v[210:213], v[234:237], v[16:19]
	v_mfma_f32_16x16x32_bf16 v[0:3], v[188:191], v[238:241], 0
	v_mfma_f32_16x16x32_bf16 v[0:3], v[210:213], v[242:245], v[0:3]
	s_setprio 0
	s_barrier
; #define PG8_STAGE(bufoff, gbase, voff) do { _Pragma("unroll") for (int _i = 0; _i < 2; ++_i) \
;         __builtin_amdgcn_global_load_lds((const unsigned*)((const char*)(gbase) + (voff)[_i]), (PG8_LAS unsigned*)(lds + (bufoff) + ldsw + _i * 8192), 16, 0, 0); } while (0)
; #define PG8_LDA(dst, b, h) do { _Pragma("unroll") for (int m = 0; m < 4; ++m) _Pragma("unroll") for (int k = 0; k < 2; ++k) dst[m][k] = *(const PG8_LAS bf16x8*)(lds + PG8_SA(b, h) + aoff + m * 2048 + k * 1024); } while (0)
; #define PG8_LDB(dst, b, h) do { _Pragma("unroll") for (int n = 0; n < 2; ++n) _Pragma("unroll") for (int k = 0; k < 2; ++k) dst[n][k] = *(const PG8_LAS bf16x8*)(lds + PG8_SB(b, h) + boff + n * 2048 + k * 1024); } while (0)
; #define PG8_MMA(ai, bj, At, Bt) do { __builtin_amdgcn_s_setprio(1); _Pragma("unroll") for (int m = 0; m < 4; ++m) _Pragma("unroll") for (int n = 0; n < 2; ++n) _Pragma("unroll") for (int k = 0; k < 2; ++k) \
;         acc[ai][bj][m][n] = __builtin_amdgcn_mfma_f32_16x16x32_bf16(Bt[n][k], At[m][k], acc[ai][bj][m][n], 0, 0, 0); __builtin_amdgcn_s_setprio(0); } while (0)
; #define PG8_WAIT_V(n) asm volatile("s_waitcnt vmcnt(" #n ")" ::: "memory")
; #define PG8_WAIT_L(n) asm volatile("s_waitcnt lgkmcnt(" #n ")" ::: "memory")
; #define PG8_BAR __builtin_amdgcn_s_barrier()
; #define PG8_SCHED __builtin_amdgcn_sched_barrier(0)
; template <class Epi, class Sched, bool ALIGN_EPI = false, bool SP2 = false>
; __device__ __forceinline__ void gemm_phase(PG8_LAS unsigned char* lds, const Gemm g, const Sched& S, const Epi& E) {
;     ...
;         for (int t = 0; t < nt; t += 2) {
;     ...
;             PG8_LDB(B0, 1, 0); PG8_LDB(B1, 1, 1); PG8_SCHED; PG8_LDA(At, 1, 0); PG8_STAGE(PG8_SA(0, 1), a2 + hstep, voffA);
;             PG8_WAIT_V(8); PG8_WAIT_L(0); PG8_BAR; PG8_MMA(0, 0, At, B0); PG8_MMA(0, 1, At, B1); PG8_BAR; PG8_SCHED;
;             PG8_LDA(At, 1, 1); PG8_STAGE(PG8_SB(1, 0), b3, voffB); PG8_STAGE(PG8_SB(1, 1), b3 + hstep, voffB); PG8_STAGE(PG8_SA(1, 0), a3, voffA);
;             PG8_WAIT_V(8); PG8_WAIT_L(0); PG8_BAR; PG8_MMA(1, 0, At, B0); PG8_MMA(1, 1, At, B1); PG8_BAR; PG8_SCHED;
	s_add_u32 s4, s4, 0x40000
	s_addc_u32 s5, s5, 0
	s_mov_b32 m0, s42
	ds_read_b128 v[140:143], v254 offset:32768
	ds_read_b128 v[162:165], v254 offset:33792
	ds_read_b128 v[166:169], v254 offset:34816
	ds_read_b128 v[170:173], v254 offset:35840
	ds_read_b128 v[180:183], v254 offset:49152
	ds_read_b128 v[184:187], v254 offset:50176
	ds_read_b128 v[188:191], v254 offset:51200
	ds_read_b128 v[210:213], v254 offset:52224
	global_load_lds_dwordx4 v134, s[4:5]
	s_mov_b32 m0, s43
	ds_read_b128 v[214:217], v178 offset:32768
	ds_read_b128 v[218:221], v178 offset:33792
	ds_read_b128 v[222:225], v178 offset:34816
	ds_read_b128 v[226:229], v178 offset:35840
	ds_read_b128 v[230:233], v178 offset:36864
	ds_read_b128 v[234:237], v178 offset:37888
	ds_read_b128 v[238:241], v178 offset:38912
	ds_read_b128 v[242:245], v178 offset:39936
	global_load_lds_dwordx4 v130, s[4:5]
	s_waitcnt vmcnt(8) lgkmcnt(0)
	s_barrier
	s_setprio 1
	v_mfma_f32_16x16x32_bf16 v[124:127], v[140:143], v[214:217], v[124:127]
	v_mfma_f32_16x16x32_bf16 v[124:127], v[162:165], v[218:221], v[124:127]
	v_mfma_f32_16x16x32_bf16 v[108:111], v[140:143], v[222:225], v[108:111]
	v_mfma_f32_16x16x32_bf16 v[108:111], v[162:165], v[226:229], v[108:111]
	v_mfma_f32_16x16x32_bf16 v[92:95], v[140:143], v[230:233], v[92:95]
	v_mfma_f32_16x16x32_bf16 v[92:95], v[162:165], v[234:237], v[92:95]
	v_mfma_f32_16x16x32_bf16 v[76:79], v[140:143], v[238:241], v[76:79]
	v_mfma_f32_16x16x32_bf16 v[76:79], v[162:165], v[242:245], v[76:79]
	v_mfma_f32_16x16x32_bf16 v[120:123], v[166:169], v[214:217], v[120:123]
	v_mfma_f32_16x16x32_bf16 v[120:123], v[170:173], v[218:221], v[120:123]
	v_mfma_f32_16x16x32_bf16 v[104:107], v[166:169], v[222:225], v[104:107]
	v_mfma_f32_16x16x32_bf16 v[104:107], v[170:173], v[226:229], v[104:107]
	v_mfma_f32_16x16x32_bf16 v[88:91], v[166:169], v[230:233], v[88:91]
	v_mfma_f32_16x16x32_bf16 v[88:91], v[170:173], v[234:237], v[88:91]
	v_mfma_f32_16x16x32_bf16 v[72:75], v[166:169], v[238:241], v[72:75]
	v_mfma_f32_16x16x32_bf16 v[72:75], v[170:173], v[242:245], v[72:75]
	v_mfma_f32_16x16x32_bf16 v[116:119], v[180:183], v[214:217], v[116:119]
	v_mfma_f32_16x16x32_bf16 v[116:119], v[184:187], v[218:221], v[116:119]
	v_mfma_f32_16x16x32_bf16 v[100:103], v[180:183], v[222:225], v[100:103]
	v_mfma_f32_16x16x32_bf16 v[100:103], v[184:187], v[226:229], v[100:103]
	v_mfma_f32_16x16x32_bf16 v[84:87], v[180:183], v[230:233], v[84:87]
	v_mfma_f32_16x16x32_bf16 v[84:87], v[184:187], v[234:237], v[84:87]
	v_mfma_f32_16x16x32_bf16 v[68:71], v[180:183], v[238:241], v[68:71]
	v_mfma_f32_16x16x32_bf16 v[68:71], v[184:187], v[242:245], v[68:71]
	v_mfma_f32_16x16x32_bf16 v[112:115], v[188:191], v[214:217], v[112:115]
	v_mfma_f32_16x16x32_bf16 v[112:115], v[210:213], v[218:221], v[112:115]
	v_mfma_f32_16x16x32_bf16 v[96:99], v[188:191], v[222:225], v[96:99]
	v_mfma_f32_16x16x32_bf16 v[96:99], v[210:213], v[226:229], v[96:99]
	v_mfma_f32_16x16x32_bf16 v[80:83], v[188:191], v[230:233], v[80:83]
	v_mfma_f32_16x16x32_bf16 v[80:83], v[210:213], v[234:237], v[80:83]
	v_mfma_f32_16x16x32_bf16 v[64:67], v[188:191], v[238:241], v[64:67]
	v_mfma_f32_16x16x32_bf16 v[64:67], v[210:213], v[242:245], v[64:67]
	s_setprio 0
	s_barrier
	s_mov_b32 m0, s48
	s_add_u32 s2, s2, 0x40080
	s_addc_u32 s3, s3, 0
	s_add_u32 s98, s2, 0xfffc0000
	s_addc_u32 s99, s3, -1
	ds_read_b128 v[214:217], v178 offset:49152
	ds_read_b128 v[218:221], v178 offset:50176
	global_load_lds_dwordx4 v132, s[98:99]
	s_mov_b32 m0, s49
	ds_read_b128 v[222:225], v178 offset:51200
	ds_read_b128 v[226:229], v178 offset:52224
	global_load_lds_dwordx4 v128, s[98:99]
	s_mov_b32 m0, s52
	ds_read_b128 v[230:233], v178 offset:53248
	global_load_lds_dwordx4 v132, s[2:3]
	s_mov_b32 m0, s53
	ds_read_b128 v[234:237], v178 offset:54272
	global_load_lds_dwordx4 v128, s[2:3]
	s_mov_b32 m0, s50
	s_add_u32 s100, s4, 0xfffc0080
	s_addc_u32 s101, s5, -1
	ds_read_b128 v[238:241], v178 offset:55296
	global_load_lds_dwordx4 v134, s[100:101]
	s_mov_b32 m0, s51
	ds_read_b128 v[242:245], v178 offset:56320
	global_load_lds_dwordx4 v130, s[100:101]
	s_waitcnt vmcnt(8) lgkmcnt(0)
	s_barrier
	s_setprio 1
	v_mfma_f32_16x16x32_bf16 v[60:63], v[140:143], v[214:217], v[60:63]
	v_mfma_f32_16x16x32_bf16 v[60:63], v[162:165], v[218:221], v[60:63]
	v_mfma_f32_16x16x32_bf16 v[44:47], v[140:143], v[222:225], v[44:47]
	v_mfma_f32_16x16x32_bf16 v[44:47], v[162:165], v[226:229], v[44:47]
	v_mfma_f32_16x16x32_bf16 v[28:31], v[140:143], v[230:233], v[28:31]
	v_mfma_f32_16x16x32_bf16 v[28:31], v[162:165], v[234:237], v[28:31]
	v_mfma_f32_16x16x32_bf16 v[12:15], v[140:143], v[238:241], v[12:15]
	v_mfma_f32_16x16x32_bf16 v[12:15], v[162:165], v[242:245], v[12:15]
	v_mfma_f32_16x16x32_bf16 v[56:59], v[166:169], v[214:217], v[56:59]
	v_mfma_f32_16x16x32_bf16 v[56:59], v[170:173], v[218:221], v[56:59]
	v_mfma_f32_16x16x32_bf16 v[40:43], v[166:169], v[222:225], v[40:43]
	v_mfma_f32_16x16x32_bf16 v[40:43], v[170:173], v[226:229], v[40:43]
	v_mfma_f32_16x16x32_bf16 v[24:27], v[166:169], v[230:233], v[24:27]
	v_mfma_f32_16x16x32_bf16 v[24:27], v[170:173], v[234:237], v[24:27]
	v_mfma_f32_16x16x32_bf16 v[8:11], v[166:169], v[238:241], v[8:11]
	v_mfma_f32_16x16x32_bf16 v[8:11], v[170:173], v[242:245], v[8:11]
	v_mfma_f32_16x16x32_bf16 v[52:55], v[180:183], v[214:217], v[52:55]
	v_mfma_f32_16x16x32_bf16 v[52:55], v[184:187], v[218:221], v[52:55]
	v_mfma_f32_16x16x32_bf16 v[36:39], v[180:183], v[222:225], v[36:39]
	v_mfma_f32_16x16x32_bf16 v[36:39], v[184:187], v[226:229], v[36:39]
	v_mfma_f32_16x16x32_bf16 v[20:23], v[180:183], v[230:233], v[20:23]
	v_mfma_f32_16x16x32_bf16 v[20:23], v[184:187], v[234:237], v[20:23]
	v_mfma_f32_16x16x32_bf16 v[4:7], v[180:183], v[238:241], v[4:7]
	v_mfma_f32_16x16x32_bf16 v[4:7], v[184:187], v[242:245], v[4:7]
	v_mfma_f32_16x16x32_bf16 v[48:51], v[188:191], v[214:217], v[48:51]
	v_mfma_f32_16x16x32_bf16 v[48:51], v[210:213], v[218:221], v[48:51]
	v_mfma_f32_16x16x32_bf16 v[32:35], v[188:191], v[222:225], v[32:35]
	v_mfma_f32_16x16x32_bf16 v[32:35], v[210:213], v[226:229], v[32:35]
	v_mfma_f32_16x16x32_bf16 v[16:19], v[188:191], v[230:233], v[16:19]
	v_mfma_f32_16x16x32_bf16 v[16:19], v[210:213], v[234:237], v[16:19]
	v_mfma_f32_16x16x32_bf16 v[0:3], v[188:191], v[238:241], v[0:3]
	v_mfma_f32_16x16x32_bf16 v[0:3], v[210:213], v[242:245], v[0:3]
	s_setprio 0
	s_barrier
	s_add_i32 s55, s55, 2
	s_add_u32 s0, s0, 0x100
	s_addc_u32 s1, s1, 0
	s_add_u32 s38, s38, 0x100
	s_addc_u32 s39, s39, 0
	s_cmp_gt_u32 s55, 13
; #define PG8_STAGE(bufoff, gbase, voff) do { _Pragma("unroll") for (int _i = 0; _i < 2; ++_i) \
;         __builtin_amdgcn_global_load_lds((const unsigned*)((const char*)(gbase) + (voff)[_i]), (PG8_LAS unsigned*)(lds + (bufoff) + ldsw + _i * 8192), 16, 0, 0); } while (0)
; #define PG8_LDA(dst, b, h) do { _Pragma("unroll") for (int m = 0; m < 4; ++m) _Pragma("unroll") for (int k = 0; k < 2; ++k) dst[m][k] = *(const PG8_LAS bf16x8*)(lds + PG8_SA(b, h) + aoff + m * 2048 + k * 1024); } while (0)
; #define PG8_LDB(dst, b, h) do { _Pragma("unroll") for (int n = 0; n < 2; ++n) _Pragma("unroll") for (int k = 0; k < 2; ++k) dst[n][k] = *(const PG8_LAS bf16x8*)(lds + PG8_SB(b, h) + boff + n * 2048 + k * 1024); } while (0)
; #define PG8_MMA(ai, bj, At, Bt) do { __builtin_amdgcn_s_setprio(1); _Pragma("unroll") for (int m = 0; m < 4; ++m) _Pragma("unroll") for (int n = 0; n < 2; ++n) _Pragma("unroll") for (int k = 0; k < 2; ++k) \
;         acc[ai][bj][m][n] = __builtin_amdgcn_mfma_f32_16x16x32_bf16(Bt[n][k], At[m][k], acc[ai][bj][m][n], 0, 0, 0); __builtin_amdgcn_s_setprio(0); } while (0)
; #define PG8_WAIT_V(n) asm volatile("s_waitcnt vmcnt(" #n ")" ::: "memory")
; #define PG8_BAR __builtin_amdgcn_s_barrier()
; template <class Epi, class Sched, bool ALIGN_EPI = false, bool SP2 = false>
; __device__ __forceinline__ void gemm_phase(PG8_LAS unsigned char* lds, const Gemm g, const Sched& S, const Epi& E) {
;     ...
;         for (int t = 0; t < nt; t += 2) {
;             const bool last = (t == nt - 2);
;             const char* a1 = cA + (size_t)(t + 1) * kstep;
;             const char* a2 = last ? nA : cA + (size_t)(t + 2) * kstep; const char* b2 = last ? nB : cB + (size_t)(t + 2) * kstep;
;             const char* a3 = a2 + kstep; const char* b3 = b2 + kstep;
;             if (last && has_next) S.a_ready(nxt);
;             if constexpr (SP2) {
;             PG8_LDB(B0, 0, 0); PG8_LDB(B1, 0, 1); PG8_SCHED; PG8_LDA(At, 0, 0); PG8_STAGE(PG8_SA(1, 1), a1 + hstep, voffA);
;             PG8_WAIT_V(8); PG8_WAIT_L(0); PG8_BAR; PG8_MMA(0, 0, At, B0); PG8_MMA(0, 1, At, B1); PG8_BAR; PG8_SCHED;
;             PG8_LDA(At, 0, 1); PG8_STAGE(PG8_SB(0, 0), b2, voffB); PG8_STAGE(PG8_SB(0, 1), b2 + hstep, voffB); PG8_STAGE(PG8_SA(0, 0), a2, voffA);
;             PG8_WAIT_V(8); PG8_WAIT_L(0); PG8_BAR; PG8_MMA(1, 0, At, B0); PG8_MMA(1, 1, At, B1); PG8_BAR; PG8_SCHED;
.LBB0_749:
	s_add_u32 s2, s0, 0xfffc0080
	s_addc_u32 s3, s1, -1
	s_cmp_eq_u32 s55, 12
	s_cselect_b32 s5, s13, s3
	s_cselect_b32 s4, s25, s2
	s_cselect_b32 s3, s23, s39
	s_cselect_b32 s2, s33, s38
	s_add_i32 m0, s6, 0xc000
	ds_read_b128 v[140:143], v254
	ds_read_b128 v[162:165], v254 offset:1024
	ds_read_b128 v[166:169], v254 offset:2048
	ds_read_b128 v[170:173], v254 offset:3072
	ds_read_b128 v[180:183], v254 offset:16384
	ds_read_b128 v[184:187], v254 offset:17408
	ds_read_b128 v[188:191], v254 offset:18432
	ds_read_b128 v[210:213], v254 offset:19456
	global_load_lds_dwordx4 v136, s[0:1]
	s_add_i32 m0, s6, 0xe000
	ds_read_b128 v[214:217], v178
	ds_read_b128 v[218:221], v178 offset:1024
	ds_read_b128 v[222:225], v178 offset:2048
	ds_read_b128 v[226:229], v178 offset:3072
	ds_read_b128 v[230:233], v178 offset:4096
	ds_read_b128 v[234:237], v178 offset:5120
	ds_read_b128 v[238:241], v178 offset:6144
	ds_read_b128 v[242:245], v178 offset:7168
	global_load_lds_dwordx4 v138, s[0:1]
	s_waitcnt vmcnt(8) lgkmcnt(0)
	s_barrier
	s_setprio 1
	v_mfma_f32_16x16x32_bf16 v[124:127], v[140:143], v[214:217], v[124:127]
	v_mfma_f32_16x16x32_bf16 v[124:127], v[162:165], v[218:221], v[124:127]
	v_mfma_f32_16x16x32_bf16 v[108:111], v[140:143], v[222:225], v[108:111]
	v_mfma_f32_16x16x32_bf16 v[108:111], v[162:165], v[226:229], v[108:111]
	v_mfma_f32_16x16x32_bf16 v[92:95], v[140:143], v[230:233], v[92:95]
	v_mfma_f32_16x16x32_bf16 v[92:95], v[162:165], v[234:237], v[92:95]
	v_mfma_f32_16x16x32_bf16 v[76:79], v[140:143], v[238:241], v[76:79]
	v_mfma_f32_16x16x32_bf16 v[76:79], v[162:165], v[242:245], v[76:79]
	v_mfma_f32_16x16x32_bf16 v[120:123], v[166:169], v[214:217], v[120:123]
	v_mfma_f32_16x16x32_bf16 v[120:123], v[170:173], v[218:221], v[120:123]
	v_mfma_f32_16x16x32_bf16 v[104:107], v[166:169], v[222:225], v[104:107]
	v_mfma_f32_16x16x32_bf16 v[104:107], v[170:173], v[226:229], v[104:107]
	v_mfma_f32_16x16x32_bf16 v[88:91], v[166:169], v[230:233], v[88:91]
	v_mfma_f32_16x16x32_bf16 v[88:91], v[170:173], v[234:237], v[88:91]
	v_mfma_f32_16x16x32_bf16 v[72:75], v[166:169], v[238:241], v[72:75]
	v_mfma_f32_16x16x32_bf16 v[72:75], v[170:173], v[242:245], v[72:75]
	v_mfma_f32_16x16x32_bf16 v[116:119], v[180:183], v[214:217], v[116:119]
	v_mfma_f32_16x16x32_bf16 v[116:119], v[184:187], v[218:221], v[116:119]
	v_mfma_f32_16x16x32_bf16 v[100:103], v[180:183], v[222:225], v[100:103]
	v_mfma_f32_16x16x32_bf16 v[100:103], v[184:187], v[226:229], v[100:103]
	v_mfma_f32_16x16x32_bf16 v[84:87], v[180:183], v[230:233], v[84:87]
	v_mfma_f32_16x16x32_bf16 v[84:87], v[184:187], v[234:237], v[84:87]
	v_mfma_f32_16x16x32_bf16 v[68:71], v[180:183], v[238:241], v[68:71]
	v_mfma_f32_16x16x32_bf16 v[68:71], v[184:187], v[242:245], v[68:71]
	v_mfma_f32_16x16x32_bf16 v[112:115], v[188:191], v[214:217], v[112:115]
	v_mfma_f32_16x16x32_bf16 v[112:115], v[210:213], v[218:221], v[112:115]
	v_mfma_f32_16x16x32_bf16 v[96:99], v[188:191], v[222:225], v[96:99]
	v_mfma_f32_16x16x32_bf16 v[96:99], v[210:213], v[226:229], v[96:99]
	v_mfma_f32_16x16x32_bf16 v[80:83], v[188:191], v[230:233], v[80:83]
	v_mfma_f32_16x16x32_bf16 v[80:83], v[210:213], v[234:237], v[80:83]
	v_mfma_f32_16x16x32_bf16 v[64:67], v[188:191], v[238:241], v[64:67]
	v_mfma_f32_16x16x32_bf16 v[64:67], v[210:213], v[242:245], v[64:67]
	s_setprio 0
	s_barrier
	s_mov_b32 m0, s31
	s_add_u32 s56, s2, 0x40000
	s_addc_u32 s57, s3, 0
	ds_read_b128 v[214:217], v178 offset:16384
	ds_read_b128 v[218:221], v178 offset:17408
	global_load_lds_dwordx4 v132, s[2:3]
	s_mov_b32 m0, s34
	ds_read_b128 v[222:225], v178 offset:18432
	ds_read_b128 v[226:229], v178 offset:19456
	global_load_lds_dwordx4 v128, s[2:3]
	s_mov_b32 m0, s35
	ds_read_b128 v[230:233], v178 offset:20480
	global_load_lds_dwordx4 v132, s[56:57]
	s_mov_b32 m0, s40
	ds_read_b128 v[234:237], v178 offset:21504
	global_load_lds_dwordx4 v128, s[56:57]
	s_mov_b32 m0, s6
	ds_read_b128 v[238:241], v178 offset:22528
	global_load_lds_dwordx4 v134, s[4:5]
	s_mov_b32 m0, s41
	ds_read_b128 v[242:245], v178 offset:23552
	global_load_lds_dwordx4 v130, s[4:5]
	s_waitcnt vmcnt(8) lgkmcnt(0)
	s_barrier
	s_setprio 1
	v_mfma_f32_16x16x32_bf16 v[60:63], v[140:143], v[214:217], v[60:63]
	v_mfma_f32_16x16x32_bf16 v[60:63], v[162:165], v[218:221], v[60:63]
	v_mfma_f32_16x16x32_bf16 v[44:47], v[140:143], v[222:225], v[44:47]
	v_mfma_f32_16x16x32_bf16 v[44:47], v[162:165], v[226:229], v[44:47]
	v_mfma_f32_16x16x32_bf16 v[28:31], v[140:143], v[230:233], v[28:31]
	v_mfma_f32_16x16x32_bf16 v[28:31], v[162:165], v[234:237], v[28:31]
	v_mfma_f32_16x16x32_bf16 v[12:15], v[140:143], v[238:241], v[12:15]
	v_mfma_f32_16x16x32_bf16 v[12:15], v[162:165], v[242:245], v[12:15]
	v_mfma_f32_16x16x32_bf16 v[56:59], v[166:169], v[214:217], v[56:59]
	v_mfma_f32_16x16x32_bf16 v[56:59], v[170:173], v[218:221], v[56:59]
	v_mfma_f32_16x16x32_bf16 v[40:43], v[166:169], v[222:225], v[40:43]
	v_mfma_f32_16x16x32_bf16 v[40:43], v[170:173], v[226:229], v[40:43]
	v_mfma_f32_16x16x32_bf16 v[24:27], v[166:169], v[230:233], v[24:27]
	v_mfma_f32_16x16x32_bf16 v[24:27], v[170:173], v[234:237], v[24:27]
	v_mfma_f32_16x16x32_bf16 v[8:11], v[166:169], v[238:241], v[8:11]
	v_mfma_f32_16x16x32_bf16 v[8:11], v[170:173], v[242:245], v[8:11]
	v_mfma_f32_16x16x32_bf16 v[52:55], v[180:183], v[214:217], v[52:55]
	v_mfma_f32_16x16x32_bf16 v[52:55], v[184:187], v[218:221], v[52:55]
	v_mfma_f32_16x16x32_bf16 v[36:39], v[180:183], v[222:225], v[36:39]
	v_mfma_f32_16x16x32_bf16 v[36:39], v[184:187], v[226:229], v[36:39]
	v_mfma_f32_16x16x32_bf16 v[20:23], v[180:183], v[230:233], v[20:23]
	v_mfma_f32_16x16x32_bf16 v[20:23], v[184:187], v[234:237], v[20:23]
	v_mfma_f32_16x16x32_bf16 v[4:7], v[180:183], v[238:241], v[4:7]
	v_mfma_f32_16x16x32_bf16 v[4:7], v[184:187], v[242:245], v[4:7]
	v_mfma_f32_16x16x32_bf16 v[48:51], v[188:191], v[214:217], v[48:51]
	v_mfma_f32_16x16x32_bf16 v[48:51], v[210:213], v[218:221], v[48:51]
	v_mfma_f32_16x16x32_bf16 v[32:35], v[188:191], v[222:225], v[32:35]
	v_mfma_f32_16x16x32_bf16 v[32:35], v[210:213], v[226:229], v[32:35]
	v_mfma_f32_16x16x32_bf16 v[16:19], v[188:191], v[230:233], v[16:19]
	v_mfma_f32_16x16x32_bf16 v[16:19], v[210:213], v[234:237], v[16:19]
	v_mfma_f32_16x16x32_bf16 v[0:3], v[188:191], v[238:241], v[0:3]
	v_mfma_f32_16x16x32_bf16 v[0:3], v[210:213], v[242:245], v[0:3]
	s_setprio 0
	s_barrier
; #define PG8_STAGE(bufoff, gbase, voff) do { _Pragma("unroll") for (int _i = 0; _i < 2; ++_i) \
;         __builtin_amdgcn_global_load_lds((const unsigned*)((const char*)(gbase) + (voff)[_i]), (PG8_LAS unsigned*)(lds + (bufoff) + ldsw + _i * 8192), 16, 0, 0); } while (0)
; #define PG8_LDA(dst, b, h) do { _Pragma("unroll") for (int m = 0; m < 4; ++m) _Pragma("unroll") for (int k = 0; k < 2; ++k) dst[m][k] = *(const PG8_LAS bf16x8*)(lds + PG8_SA(b, h) + aoff + m * 2048 + k * 1024); } while (0)
; #define PG8_LDB(dst, b, h) do { _Pragma("unroll") for (int n = 0; n < 2; ++n) _Pragma("unroll") for (int k = 0; k < 2; ++k) dst[n][k] = *(const PG8_LAS bf16x8*)(lds + PG8_SB(b, h) + boff + n * 2048 + k * 1024); } while (0)
; #define PG8_MMA(ai, bj, At, Bt) do { __builtin_amdgcn_s_setprio(1); _Pragma("unroll") for (int m = 0; m < 4; ++m) _Pragma("unroll") for (int n = 0; n < 2; ++n) _Pragma("unroll") for (int k = 0; k < 2; ++k) \
;         acc[ai][bj][m][n] = __builtin_amdgcn_mfma_f32_16x16x32_bf16(Bt[n][k], At[m][k], acc[ai][bj][m][n], 0, 0, 0); __builtin_amdgcn_s_setprio(0); } while (0)
; #define PG8_WAIT_V(n) asm volatile("s_waitcnt vmcnt(" #n ")" ::: "memory")
; #define PG8_WAIT_L(n) asm volatile("s_waitcnt lgkmcnt(" #n ")" ::: "memory")
; #define PG8_BAR __builtin_amdgcn_s_barrier()
; #define PG8_SCHED __builtin_amdgcn_sched_barrier(0)
; template <class Epi, class Sched, bool ALIGN_EPI = false, bool SP2 = false>
; __device__ __forceinline__ void gemm_phase(PG8_LAS unsigned char* lds, const Gemm g, const Sched& S, const Epi& E) {
;     ...
;         for (int t = 0; t < nt; t += 2) {
;     ...
;             PG8_LDB(B0, 1, 0); PG8_LDB(B1, 1, 1); PG8_SCHED; PG8_LDA(At, 1, 0); PG8_STAGE(PG8_SA(0, 1), a2 + hstep, voffA);
;             PG8_WAIT_V(8); PG8_WAIT_L(0); PG8_BAR; PG8_MMA(0, 0, At, B0); PG8_MMA(0, 1, At, B1); PG8_BAR; PG8_SCHED;
;             PG8_LDA(At, 1, 1); PG8_STAGE(PG8_SB(1, 0), b3, voffB); PG8_STAGE(PG8_SB(1, 1), b3 + hstep, voffB); PG8_STAGE(PG8_SA(1, 0), a3, voffA);
;             PG8_WAIT_V(8); PG8_WAIT_L(0); PG8_BAR; PG8_MMA(1, 0, At, B0); PG8_MMA(1, 1, At, B1); PG8_BAR; PG8_SCHED;
	s_add_u32 s4, s4, 0x40000
	s_addc_u32 s5, s5, 0
	s_mov_b32 m0, s42
	ds_read_b128 v[140:143], v254 offset:32768
	ds_read_b128 v[162:165], v254 offset:33792
	ds_read_b128 v[166:169], v254 offset:34816
	ds_read_b128 v[170:173], v254 offset:35840
	ds_read_b128 v[180:183], v254 offset:49152
	ds_read_b128 v[184:187], v254 offset:50176
	ds_read_b128 v[188:191], v254 offset:51200
	ds_read_b128 v[210:213], v254 offset:52224
	global_load_lds_dwordx4 v134, s[4:5]
	s_mov_b32 m0, s43
	ds_read_b128 v[214:217], v178 offset:32768
	ds_read_b128 v[218:221], v178 offset:33792
	ds_read_b128 v[222:225], v178 offset:34816
	ds_read_b128 v[226:229], v178 offset:35840
	ds_read_b128 v[230:233], v178 offset:36864
	ds_read_b128 v[234:237], v178 offset:37888
	ds_read_b128 v[238:241], v178 offset:38912
	ds_read_b128 v[242:245], v178 offset:39936
	global_load_lds_dwordx4 v130, s[4:5]
	s_waitcnt vmcnt(8) lgkmcnt(0)
	s_barrier
	s_setprio 1
	v_mfma_f32_16x16x32_bf16 v[124:127], v[140:143], v[214:217], v[124:127]
	v_mfma_f32_16x16x32_bf16 v[124:127], v[162:165], v[218:221], v[124:127]
	v_mfma_f32_16x16x32_bf16 v[108:111], v[140:143], v[222:225], v[108:111]
	v_mfma_f32_16x16x32_bf16 v[108:111], v[162:165], v[226:229], v[108:111]
	v_mfma_f32_16x16x32_bf16 v[92:95], v[140:143], v[230:233], v[92:95]
	v_mfma_f32_16x16x32_bf16 v[92:95], v[162:165], v[234:237], v[92:95]
	v_mfma_f32_16x16x32_bf16 v[76:79], v[140:143], v[238:241], v[76:79]
	v_mfma_f32_16x16x32_bf16 v[76:79], v[162:165], v[242:245], v[76:79]
	v_mfma_f32_16x16x32_bf16 v[120:123], v[166:169], v[214:217], v[120:123]
	v_mfma_f32_16x16x32_bf16 v[120:123], v[170:173], v[218:221], v[120:123]
	v_mfma_f32_16x16x32_bf16 v[104:107], v[166:169], v[222:225], v[104:107]
	v_mfma_f32_16x16x32_bf16 v[104:107], v[170:173], v[226:229], v[104:107]
	v_mfma_f32_16x16x32_bf16 v[88:91], v[166:169], v[230:233], v[88:91]
	v_mfma_f32_16x16x32_bf16 v[88:91], v[170:173], v[234:237], v[88:91]
	v_mfma_f32_16x16x32_bf16 v[72:75], v[166:169], v[238:241], v[72:75]
	v_mfma_f32_16x16x32_bf16 v[72:75], v[170:173], v[242:245], v[72:75]
	v_mfma_f32_16x16x32_bf16 v[116:119], v[180:183], v[214:217], v[116:119]
	v_mfma_f32_16x16x32_bf16 v[116:119], v[184:187], v[218:221], v[116:119]
	v_mfma_f32_16x16x32_bf16 v[100:103], v[180:183], v[222:225], v[100:103]
	v_mfma_f32_16x16x32_bf16 v[100:103], v[184:187], v[226:229], v[100:103]
	v_mfma_f32_16x16x32_bf16 v[84:87], v[180:183], v[230:233], v[84:87]
	v_mfma_f32_16x16x32_bf16 v[84:87], v[184:187], v[234:237], v[84:87]
	v_mfma_f32_16x16x32_bf16 v[68:71], v[180:183], v[238:241], v[68:71]
	v_mfma_f32_16x16x32_bf16 v[68:71], v[184:187], v[242:245], v[68:71]
	v_mfma_f32_16x16x32_bf16 v[112:115], v[188:191], v[214:217], v[112:115]
	v_mfma_f32_16x16x32_bf16 v[112:115], v[210:213], v[218:221], v[112:115]
	v_mfma_f32_16x16x32_bf16 v[96:99], v[188:191], v[222:225], v[96:99]
	v_mfma_f32_16x16x32_bf16 v[96:99], v[210:213], v[226:229], v[96:99]
	v_mfma_f32_16x16x32_bf16 v[80:83], v[188:191], v[230:233], v[80:83]
	v_mfma_f32_16x16x32_bf16 v[80:83], v[210:213], v[234:237], v[80:83]
	v_mfma_f32_16x16x32_bf16 v[64:67], v[188:191], v[238:241], v[64:67]
	v_mfma_f32_16x16x32_bf16 v[64:67], v[210:213], v[242:245], v[64:67]
	s_setprio 0
	s_barrier
	s_mov_b32 m0, s48
	s_add_u32 s2, s2, 0x40080
	s_addc_u32 s3, s3, 0
	s_add_u32 s98, s2, 0xfffc0000
	s_addc_u32 s99, s3, -1
	ds_read_b128 v[214:217], v178 offset:49152
	ds_read_b128 v[218:221], v178 offset:50176
	global_load_lds_dwordx4 v132, s[98:99]
	s_mov_b32 m0, s49
	ds_read_b128 v[222:225], v178 offset:51200
	ds_read_b128 v[226:229], v178 offset:52224
	global_load_lds_dwordx4 v128, s[98:99]
	s_mov_b32 m0, s52
	ds_read_b128 v[230:233], v178 offset:53248
	global_load_lds_dwordx4 v132, s[2:3]
	s_mov_b32 m0, s53
	ds_read_b128 v[234:237], v178 offset:54272
	global_load_lds_dwordx4 v128, s[2:3]
	s_mov_b32 m0, s50
	s_add_u32 s100, s4, 0xfffc0080
	s_addc_u32 s101, s5, -1
	ds_read_b128 v[238:241], v178 offset:55296
	global_load_lds_dwordx4 v134, s[100:101]
	s_mov_b32 m0, s51
	ds_read_b128 v[242:245], v178 offset:56320
	global_load_lds_dwordx4 v130, s[100:101]
	s_waitcnt vmcnt(8) lgkmcnt(0)
	s_barrier
	s_setprio 1
	v_mfma_f32_16x16x32_bf16 v[60:63], v[140:143], v[214:217], v[60:63]
	v_mfma_f32_16x16x32_bf16 v[60:63], v[162:165], v[218:221], v[60:63]
	v_mfma_f32_16x16x32_bf16 v[44:47], v[140:143], v[222:225], v[44:47]
	v_mfma_f32_16x16x32_bf16 v[44:47], v[162:165], v[226:229], v[44:47]
	v_mfma_f32_16x16x32_bf16 v[28:31], v[140:143], v[230:233], v[28:31]
	v_mfma_f32_16x16x32_bf16 v[28:31], v[162:165], v[234:237], v[28:31]
	v_mfma_f32_16x16x32_bf16 v[12:15], v[140:143], v[238:241], v[12:15]
	v_mfma_f32_16x16x32_bf16 v[12:15], v[162:165], v[242:245], v[12:15]
	v_mfma_f32_16x16x32_bf16 v[56:59], v[166:169], v[214:217], v[56:59]
	v_mfma_f32_16x16x32_bf16 v[56:59], v[170:173], v[218:221], v[56:59]
	v_mfma_f32_16x16x32_bf16 v[40:43], v[166:169], v[222:225], v[40:43]
	v_mfma_f32_16x16x32_bf16 v[40:43], v[170:173], v[226:229], v[40:43]
	v_mfma_f32_16x16x32_bf16 v[24:27], v[166:169], v[230:233], v[24:27]
	v_mfma_f32_16x16x32_bf16 v[24:27], v[170:173], v[234:237], v[24:27]
	v_mfma_f32_16x16x32_bf16 v[8:11], v[166:169], v[238:241], v[8:11]
	v_mfma_f32_16x16x32_bf16 v[8:11], v[170:173], v[242:245], v[8:11]
	v_mfma_f32_16x16x32_bf16 v[52:55], v[180:183], v[214:217], v[52:55]
	v_mfma_f32_16x16x32_bf16 v[52:55], v[184:187], v[218:221], v[52:55]
	v_mfma_f32_16x16x32_bf16 v[36:39], v[180:183], v[222:225], v[36:39]
	v_mfma_f32_16x16x32_bf16 v[36:39], v[184:187], v[226:229], v[36:39]
	v_mfma_f32_16x16x32_bf16 v[20:23], v[180:183], v[230:233], v[20:23]
	v_mfma_f32_16x16x32_bf16 v[20:23], v[184:187], v[234:237], v[20:23]
	v_mfma_f32_16x16x32_bf16 v[4:7], v[180:183], v[238:241], v[4:7]
	v_mfma_f32_16x16x32_bf16 v[4:7], v[184:187], v[242:245], v[4:7]
	v_mfma_f32_16x16x32_bf16 v[48:51], v[188:191], v[214:217], v[48:51]
	v_mfma_f32_16x16x32_bf16 v[48:51], v[210:213], v[218:221], v[48:51]
	v_mfma_f32_16x16x32_bf16 v[32:35], v[188:191], v[222:225], v[32:35]
	v_mfma_f32_16x16x32_bf16 v[32:35], v[210:213], v[226:229], v[32:35]
	v_mfma_f32_16x16x32_bf16 v[16:19], v[188:191], v[230:233], v[16:19]
	v_mfma_f32_16x16x32_bf16 v[16:19], v[210:213], v[234:237], v[16:19]
	v_mfma_f32_16x16x32_bf16 v[0:3], v[188:191], v[238:241], v[0:3]
	v_mfma_f32_16x16x32_bf16 v[0:3], v[210:213], v[242:245], v[0:3]
	s_setprio 0
	s_barrier
	s_add_i32 s55, s55, 2
	s_add_u32 s0, s0, 0x100
	s_addc_u32 s1, s1, 0
	s_add_u32 s38, s38, 0x100
	s_addc_u32 s39, s39, 0
	s_cmp_gt_u32 s55, 13
	s_cbranch_scc0 .LBB0_749
	s_and_b64 vcc, exec, s[18:19]
	s_cbranch_vccz .LBB0_752
	s_barrier

; #define PG8_STAGE(bufoff, gbase, voff) do { _Pragma("unroll") for (int _i = 0; _i < 2; ++_i) \
;         __builtin_amdgcn_global_load_lds((const unsigned*)((const char*)(gbase) + (voff)[_i]), (PG8_LAS unsigned*)(lds + (bufoff) + ldsw + _i * 8192), 16, 0, 0); } while (0)
; #define PG8_LDA(dst, b, h) do { _Pragma("unroll") for (int m = 0; m < 4; ++m) _Pragma("unroll") for (int k = 0; k < 2; ++k) dst[m][k] = *(const PG8_LAS bf16x8*)(lds + PG8_SA(b, h) + aoff + m * 2048 + k * 1024); } while (0)
; #define PG8_LDB(dst, b, h) do { _Pragma("unroll") for (int n = 0; n < 2; ++n) _Pragma("unroll") for (int k = 0; k < 2; ++k) dst[n][k] = *(const PG8_LAS bf16x8*)(lds + PG8_SB(b, h) + boff + n * 2048 + k * 1024); } while (0)
; #define PG8_MMA(ai, bj, At, Bt) do { __builtin_amdgcn_s_setprio(1); _Pragma("unroll") for (int m = 0; m < 4; ++m) _Pragma("unroll") for (int n = 0; n < 2; ++n) _Pragma("unroll") for (int k = 0; k < 2; ++k) \
;         acc[ai][bj][m][n] = __builtin_amdgcn_mfma_f32_16x16x32_bf16(Bt[n][k], At[m][k], acc[ai][bj][m][n], 0, 0, 0); __builtin_amdgcn_s_setprio(0); } while (0)
; #define PG8_WAIT_V(n) asm volatile("s_waitcnt vmcnt(" #n ")" ::: "memory")
; #define PG8_WAIT_L(n) asm volatile("s_waitcnt lgkmcnt(" #n ")" ::: "memory")
; template <class Epi, class Sched, bool ALIGN_EPI = false, bool SP2 = false>
; __device__ __forceinline__ void gemm_phase(PG8_LAS unsigned char* lds, const Gemm g, const Sched& S, const Epi& E) {
;     ...
;             const bool last = (t == nt - 2);
;             const char* a1 = cA + (size_t)(t + 1) * kstep;
;             const char* a2 = last ? nA : cA + (size_t)(t + 2) * kstep; const char* b2 = last ? nB : cB + (size_t)(t + 2) * kstep;
;             const char* a3 = a2 + kstep; const char* b3 = b2 + kstep;
;             if (last && has_next) S.a_ready(nxt);
;             if constexpr (SP2) {
;             PG8_LDB(B0, 0, 0); PG8_LDB(B1, 0, 1); PG8_SCHED; PG8_LDA(At, 0, 0); PG8_STAGE(PG8_SA(1, 1), a1 + hstep, voffA);
;             PG8_WAIT_V(8); PG8_WAIT_L(0); PG8_BAR; PG8_MMA(0, 0, At, B0); PG8_MMA(0, 1, At, B1); PG8_BAR; PG8_SCHED;
;             PG8_LDA(At, 0, 1); PG8_STAGE(PG8_SB(0, 0), b2, voffB); PG8_STAGE(PG8_SB(0, 1), b2 + hstep, voffB); PG8_STAGE(PG8_SA(0, 0), a2, voffA);
;             PG8_WAIT_V(8); PG8_WAIT_L(0); PG8_BAR; PG8_MMA(1, 0, At, B0); PG8_MMA(1, 1, At, B1); PG8_BAR; PG8_SCHED;
.Labi_peel:
	s_waitcnt lgkmcnt(0)
	s_add_u32 s2, s0, 0xfffc0080
	s_addc_u32 s3, s1, -1
	s_cmp_eq_u32 s52, 12
	s_cselect_b32 s5, s17, s3
	s_cselect_b32 s4, s48, s2
	s_cselect_b32 s3, s15, s51
	s_cselect_b32 s2, s49, s50
	s_add_i32 m0, s6, 0xc000
	ds_read_b128 v[140:143], v254
	ds_read_b128 v[162:165], v254 offset:1024
	ds_read_b128 v[166:169], v254 offset:2048
	ds_read_b128 v[176:179], v254 offset:3072
	ds_read_b128 v[180:183], v254 offset:16384
	ds_read_b128 v[184:187], v254 offset:17408
	ds_read_b128 v[188:191], v254 offset:18432
	ds_read_b128 v[210:213], v254 offset:19456
	global_load_lds_dwordx4 v136, s[0:1]
	s_add_i32 m0, s6, 0xe000
	ds_read_b128 v[214:217], v173
	ds_read_b128 v[218:221], v173 offset:1024
	ds_read_b128 v[222:225], v173 offset:2048
	ds_read_b128 v[226:229], v173 offset:3072
	ds_read_b128 v[230:233], v173 offset:4096
	ds_read_b128 v[234:237], v173 offset:5120
	ds_read_b128 v[238:241], v173 offset:6144
	ds_read_b128 v[242:245], v173 offset:7168
	global_load_lds_dwordx4 v138, s[0:1]
	s_waitcnt vmcnt(8) lgkmcnt(0)
	s_barrier
	s_setprio 1
	v_mfma_f32_16x16x32_bf16 v[124:127], v[140:143], v[214:217], 0
	v_mfma_f32_16x16x32_bf16 v[124:127], v[162:165], v[218:221], v[124:127]
	v_mfma_f32_16x16x32_bf16 v[112:115], v[140:143], v[222:225], 0
	v_mfma_f32_16x16x32_bf16 v[112:115], v[162:165], v[226:229], v[112:115]
	v_mfma_f32_16x16x32_bf16 v[96:99], v[140:143], v[230:233], 0
	v_mfma_f32_16x16x32_bf16 v[96:99], v[162:165], v[234:237], v[96:99]
	v_mfma_f32_16x16x32_bf16 v[80:83], v[140:143], v[238:241], 0
	v_mfma_f32_16x16x32_bf16 v[80:83], v[162:165], v[242:245], v[80:83]
	v_mfma_f32_16x16x32_bf16 v[120:123], v[166:169], v[214:217], 0
	v_mfma_f32_16x16x32_bf16 v[120:123], v[176:179], v[218:221], v[120:123]
	v_mfma_f32_16x16x32_bf16 v[104:107], v[166:169], v[222:225], 0
	v_mfma_f32_16x16x32_bf16 v[104:107], v[176:179], v[226:229], v[104:107]
	v_mfma_f32_16x16x32_bf16 v[88:91], v[166:169], v[230:233], 0
	v_mfma_f32_16x16x32_bf16 v[88:91], v[176:179], v[234:237], v[88:91]
	v_mfma_f32_16x16x32_bf16 v[72:75], v[166:169], v[238:241], 0
	v_mfma_f32_16x16x32_bf16 v[72:75], v[176:179], v[242:245], v[72:75]
	v_mfma_f32_16x16x32_bf16 v[116:119], v[180:183], v[214:217], 0
	v_mfma_f32_16x16x32_bf16 v[116:119], v[184:187], v[218:221], v[116:119]
	v_mfma_f32_16x16x32_bf16 v[100:103], v[180:183], v[222:225], 0
	v_mfma_f32_16x16x32_bf16 v[100:103], v[184:187], v[226:229], v[100:103]
	v_mfma_f32_16x16x32_bf16 v[84:87], v[180:183], v[230:233], 0
	v_mfma_f32_16x16x32_bf16 v[84:87], v[184:187], v[234:237], v[84:87]
	v_mfma_f32_16x16x32_bf16 v[68:71], v[180:183], v[238:241], 0
	v_mfma_f32_16x16x32_bf16 v[68:71], v[184:187], v[242:245], v[68:71]
	v_mfma_f32_16x16x32_bf16 v[108:111], v[188:191], v[214:217], 0
	v_mfma_f32_16x16x32_bf16 v[108:111], v[210:213], v[218:221], v[108:111]
	v_mfma_f32_16x16x32_bf16 v[92:95], v[188:191], v[222:225], 0
	v_mfma_f32_16x16x32_bf16 v[92:95], v[210:213], v[226:229], v[92:95]
	v_mfma_f32_16x16x32_bf16 v[76:79], v[188:191], v[230:233], 0
	v_mfma_f32_16x16x32_bf16 v[76:79], v[210:213], v[234:237], v[76:79]
	v_mfma_f32_16x16x32_bf16 v[64:67], v[188:191], v[238:241], 0
	v_mfma_f32_16x16x32_bf16 v[64:67], v[210:213], v[242:245], v[64:67]
	s_setprio 0
	s_barrier
	s_mov_b32 m0, s27
	s_add_u32 s54, s2, 0x40000
	s_addc_u32 s55, s3, 0
	ds_read_b128 v[214:217], v173 offset:16384
	ds_read_b128 v[218:221], v173 offset:17408
	global_load_lds_dwordx4 v132, s[2:3]
	s_mov_b32 m0, s28
	ds_read_b128 v[222:225], v173 offset:18432
	ds_read_b128 v[226:229], v173 offset:19456
	global_load_lds_dwordx4 v128, s[2:3]
	s_mov_b32 m0, s29
	ds_read_b128 v[230:233], v173 offset:20480
	global_load_lds_dwordx4 v132, s[54:55]
	s_mov_b32 m0, s30
	ds_read_b128 v[234:237], v173 offset:21504
	global_load_lds_dwordx4 v128, s[54:55]
	s_mov_b32 m0, s6
	ds_read_b128 v[238:241], v173 offset:22528
	global_load_lds_dwordx4 v134, s[4:5]
	s_mov_b32 m0, s31
	ds_read_b128 v[242:245], v173 offset:23552
	global_load_lds_dwordx4 v130, s[4:5]
	s_waitcnt vmcnt(8) lgkmcnt(0)
	s_barrier
	s_setprio 1
	v_mfma_f32_16x16x32_bf16 v[60:63], v[140:143], v[214:217], 0
	v_mfma_f32_16x16x32_bf16 v[60:63], v[162:165], v[218:221], v[60:63]
	v_mfma_f32_16x16x32_bf16 v[48:51], v[140:143], v[222:225], 0
	v_mfma_f32_16x16x32_bf16 v[48:51], v[162:165], v[226:229], v[48:51]
	v_mfma_f32_16x16x32_bf16 v[32:35], v[140:143], v[230:233], 0
	v_mfma_f32_16x16x32_bf16 v[32:35], v[162:165], v[234:237], v[32:35]
	v_mfma_f32_16x16x32_bf16 v[16:19], v[140:143], v[238:241], 0
	v_mfma_f32_16x16x32_bf16 v[16:19], v[162:165], v[242:245], v[16:19]
	v_mfma_f32_16x16x32_bf16 v[56:59], v[166:169], v[214:217], 0
	v_mfma_f32_16x16x32_bf16 v[56:59], v[176:179], v[218:221], v[56:59]
	v_mfma_f32_16x16x32_bf16 v[40:43], v[166:169], v[222:225], 0
	v_mfma_f32_16x16x32_bf16 v[40:43], v[176:179], v[226:229], v[40:43]
	v_mfma_f32_16x16x32_bf16 v[24:27], v[166:169], v[230:233], 0
	v_mfma_f32_16x16x32_bf16 v[24:27], v[176:179], v[234:237], v[24:27]
	v_mfma_f32_16x16x32_bf16 v[8:11], v[166:169], v[238:241], 0
	v_mfma_f32_16x16x32_bf16 v[8:11], v[176:179], v[242:245], v[8:11]
	v_mfma_f32_16x16x32_bf16 v[52:55], v[180:183], v[214:217], 0
	v_mfma_f32_16x16x32_bf16 v[52:55], v[184:187], v[218:221], v[52:55]
	v_mfma_f32_16x16x32_bf16 v[36:39], v[180:183], v[222:225], 0
	v_mfma_f32_16x16x32_bf16 v[36:39], v[184:187], v[226:229], v[36:39]
	v_mfma_f32_16x16x32_bf16 v[20:23], v[180:183], v[230:233], 0
	v_mfma_f32_16x16x32_bf16 v[20:23], v[184:187], v[234:237], v[20:23]
	v_mfma_f32_16x16x32_bf16 v[4:7], v[180:183], v[238:241], 0
	v_mfma_f32_16x16x32_bf16 v[4:7], v[184:187], v[242:245], v[4:7]
	v_mfma_f32_16x16x32_bf16 v[44:47], v[188:191], v[214:217], 0
	v_mfma_f32_16x16x32_bf16 v[44:47], v[210:213], v[218:221], v[44:47]
	v_mfma_f32_16x16x32_bf16 v[28:31], v[188:191], v[222:225], 0
	v_mfma_f32_16x16x32_bf16 v[28:31], v[210:213], v[226:229], v[28:31]
	v_mfma_f32_16x16x32_bf16 v[12:15], v[188:191], v[230:233], 0
	v_mfma_f32_16x16x32_bf16 v[12:15], v[210:213], v[234:237], v[12:15]
	v_mfma_f32_16x16x32_bf16 v[0:3], v[188:191], v[238:241], 0
	v_mfma_f32_16x16x32_bf16 v[0:3], v[210:213], v[242:245], v[0:3]
	s_setprio 0
	s_barrier
; #define PG8_STAGE(bufoff, gbase, voff) do { _Pragma("unroll") for (int _i = 0; _i < 2; ++_i) \
;         __builtin_amdgcn_global_load_lds((const unsigned*)((const char*)(gbase) + (voff)[_i]), (PG8_LAS unsigned*)(lds + (bufoff) + ldsw + _i * 8192), 16, 0, 0); } while (0)
; #define PG8_LDA(dst, b, h) do { _Pragma("unroll") for (int m = 0; m < 4; ++m) _Pragma("unroll") for (int k = 0; k < 2; ++k) dst[m][k] = *(const PG8_LAS bf16x8*)(lds + PG8_SA(b, h) + aoff + m * 2048 + k * 1024); } while (0)
; #define PG8_LDB(dst, b, h) do { _Pragma("unroll") for (int n = 0; n < 2; ++n) _Pragma("unroll") for (int k = 0; k < 2; ++k) dst[n][k] = *(const PG8_LAS bf16x8*)(lds + PG8_SB(b, h) + boff + n * 2048 + k * 1024); } while (0)
; #define PG8_MMA(ai, bj, At, Bt) do { __builtin_amdgcn_s_setprio(1); _Pragma("unroll") for (int m = 0; m < 4; ++m) _Pragma("unroll") for (int n = 0; n < 2; ++n) _Pragma("unroll") for (int k = 0; k < 2; ++k) \
;         acc[ai][bj][m][n] = __builtin_amdgcn_mfma_f32_16x16x32_bf16(Bt[n][k], At[m][k], acc[ai][bj][m][n], 0, 0, 0); __builtin_amdgcn_s_setprio(0); } while (0)
; #define PG8_WAIT_V(n) asm volatile("s_waitcnt vmcnt(" #n ")" ::: "memory")
; #define PG8_WAIT_L(n) asm volatile("s_waitcnt lgkmcnt(" #n ")" ::: "memory")
; #define PG8_BAR __builtin_amdgcn_s_barrier()
; template <class Epi, class Sched, bool ALIGN_EPI = false, bool SP2 = false>
; __device__ __forceinline__ void gemm_phase(PG8_LAS unsigned char* lds, const Gemm g, const Sched& S, const Epi& E) {
;     ...
;         for (int t = 0; t < nt; t += 2) {
;             const bool last = (t == nt - 2);
;             const char* a1 = cA + (size_t)(t + 1) * kstep;
;             const char* a2 = last ? nA : cA + (size_t)(t + 2) * kstep; const char* b2 = last ? nB : cB + (size_t)(t + 2) * kstep;
;             const char* a3 = a2 + kstep; const char* b3 = b2 + kstep;
;     ...
;             PG8_LDB(B0, 1, 0); PG8_LDB(B1, 1, 1); PG8_SCHED; PG8_LDA(At, 1, 0); PG8_STAGE(PG8_SA(0, 1), a2 + hstep, voffA);
;             PG8_WAIT_V(8); PG8_WAIT_L(0); PG8_BAR; PG8_MMA(0, 0, At, B0); PG8_MMA(0, 1, At, B1); PG8_BAR; PG8_SCHED;
;             PG8_LDA(At, 1, 1); PG8_STAGE(PG8_SB(1, 0), b3, voffB); PG8_STAGE(PG8_SB(1, 1), b3 + hstep, voffB); PG8_STAGE(PG8_SA(1, 0), a3, voffA);
;             PG8_WAIT_V(8); PG8_WAIT_L(0); PG8_BAR; PG8_MMA(1, 0, At, B0); PG8_MMA(1, 1, At, B1); PG8_BAR; PG8_SCHED;
	s_add_u32 s4, s4, 0x40000
	s_addc_u32 s5, s5, 0
	s_mov_b32 m0, s33
	ds_read_b128 v[140:143], v254 offset:32768
	ds_read_b128 v[162:165], v254 offset:33792
	ds_read_b128 v[166:169], v254 offset:34816
	ds_read_b128 v[176:179], v254 offset:35840
	ds_read_b128 v[180:183], v254 offset:49152
	ds_read_b128 v[184:187], v254 offset:50176
	ds_read_b128 v[188:191], v254 offset:51200
	ds_read_b128 v[210:213], v254 offset:52224
	global_load_lds_dwordx4 v134, s[4:5]
	s_mov_b32 m0, s34
	ds_read_b128 v[214:217], v173 offset:32768
	ds_read_b128 v[218:221], v173 offset:33792
	ds_read_b128 v[222:225], v173 offset:34816
	ds_read_b128 v[226:229], v173 offset:35840
	ds_read_b128 v[230:233], v173 offset:36864
	ds_read_b128 v[234:237], v173 offset:37888
	ds_read_b128 v[238:241], v173 offset:38912
	ds_read_b128 v[242:245], v173 offset:39936
	global_load_lds_dwordx4 v130, s[4:5]
	s_waitcnt vmcnt(8) lgkmcnt(0)
	s_barrier
	s_setprio 1
	v_mfma_f32_16x16x32_bf16 v[124:127], v[140:143], v[214:217], v[124:127]
	v_mfma_f32_16x16x32_bf16 v[124:127], v[162:165], v[218:221], v[124:127]
	v_mfma_f32_16x16x32_bf16 v[112:115], v[140:143], v[222:225], v[112:115]
	v_mfma_f32_16x16x32_bf16 v[112:115], v[162:165], v[226:229], v[112:115]
	v_mfma_f32_16x16x32_bf16 v[96:99], v[140:143], v[230:233], v[96:99]
	v_mfma_f32_16x16x32_bf16 v[96:99], v[162:165], v[234:237], v[96:99]
	v_mfma_f32_16x16x32_bf16 v[80:83], v[140:143], v[238:241], v[80:83]
	v_mfma_f32_16x16x32_bf16 v[80:83], v[162:165], v[242:245], v[80:83]
	v_mfma_f32_16x16x32_bf16 v[120:123], v[166:169], v[214:217], v[120:123]
	v_mfma_f32_16x16x32_bf16 v[120:123], v[176:179], v[218:221], v[120:123]
	v_mfma_f32_16x16x32_bf16 v[104:107], v[166:169], v[222:225], v[104:107]
	v_mfma_f32_16x16x32_bf16 v[104:107], v[176:179], v[226:229], v[104:107]
	v_mfma_f32_16x16x32_bf16 v[88:91], v[166:169], v[230:233], v[88:91]
	v_mfma_f32_16x16x32_bf16 v[88:91], v[176:179], v[234:237], v[88:91]
	v_mfma_f32_16x16x32_bf16 v[72:75], v[166:169], v[238:241], v[72:75]
	v_mfma_f32_16x16x32_bf16 v[72:75], v[176:179], v[242:245], v[72:75]
	v_mfma_f32_16x16x32_bf16 v[116:119], v[180:183], v[214:217], v[116:119]
	v_mfma_f32_16x16x32_bf16 v[116:119], v[184:187], v[218:221], v[116:119]
	v_mfma_f32_16x16x32_bf16 v[100:103], v[180:183], v[222:225], v[100:103]
	v_mfma_f32_16x16x32_bf16 v[100:103], v[184:187], v[226:229], v[100:103]
	v_mfma_f32_16x16x32_bf16 v[84:87], v[180:183], v[230:233], v[84:87]
	v_mfma_f32_16x16x32_bf16 v[84:87], v[184:187], v[234:237], v[84:87]
	v_mfma_f32_16x16x32_bf16 v[68:71], v[180:183], v[238:241], v[68:71]
	v_mfma_f32_16x16x32_bf16 v[68:71], v[184:187], v[242:245], v[68:71]
	v_mfma_f32_16x16x32_bf16 v[108:111], v[188:191], v[214:217], v[108:111]
	v_mfma_f32_16x16x32_bf16 v[108:111], v[210:213], v[218:221], v[108:111]
	v_mfma_f32_16x16x32_bf16 v[92:95], v[188:191], v[222:225], v[92:95]
	v_mfma_f32_16x16x32_bf16 v[92:95], v[210:213], v[226:229], v[92:95]
	v_mfma_f32_16x16x32_bf16 v[76:79], v[188:191], v[230:233], v[76:79]
	v_mfma_f32_16x16x32_bf16 v[76:79], v[210:213], v[234:237], v[76:79]
	v_mfma_f32_16x16x32_bf16 v[64:67], v[188:191], v[238:241], v[64:67]
	v_mfma_f32_16x16x32_bf16 v[64:67], v[210:213], v[242:245], v[64:67]
	s_setprio 0
	s_barrier
	s_mov_b32 m0, s37
	s_add_u32 s2, s2, 0x40080
	s_addc_u32 s3, s3, 0
	s_add_u32 s98, s2, 0xfffc0000
	s_addc_u32 s99, s3, -1
	ds_read_b128 v[214:217], v173 offset:49152
	ds_read_b128 v[218:221], v173 offset:50176
	global_load_lds_dwordx4 v132, s[98:99]
	s_mov_b32 m0, s38
	ds_read_b128 v[222:225], v173 offset:51200
	ds_read_b128 v[226:229], v173 offset:52224
	global_load_lds_dwordx4 v128, s[98:99]
	s_mov_b32 m0, s41
	ds_read_b128 v[230:233], v173 offset:53248
	global_load_lds_dwordx4 v132, s[2:3]
	s_mov_b32 m0, s42
	ds_read_b128 v[234:237], v173 offset:54272
	global_load_lds_dwordx4 v128, s[2:3]
	s_mov_b32 m0, s39
	s_add_u32 s100, s4, 0xfffc0080
	s_addc_u32 s101, s5, -1
	ds_read_b128 v[238:241], v173 offset:55296
	global_load_lds_dwordx4 v134, s[100:101]
	s_mov_b32 m0, s40
	ds_read_b128 v[242:245], v173 offset:56320
	global_load_lds_dwordx4 v130, s[100:101]
	s_waitcnt vmcnt(8) lgkmcnt(0)
	s_barrier
	s_setprio 1
	v_mfma_f32_16x16x32_bf16 v[60:63], v[140:143], v[214:217], v[60:63]
	v_mfma_f32_16x16x32_bf16 v[60:63], v[162:165], v[218:221], v[60:63]
	v_mfma_f32_16x16x32_bf16 v[48:51], v[140:143], v[222:225], v[48:51]
	v_mfma_f32_16x16x32_bf16 v[48:51], v[162:165], v[226:229], v[48:51]
	v_mfma_f32_16x16x32_bf16 v[32:35], v[140:143], v[230:233], v[32:35]
	v_mfma_f32_16x16x32_bf16 v[32:35], v[162:165], v[234:237], v[32:35]
	v_mfma_f32_16x16x32_bf16 v[16:19], v[140:143], v[238:241], v[16:19]
	v_mfma_f32_16x16x32_bf16 v[16:19], v[162:165], v[242:245], v[16:19]
	v_mfma_f32_16x16x32_bf16 v[56:59], v[166:169], v[214:217], v[56:59]
	v_mfma_f32_16x16x32_bf16 v[56:59], v[176:179], v[218:221], v[56:59]
	v_mfma_f32_16x16x32_bf16 v[40:43], v[166:169], v[222:225], v[40:43]
	v_mfma_f32_16x16x32_bf16 v[40:43], v[176:179], v[226:229], v[40:43]
	v_mfma_f32_16x16x32_bf16 v[24:27], v[166:169], v[230:233], v[24:27]
	v_mfma_f32_16x16x32_bf16 v[24:27], v[176:179], v[234:237], v[24:27]
	v_mfma_f32_16x16x32_bf16 v[8:11], v[166:169], v[238:241], v[8:11]
	v_mfma_f32_16x16x32_bf16 v[8:11], v[176:179], v[242:245], v[8:11]
	v_mfma_f32_16x16x32_bf16 v[52:55], v[180:183], v[214:217], v[52:55]
	v_mfma_f32_16x16x32_bf16 v[52:55], v[184:187], v[218:221], v[52:55]
	v_mfma_f32_16x16x32_bf16 v[36:39], v[180:183], v[222:225], v[36:39]
	v_mfma_f32_16x16x32_bf16 v[36:39], v[184:187], v[226:229], v[36:39]
	v_mfma_f32_16x16x32_bf16 v[20:23], v[180:183], v[230:233], v[20:23]
	v_mfma_f32_16x16x32_bf16 v[20:23], v[184:187], v[234:237], v[20:23]
	v_mfma_f32_16x16x32_bf16 v[4:7], v[180:183], v[238:241], v[4:7]
	v_mfma_f32_16x16x32_bf16 v[4:7], v[184:187], v[242:245], v[4:7]
	v_mfma_f32_16x16x32_bf16 v[44:47], v[188:191], v[214:217], v[44:47]
	v_mfma_f32_16x16x32_bf16 v[44:47], v[210:213], v[218:221], v[44:47]
	v_mfma_f32_16x16x32_bf16 v[28:31], v[188:191], v[222:225], v[28:31]
	v_mfma_f32_16x16x32_bf16 v[28:31], v[210:213], v[226:229], v[28:31]
	v_mfma_f32_16x16x32_bf16 v[12:15], v[188:191], v[230:233], v[12:15]
	v_mfma_f32_16x16x32_bf16 v[12:15], v[210:213], v[234:237], v[12:15]
	v_mfma_f32_16x16x32_bf16 v[0:3], v[188:191], v[238:241], v[0:3]
	v_mfma_f32_16x16x32_bf16 v[0:3], v[210:213], v[242:245], v[0:3]
	s_setprio 0
	s_barrier
	s_add_i32 s52, s52, 2
	s_add_u32 s0, s0, 0x100
	s_addc_u32 s1, s1, 0
	s_add_u32 s50, s50, 0x100
	s_addc_u32 s51, s51, 0
	s_cmp_gt_u32 s52, 13
; #define PG8_STAGE(bufoff, gbase, voff) do { _Pragma("unroll") for (int _i = 0; _i < 2; ++_i) \
;         __builtin_amdgcn_global_load_lds((const unsigned*)((const char*)(gbase) + (voff)[_i]), (PG8_LAS unsigned*)(lds + (bufoff) + ldsw + _i * 8192), 16, 0, 0); } while (0)
; #define PG8_LDA(dst, b, h) do { _Pragma("unroll") for (int m = 0; m < 4; ++m) _Pragma("unroll") for (int k = 0; k < 2; ++k) dst[m][k] = *(const PG8_LAS bf16x8*)(lds + PG8_SA(b, h) + aoff + m * 2048 + k * 1024); } while (0)
; #define PG8_LDB(dst, b, h) do { _Pragma("unroll") for (int n = 0; n < 2; ++n) _Pragma("unroll") for (int k = 0; k < 2; ++k) dst[n][k] = *(const PG8_LAS bf16x8*)(lds + PG8_SB(b, h) + boff + n * 2048 + k * 1024); } while (0)
; #define PG8_MMA(ai, bj, At, Bt) do { __builtin_amdgcn_s_setprio(1); _Pragma("unroll") for (int m = 0; m < 4; ++m) _Pragma("unroll") for (int n = 0; n < 2; ++n) _Pragma("unroll") for (int k = 0; k < 2; ++k) \
;         acc[ai][bj][m][n] = __builtin_amdgcn_mfma_f32_16x16x32_bf16(Bt[n][k], At[m][k], acc[ai][bj][m][n], 0, 0, 0); __builtin_amdgcn_s_setprio(0); } while (0)
; #define PG8_WAIT_V(n) asm volatile("s_waitcnt vmcnt(" #n ")" ::: "memory")
; #define PG8_WAIT_L(n) asm volatile("s_waitcnt lgkmcnt(" #n ")" ::: "memory")
; #define PG8_BAR __builtin_amdgcn_s_barrier()
; #define PG8_SCHED __builtin_amdgcn_sched_barrier(0)
; template <class Epi, class Sched, bool ALIGN_EPI = false, bool SP2 = false>
; __device__ __forceinline__ void gemm_phase(PG8_LAS unsigned char* lds, const Gemm g, const Sched& S, const Epi& E) {
;     ...
;             const bool last = (t == nt - 2);
;             const char* a1 = cA + (size_t)(t + 1) * kstep;
;             const char* a2 = last ? nA : cA + (size_t)(t + 2) * kstep; const char* b2 = last ? nB : cB + (size_t)(t + 2) * kstep;
;             const char* a3 = a2 + kstep; const char* b3 = b2 + kstep;
;     ...
;             PG8_LDB(B0, 0, 0); PG8_LDB(B1, 0, 1); PG8_SCHED; PG8_LDA(At, 0, 0); PG8_STAGE(PG8_SA(1, 1), a1 + hstep, voffA);
;             PG8_WAIT_V(8); PG8_WAIT_L(0); PG8_BAR; PG8_MMA(0, 0, At, B0); PG8_MMA(0, 1, At, B1); PG8_BAR; PG8_SCHED;
;             PG8_LDA(At, 0, 1); PG8_STAGE(PG8_SB(0, 0), b2, voffB); PG8_STAGE(PG8_SB(0, 1), b2 + hstep, voffB); PG8_STAGE(PG8_SA(0, 0), a2, voffA);
;             PG8_WAIT_V(8); PG8_WAIT_L(0); PG8_BAR; PG8_MMA(1, 0, At, B0); PG8_MMA(1, 1, At, B1); PG8_BAR; PG8_SCHED;
.LBB0_792:
	s_waitcnt lgkmcnt(0)
	s_add_u32 s2, s0, 0xfffc0080
	s_addc_u32 s3, s1, -1
	s_cmp_eq_u32 s52, 12
	s_cselect_b32 s5, s17, s3
	s_cselect_b32 s4, s48, s2
	s_cselect_b32 s3, s15, s51
	s_cselect_b32 s2, s49, s50
	s_add_i32 m0, s6, 0xc000
	ds_read_b128 v[140:143], v254
	ds_read_b128 v[162:165], v254 offset:1024
	ds_read_b128 v[166:169], v254 offset:2048
	ds_read_b128 v[176:179], v254 offset:3072
	ds_read_b128 v[180:183], v254 offset:16384
	ds_read_b128 v[184:187], v254 offset:17408
	ds_read_b128 v[188:191], v254 offset:18432
	ds_read_b128 v[210:213], v254 offset:19456
	global_load_lds_dwordx4 v136, s[0:1]
	s_add_i32 m0, s6, 0xe000
	ds_read_b128 v[214:217], v173
	ds_read_b128 v[218:221], v173 offset:1024
	ds_read_b128 v[222:225], v173 offset:2048
	ds_read_b128 v[226:229], v173 offset:3072
	ds_read_b128 v[230:233], v173 offset:4096
	ds_read_b128 v[234:237], v173 offset:5120
	ds_read_b128 v[238:241], v173 offset:6144
	ds_read_b128 v[242:245], v173 offset:7168
	global_load_lds_dwordx4 v138, s[0:1]
	s_waitcnt vmcnt(8) lgkmcnt(0)
	s_barrier
	s_setprio 1
	v_mfma_f32_16x16x32_bf16 v[124:127], v[140:143], v[214:217], v[124:127]
	v_mfma_f32_16x16x32_bf16 v[124:127], v[162:165], v[218:221], v[124:127]
	v_mfma_f32_16x16x32_bf16 v[112:115], v[140:143], v[222:225], v[112:115]
	v_mfma_f32_16x16x32_bf16 v[112:115], v[162:165], v[226:229], v[112:115]
	v_mfma_f32_16x16x32_bf16 v[96:99], v[140:143], v[230:233], v[96:99]
	v_mfma_f32_16x16x32_bf16 v[96:99], v[162:165], v[234:237], v[96:99]
	v_mfma_f32_16x16x32_bf16 v[80:83], v[140:143], v[238:241], v[80:83]
	v_mfma_f32_16x16x32_bf16 v[80:83], v[162:165], v[242:245], v[80:83]
	v_mfma_f32_16x16x32_bf16 v[120:123], v[166:169], v[214:217], v[120:123]
	v_mfma_f32_16x16x32_bf16 v[120:123], v[176:179], v[218:221], v[120:123]
	v_mfma_f32_16x16x32_bf16 v[104:107], v[166:169], v[222:225], v[104:107]
	v_mfma_f32_16x16x32_bf16 v[104:107], v[176:179], v[226:229], v[104:107]
	v_mfma_f32_16x16x32_bf16 v[88:91], v[166:169], v[230:233], v[88:91]
	v_mfma_f32_16x16x32_bf16 v[88:91], v[176:179], v[234:237], v[88:91]
	v_mfma_f32_16x16x32_bf16 v[72:75], v[166:169], v[238:241], v[72:75]
	v_mfma_f32_16x16x32_bf16 v[72:75], v[176:179], v[242:245], v[72:75]
	v_mfma_f32_16x16x32_bf16 v[116:119], v[180:183], v[214:217], v[116:119]
	v_mfma_f32_16x16x32_bf16 v[116:119], v[184:187], v[218:221], v[116:119]
	v_mfma_f32_16x16x32_bf16 v[100:103], v[180:183], v[222:225], v[100:103]
	v_mfma_f32_16x16x32_bf16 v[100:103], v[184:187], v[226:229], v[100:103]
	v_mfma_f32_16x16x32_bf16 v[84:87], v[180:183], v[230:233], v[84:87]
	v_mfma_f32_16x16x32_bf16 v[84:87], v[184:187], v[234:237], v[84:87]
	v_mfma_f32_16x16x32_bf16 v[68:71], v[180:183], v[238:241], v[68:71]
	v_mfma_f32_16x16x32_bf16 v[68:71], v[184:187], v[242:245], v[68:71]
	v_mfma_f32_16x16x32_bf16 v[108:111], v[188:191], v[214:217], v[108:111]
	v_mfma_f32_16x16x32_bf16 v[108:111], v[210:213], v[218:221], v[108:111]
	v_mfma_f32_16x16x32_bf16 v[92:95], v[188:191], v[222:225], v[92:95]
	v_mfma_f32_16x16x32_bf16 v[92:95], v[210:213], v[226:229], v[92:95]
	v_mfma_f32_16x16x32_bf16 v[76:79], v[188:191], v[230:233], v[76:79]
	v_mfma_f32_16x16x32_bf16 v[76:79], v[210:213], v[234:237], v[76:79]
	v_mfma_f32_16x16x32_bf16 v[64:67], v[188:191], v[238:241], v[64:67]
	v_mfma_f32_16x16x32_bf16 v[64:67], v[210:213], v[242:245], v[64:67]
	s_setprio 0
	s_barrier
	s_mov_b32 m0, s27
	s_add_u32 s54, s2, 0x40000
	s_addc_u32 s55, s3, 0
	ds_read_b128 v[214:217], v173 offset:16384
	ds_read_b128 v[218:221], v173 offset:17408
	global_load_lds_dwordx4 v132, s[2:3]
	s_mov_b32 m0, s28
	ds_read_b128 v[222:225], v173 offset:18432
	ds_read_b128 v[226:229], v173 offset:19456
	global_load_lds_dwordx4 v128, s[2:3]
	s_mov_b32 m0, s29
	ds_read_b128 v[230:233], v173 offset:20480
	global_load_lds_dwordx4 v132, s[54:55]
	s_mov_b32 m0, s30
	ds_read_b128 v[234:237], v173 offset:21504
	global_load_lds_dwordx4 v128, s[54:55]
	s_mov_b32 m0, s6
	ds_read_b128 v[238:241], v173 offset:22528
	global_load_lds_dwordx4 v134, s[4:5]
	s_mov_b32 m0, s31
	ds_read_b128 v[242:245], v173 offset:23552
	global_load_lds_dwordx4 v130, s[4:5]
	s_waitcnt vmcnt(8) lgkmcnt(0)
	s_barrier
	s_setprio 1
	v_mfma_f32_16x16x32_bf16 v[60:63], v[140:143], v[214:217], v[60:63]
	v_mfma_f32_16x16x32_bf16 v[60:63], v[162:165], v[218:221], v[60:63]
	v_mfma_f32_16x16x32_bf16 v[48:51], v[140:143], v[222:225], v[48:51]
	v_mfma_f32_16x16x32_bf16 v[48:51], v[162:165], v[226:229], v[48:51]
	v_mfma_f32_16x16x32_bf16 v[32:35], v[140:143], v[230:233], v[32:35]
	v_mfma_f32_16x16x32_bf16 v[32:35], v[162:165], v[234:237], v[32:35]
	v_mfma_f32_16x16x32_bf16 v[16:19], v[140:143], v[238:241], v[16:19]
	v_mfma_f32_16x16x32_bf16 v[16:19], v[162:165], v[242:245], v[16:19]
	v_mfma_f32_16x16x32_bf16 v[56:59], v[166:169], v[214:217], v[56:59]
	v_mfma_f32_16x16x32_bf16 v[56:59], v[176:179], v[218:221], v[56:59]
	v_mfma_f32_16x16x32_bf16 v[40:43], v[166:169], v[222:225], v[40:43]
	v_mfma_f32_16x16x32_bf16 v[40:43], v[176:179], v[226:229], v[40:43]
	v_mfma_f32_16x16x32_bf16 v[24:27], v[166:169], v[230:233], v[24:27]
	v_mfma_f32_16x16x32_bf16 v[24:27], v[176:179], v[234:237], v[24:27]
	v_mfma_f32_16x16x32_bf16 v[8:11], v[166:169], v[238:241], v[8:11]
	v_mfma_f32_16x16x32_bf16 v[8:11], v[176:179], v[242:245], v[8:11]
	v_mfma_f32_16x16x32_bf16 v[52:55], v[180:183], v[214:217], v[52:55]
	v_mfma_f32_16x16x32_bf16 v[52:55], v[184:187], v[218:221], v[52:55]
	v_mfma_f32_16x16x32_bf16 v[36:39], v[180:183], v[222:225], v[36:39]
	v_mfma_f32_16x16x32_bf16 v[36:39], v[184:187], v[226:229], v[36:39]
	v_mfma_f32_16x16x32_bf16 v[20:23], v[180:183], v[230:233], v[20:23]
	v_mfma_f32_16x16x32_bf16 v[20:23], v[184:187], v[234:237], v[20:23]
	v_mfma_f32_16x16x32_bf16 v[4:7], v[180:183], v[238:241], v[4:7]
	v_mfma_f32_16x16x32_bf16 v[4:7], v[184:187], v[242:245], v[4:7]
	v_mfma_f32_16x16x32_bf16 v[44:47], v[188:191], v[214:217], v[44:47]
	v_mfma_f32_16x16x32_bf16 v[44:47], v[210:213], v[218:221], v[44:47]
	v_mfma_f32_16x16x32_bf16 v[28:31], v[188:191], v[222:225], v[28:31]
	v_mfma_f32_16x16x32_bf16 v[28:31], v[210:213], v[226:229], v[28:31]
	v_mfma_f32_16x16x32_bf16 v[12:15], v[188:191], v[230:233], v[12:15]
	v_mfma_f32_16x16x32_bf16 v[12:15], v[210:213], v[234:237], v[12:15]
	v_mfma_f32_16x16x32_bf16 v[0:3], v[188:191], v[238:241], v[0:3]
	v_mfma_f32_16x16x32_bf16 v[0:3], v[210:213], v[242:245], v[0:3]
	s_setprio 0
	s_barrier
; #define PG8_STAGE(bufoff, gbase, voff) do { _Pragma("unroll") for (int _i = 0; _i < 2; ++_i) \
;         __builtin_amdgcn_global_load_lds((const unsigned*)((const char*)(gbase) + (voff)[_i]), (PG8_LAS unsigned*)(lds + (bufoff) + ldsw + _i * 8192), 16, 0, 0); } while (0)
; #define PG8_LDA(dst, b, h) do { _Pragma("unroll") for (int m = 0; m < 4; ++m) _Pragma("unroll") for (int k = 0; k < 2; ++k) dst[m][k] = *(const PG8_LAS bf16x8*)(lds + PG8_SA(b, h) + aoff + m * 2048 + k * 1024); } while (0)
; #define PG8_LDB(dst, b, h) do { _Pragma("unroll") for (int n = 0; n < 2; ++n) _Pragma("unroll") for (int k = 0; k < 2; ++k) dst[n][k] = *(const PG8_LAS bf16x8*)(lds + PG8_SB(b, h) + boff + n * 2048 + k * 1024); } while (0)
; #define PG8_MMA(ai, bj, At, Bt) do { __builtin_amdgcn_s_setprio(1); _Pragma("unroll") for (int m = 0; m < 4; ++m) _Pragma("unroll") for (int n = 0; n < 2; ++n) _Pragma("unroll") for (int k = 0; k < 2; ++k) \
;         acc[ai][bj][m][n] = __builtin_amdgcn_mfma_f32_16x16x32_bf16(Bt[n][k], At[m][k], acc[ai][bj][m][n], 0, 0, 0); __builtin_amdgcn_s_setprio(0); } while (0)
; #define PG8_WAIT_V(n) asm volatile("s_waitcnt vmcnt(" #n ")" ::: "memory")
; #define PG8_WAIT_L(n) asm volatile("s_waitcnt lgkmcnt(" #n ")" ::: "memory")
; #define PG8_BAR __builtin_amdgcn_s_barrier()
; #define PG8_SCHED __builtin_amdgcn_sched_barrier(0)
; template <class Epi, class Sched, bool ALIGN_EPI = false, bool SP2 = false>
; __device__ __forceinline__ void gemm_phase(PG8_LAS unsigned char* lds, const Gemm g, const Sched& S, const Epi& E) {
;     ...
;         for (int t = 0; t < nt; t += 2) {
;     ...
;             PG8_LDB(B0, 1, 0); PG8_LDB(B1, 1, 1); PG8_SCHED; PG8_LDA(At, 1, 0); PG8_STAGE(PG8_SA(0, 1), a2 + hstep, voffA);
;             PG8_WAIT_V(8); PG8_WAIT_L(0); PG8_BAR; PG8_MMA(0, 0, At, B0); PG8_MMA(0, 1, At, B1); PG8_BAR; PG8_SCHED;
;             PG8_LDA(At, 1, 1); PG8_STAGE(PG8_SB(1, 0), b3, voffB); PG8_STAGE(PG8_SB(1, 1), b3 + hstep, voffB); PG8_STAGE(PG8_SA(1, 0), a3, voffA);
;             PG8_WAIT_V(8); PG8_WAIT_L(0); PG8_BAR; PG8_MMA(1, 0, At, B0); PG8_MMA(1, 1, At, B1); PG8_BAR; PG8_SCHED;
;     ...
;         if constexpr (ALIGN_EPI) { if (wr == 0) PG8_BAR; }
	s_add_u32 s4, s4, 0x40000
	s_addc_u32 s5, s5, 0
	s_mov_b32 m0, s33
	ds_read_b128 v[140:143], v254 offset:32768
	ds_read_b128 v[162:165], v254 offset:33792
	ds_read_b128 v[166:169], v254 offset:34816
	ds_read_b128 v[176:179], v254 offset:35840
	ds_read_b128 v[180:183], v254 offset:49152
	ds_read_b128 v[184:187], v254 offset:50176
	ds_read_b128 v[188:191], v254 offset:51200
	ds_read_b128 v[210:213], v254 offset:52224
	global_load_lds_dwordx4 v134, s[4:5]
	s_mov_b32 m0, s34
	ds_read_b128 v[214:217], v173 offset:32768
	ds_read_b128 v[218:221], v173 offset:33792
	ds_read_b128 v[222:225], v173 offset:34816
	ds_read_b128 v[226:229], v173 offset:35840
	ds_read_b128 v[230:233], v173 offset:36864
	ds_read_b128 v[234:237], v173 offset:37888
	ds_read_b128 v[238:241], v173 offset:38912
	ds_read_b128 v[242:245], v173 offset:39936
	global_load_lds_dwordx4 v130, s[4:5]
	s_waitcnt vmcnt(8) lgkmcnt(0)
	s_barrier
	s_setprio 1
	v_mfma_f32_16x16x32_bf16 v[124:127], v[140:143], v[214:217], v[124:127]
	v_mfma_f32_16x16x32_bf16 v[124:127], v[162:165], v[218:221], v[124:127]
	v_mfma_f32_16x16x32_bf16 v[112:115], v[140:143], v[222:225], v[112:115]
	v_mfma_f32_16x16x32_bf16 v[112:115], v[162:165], v[226:229], v[112:115]
	v_mfma_f32_16x16x32_bf16 v[96:99], v[140:143], v[230:233], v[96:99]
	v_mfma_f32_16x16x32_bf16 v[96:99], v[162:165], v[234:237], v[96:99]
	v_mfma_f32_16x16x32_bf16 v[80:83], v[140:143], v[238:241], v[80:83]
	v_mfma_f32_16x16x32_bf16 v[80:83], v[162:165], v[242:245], v[80:83]
	v_mfma_f32_16x16x32_bf16 v[120:123], v[166:169], v[214:217], v[120:123]
	v_mfma_f32_16x16x32_bf16 v[120:123], v[176:179], v[218:221], v[120:123]
	v_mfma_f32_16x16x32_bf16 v[104:107], v[166:169], v[222:225], v[104:107]
	v_mfma_f32_16x16x32_bf16 v[104:107], v[176:179], v[226:229], v[104:107]
	v_mfma_f32_16x16x32_bf16 v[88:91], v[166:169], v[230:233], v[88:91]
	v_mfma_f32_16x16x32_bf16 v[88:91], v[176:179], v[234:237], v[88:91]
	v_mfma_f32_16x16x32_bf16 v[72:75], v[166:169], v[238:241], v[72:75]
	v_mfma_f32_16x16x32_bf16 v[72:75], v[176:179], v[242:245], v[72:75]
	v_mfma_f32_16x16x32_bf16 v[116:119], v[180:183], v[214:217], v[116:119]
	v_mfma_f32_16x16x32_bf16 v[116:119], v[184:187], v[218:221], v[116:119]
	v_mfma_f32_16x16x32_bf16 v[100:103], v[180:183], v[222:225], v[100:103]
	v_mfma_f32_16x16x32_bf16 v[100:103], v[184:187], v[226:229], v[100:103]
	v_mfma_f32_16x16x32_bf16 v[84:87], v[180:183], v[230:233], v[84:87]
	v_mfma_f32_16x16x32_bf16 v[84:87], v[184:187], v[234:237], v[84:87]
	v_mfma_f32_16x16x32_bf16 v[68:71], v[180:183], v[238:241], v[68:71]
	v_mfma_f32_16x16x32_bf16 v[68:71], v[184:187], v[242:245], v[68:71]
	v_mfma_f32_16x16x32_bf16 v[108:111], v[188:191], v[214:217], v[108:111]
	v_mfma_f32_16x16x32_bf16 v[108:111], v[210:213], v[218:221], v[108:111]
	v_mfma_f32_16x16x32_bf16 v[92:95], v[188:191], v[222:225], v[92:95]
	v_mfma_f32_16x16x32_bf16 v[92:95], v[210:213], v[226:229], v[92:95]
	v_mfma_f32_16x16x32_bf16 v[76:79], v[188:191], v[230:233], v[76:79]
	v_mfma_f32_16x16x32_bf16 v[76:79], v[210:213], v[234:237], v[76:79]
	v_mfma_f32_16x16x32_bf16 v[64:67], v[188:191], v[238:241], v[64:67]
	v_mfma_f32_16x16x32_bf16 v[64:67], v[210:213], v[242:245], v[64:67]
	s_setprio 0
	s_barrier
	s_mov_b32 m0, s37
	s_add_u32 s2, s2, 0x40080
	s_addc_u32 s3, s3, 0
	s_add_u32 s98, s2, 0xfffc0000
	s_addc_u32 s99, s3, -1
	ds_read_b128 v[214:217], v173 offset:49152
	ds_read_b128 v[218:221], v173 offset:50176
	global_load_lds_dwordx4 v132, s[98:99]
	s_mov_b32 m0, s38
	ds_read_b128 v[222:225], v173 offset:51200
	ds_read_b128 v[226:229], v173 offset:52224
	global_load_lds_dwordx4 v128, s[98:99]
	s_mov_b32 m0, s41
	ds_read_b128 v[230:233], v173 offset:53248
	global_load_lds_dwordx4 v132, s[2:3]
	s_mov_b32 m0, s42
	ds_read_b128 v[234:237], v173 offset:54272
	global_load_lds_dwordx4 v128, s[2:3]
	s_mov_b32 m0, s39
	s_add_u32 s100, s4, 0xfffc0080
	s_addc_u32 s101, s5, -1
	ds_read_b128 v[238:241], v173 offset:55296
	global_load_lds_dwordx4 v134, s[100:101]
	s_mov_b32 m0, s40
	ds_read_b128 v[242:245], v173 offset:56320
	global_load_lds_dwordx4 v130, s[100:101]
	s_waitcnt vmcnt(8) lgkmcnt(0)
	s_barrier
	s_setprio 1
	v_mfma_f32_16x16x32_bf16 v[60:63], v[140:143], v[214:217], v[60:63]
	v_mfma_f32_16x16x32_bf16 v[60:63], v[162:165], v[218:221], v[60:63]
	v_mfma_f32_16x16x32_bf16 v[48:51], v[140:143], v[222:225], v[48:51]
	v_mfma_f32_16x16x32_bf16 v[48:51], v[162:165], v[226:229], v[48:51]
	v_mfma_f32_16x16x32_bf16 v[32:35], v[140:143], v[230:233], v[32:35]
	v_mfma_f32_16x16x32_bf16 v[32:35], v[162:165], v[234:237], v[32:35]
	v_mfma_f32_16x16x32_bf16 v[16:19], v[140:143], v[238:241], v[16:19]
	v_mfma_f32_16x16x32_bf16 v[16:19], v[162:165], v[242:245], v[16:19]
	v_mfma_f32_16x16x32_bf16 v[56:59], v[166:169], v[214:217], v[56:59]
	v_mfma_f32_16x16x32_bf16 v[56:59], v[176:179], v[218:221], v[56:59]
	v_mfma_f32_16x16x32_bf16 v[40:43], v[166:169], v[222:225], v[40:43]
	v_mfma_f32_16x16x32_bf16 v[40:43], v[176:179], v[226:229], v[40:43]
	v_mfma_f32_16x16x32_bf16 v[24:27], v[166:169], v[230:233], v[24:27]
	v_mfma_f32_16x16x32_bf16 v[24:27], v[176:179], v[234:237], v[24:27]
	v_mfma_f32_16x16x32_bf16 v[8:11], v[166:169], v[238:241], v[8:11]
	v_mfma_f32_16x16x32_bf16 v[8:11], v[176:179], v[242:245], v[8:11]
	v_mfma_f32_16x16x32_bf16 v[52:55], v[180:183], v[214:217], v[52:55]
	v_mfma_f32_16x16x32_bf16 v[52:55], v[184:187], v[218:221], v[52:55]
	v_mfma_f32_16x16x32_bf16 v[36:39], v[180:183], v[222:225], v[36:39]
	v_mfma_f32_16x16x32_bf16 v[36:39], v[184:187], v[226:229], v[36:39]
	v_mfma_f32_16x16x32_bf16 v[20:23], v[180:183], v[230:233], v[20:23]
	v_mfma_f32_16x16x32_bf16 v[20:23], v[184:187], v[234:237], v[20:23]
	v_mfma_f32_16x16x32_bf16 v[4:7], v[180:183], v[238:241], v[4:7]
	v_mfma_f32_16x16x32_bf16 v[4:7], v[184:187], v[242:245], v[4:7]
	v_mfma_f32_16x16x32_bf16 v[44:47], v[188:191], v[214:217], v[44:47]
	v_mfma_f32_16x16x32_bf16 v[44:47], v[210:213], v[218:221], v[44:47]
	v_mfma_f32_16x16x32_bf16 v[28:31], v[188:191], v[222:225], v[28:31]
	v_mfma_f32_16x16x32_bf16 v[28:31], v[210:213], v[226:229], v[28:31]
	v_mfma_f32_16x16x32_bf16 v[12:15], v[188:191], v[230:233], v[12:15]
	v_mfma_f32_16x16x32_bf16 v[12:15], v[210:213], v[234:237], v[12:15]
	v_mfma_f32_16x16x32_bf16 v[0:3], v[188:191], v[238:241], v[0:3]
	v_mfma_f32_16x16x32_bf16 v[0:3], v[210:213], v[242:245], v[0:3]
	s_setprio 0
	s_barrier
	s_add_i32 s52, s52, 2
	s_add_u32 s0, s0, 0x100
	s_addc_u32 s1, s1, 0
	s_add_u32 s50, s50, 0x100
	s_addc_u32 s51, s51, 0
	s_cmp_gt_u32 s52, 13
	s_cbranch_scc0 .LBB0_792
	s_and_b64 vcc, exec, s[12:13]
	s_cbranch_vccz .LBB0_795
	s_barrier

; #define PG8_STAGE(bufoff, gbase, voff) do { _Pragma("unroll") for (int _i = 0; _i < 2; ++_i) \
;         __builtin_amdgcn_global_load_lds((const unsigned*)((const char*)(gbase) + (voff)[_i]), (PG8_LAS unsigned*)(lds + (bufoff) + ldsw + _i * 8192), 16, 0, 0); } while (0)
; #define PG8_LDA(dst, b, h) do { _Pragma("unroll") for (int m = 0; m < 4; ++m) _Pragma("unroll") for (int k = 0; k < 2; ++k) dst[m][k] = *(const PG8_LAS bf16x8*)(lds + PG8_SA(b, h) + aoff + m * 2048 + k * 1024); } while (0)
; #define PG8_LDB(dst, b, h) do { _Pragma("unroll") for (int n = 0; n < 2; ++n) _Pragma("unroll") for (int k = 0; k < 2; ++k) dst[n][k] = *(const PG8_LAS bf16x8*)(lds + PG8_SB(b, h) + boff + n * 2048 + k * 1024); } while (0)
; #define PG8_WAIT_V(n) asm volatile("s_waitcnt vmcnt(" #n ")" ::: "memory")
; #define PG8_WAIT_L(n) asm volatile("s_waitcnt lgkmcnt(" #n ")" ::: "memory")
; #define PG8_BAR __builtin_amdgcn_s_barrier()
; #define PG8_SCHED __builtin_amdgcn_sched_barrier(0)
; #define ARGS() ({ CArgs* p_ = ap; asm volatile("" : "+s"(p_)); p_; })
; template <class Epi, class Sched, bool ALIGN_EPI = false, bool SP2 = false>
; __device__ __forceinline__ void gemm_phase(PG8_LAS unsigned char* lds, const Gemm g, const Sched& S, const Epi& E) {
;     ...
;             PG8_LDB(B0, 0, 0); PG8_LDB(B1, 0, 1); PG8_SCHED; PG8_LDA(At, 0, 0); PG8_STAGE(PG8_SA(1, 1), a1 + hstep, voffA);
;             PG8_WAIT_V(8); PG8_WAIT_L(0); PG8_BAR; PG8_MMA(0, 0, At, B0); PG8_MMA(0, 1, At, B1); PG8_BAR; PG8_SCHED;
;             PG8_LDA(At, 0, 1); PG8_STAGE(PG8_SB(0, 0), b2, voffB); PG8_STAGE(PG8_SB(0, 1), b2 + hstep, voffB); PG8_STAGE(PG8_SA(0, 0), a2, voffA);
;             PG8_WAIT_V(8); PG8_WAIT_L(0); PG8_BAR; PG8_MMA(1, 0, At, B0); PG8_MMA(1, 1, At, B1); PG8_BAR; PG8_SCHED;
; __global__ void __launch_bounds__(NTHR) mk_fwd(Args args) {
;     ...
;             if (IN_PH()) { CArgs* A_ = ARGS(); unsigned char* ws = A_->ws + A_->ws_off; bf16* XB = (bf16*)(ws + WS_XB); bf16* H = (bf16*)(ws + WS_H); float* SSP = (float*)(ws + WS_SSP); (void)XB; (void)H; (void)SSP;
;             pg8::Gemm g{(const bf16*)(ws + WS_A3), (const bf16*)(ws + WS_WSGO), M, D, D}; pg8::StaticOrder S; S.init(M, D, G, (int)blockIdx.x);
;                 pg8::EpiResid<false> E{nullptr, nullptr, XB, SSP, nullptr, 1.0f};
;                 pg8::gemm_phase<pg8::EpiResid<false>, pg8::StaticOrder, true, true>(lds, g, S, E); }
.Lsgo_peel:
	s_add_u32 s2, s0, 0xfffc0080
	s_addc_u32 s3, s1, -1
	s_cmp_eq_u32 s55, 12
	s_cselect_b32 s5, s23, s3
	s_cselect_b32 s4, s51, s2
	s_cselect_b32 s3, s21, s54
	s_cselect_b32 s2, s52, s53
	s_add_i32 m0, s31, 0xc000
	ds_read_b128 v[140:143], v254
	ds_read_b128 v[166:169], v254 offset:1024
	ds_read_b128 v[170:173], v254 offset:2048
	ds_read_b128 v[174:177], v254 offset:3072
	ds_read_b128 v[178:181], v254 offset:16384
	ds_read_b128 v[182:185], v254 offset:17408
	ds_read_b128 v[186:189], v254 offset:18432
	ds_read_b128 v[210:213], v254 offset:19456
	global_load_lds_dwordx4 v136, s[0:1]
	s_add_i32 m0, s31, 0xe000
	ds_read_b128 v[214:217], v163
	ds_read_b128 v[218:221], v163 offset:1024
	ds_read_b128 v[222:225], v163 offset:2048
	ds_read_b128 v[226:229], v163 offset:3072
	ds_read_b128 v[230:233], v163 offset:4096
	ds_read_b128 v[234:237], v163 offset:5120
	ds_read_b128 v[238:241], v163 offset:6144
	ds_read_b128 v[242:245], v163 offset:7168
	global_load_lds_dwordx4 v138, s[0:1]
	s_waitcnt vmcnt(8) lgkmcnt(0)
	s_barrier
	s_setprio 1
	v_mfma_f32_16x16x32_bf16 v[124:127], v[140:143], v[214:217], 0
	v_mfma_f32_16x16x32_bf16 v[124:127], v[166:169], v[218:221], v[124:127]
	v_mfma_f32_16x16x32_bf16 v[108:111], v[140:143], v[222:225], 0
	v_mfma_f32_16x16x32_bf16 v[108:111], v[166:169], v[226:229], v[108:111]
	v_mfma_f32_16x16x32_bf16 v[92:95], v[140:143], v[230:233], 0
	v_mfma_f32_16x16x32_bf16 v[92:95], v[166:169], v[234:237], v[92:95]
	v_mfma_f32_16x16x32_bf16 v[76:79], v[140:143], v[238:241], 0
	v_mfma_f32_16x16x32_bf16 v[76:79], v[166:169], v[242:245], v[76:79]
	v_mfma_f32_16x16x32_bf16 v[120:123], v[170:173], v[214:217], 0
	v_mfma_f32_16x16x32_bf16 v[120:123], v[174:177], v[218:221], v[120:123]
	v_mfma_f32_16x16x32_bf16 v[104:107], v[170:173], v[222:225], 0
	v_mfma_f32_16x16x32_bf16 v[104:107], v[174:177], v[226:229], v[104:107]
	v_mfma_f32_16x16x32_bf16 v[88:91], v[170:173], v[230:233], 0
	v_mfma_f32_16x16x32_bf16 v[88:91], v[174:177], v[234:237], v[88:91]
	v_mfma_f32_16x16x32_bf16 v[72:75], v[170:173], v[238:241], 0
	v_mfma_f32_16x16x32_bf16 v[72:75], v[174:177], v[242:245], v[72:75]
	v_mfma_f32_16x16x32_bf16 v[116:119], v[178:181], v[214:217], 0
	v_mfma_f32_16x16x32_bf16 v[116:119], v[182:185], v[218:221], v[116:119]
	v_mfma_f32_16x16x32_bf16 v[100:103], v[178:181], v[222:225], 0
	v_mfma_f32_16x16x32_bf16 v[100:103], v[182:185], v[226:229], v[100:103]
	v_mfma_f32_16x16x32_bf16 v[84:87], v[178:181], v[230:233], 0
	v_mfma_f32_16x16x32_bf16 v[84:87], v[182:185], v[234:237], v[84:87]
	v_mfma_f32_16x16x32_bf16 v[68:71], v[178:181], v[238:241], 0
	v_mfma_f32_16x16x32_bf16 v[68:71], v[182:185], v[242:245], v[68:71]
	v_mfma_f32_16x16x32_bf16 v[112:115], v[186:189], v[214:217], 0
	v_mfma_f32_16x16x32_bf16 v[112:115], v[210:213], v[218:221], v[112:115]
	v_mfma_f32_16x16x32_bf16 v[96:99], v[186:189], v[222:225], 0
	v_mfma_f32_16x16x32_bf16 v[96:99], v[210:213], v[226:229], v[96:99]
	v_mfma_f32_16x16x32_bf16 v[80:83], v[186:189], v[230:233], 0
	v_mfma_f32_16x16x32_bf16 v[80:83], v[210:213], v[234:237], v[80:83]
	v_mfma_f32_16x16x32_bf16 v[64:67], v[186:189], v[238:241], 0
	v_mfma_f32_16x16x32_bf16 v[64:67], v[210:213], v[242:245], v[64:67]
	s_setprio 0
	s_barrier
	s_mov_b32 m0, s33
	s_add_u32 s56, s2, 0x40000
	s_addc_u32 s57, s3, 0
	ds_read_b128 v[214:217], v163 offset:16384
	ds_read_b128 v[218:221], v163 offset:17408
	global_load_lds_dwordx4 v132, s[2:3]
	s_mov_b32 m0, s34
	ds_read_b128 v[222:225], v163 offset:18432
	ds_read_b128 v[226:229], v163 offset:19456
	global_load_lds_dwordx4 v128, s[2:3]
	s_mov_b32 m0, s35
	ds_read_b128 v[230:233], v163 offset:20480
	global_load_lds_dwordx4 v132, s[56:57]
	s_mov_b32 m0, s36
	ds_read_b128 v[234:237], v163 offset:21504
	global_load_lds_dwordx4 v128, s[56:57]
	s_mov_b32 m0, s31
	ds_read_b128 v[238:241], v163 offset:22528
	global_load_lds_dwordx4 v134, s[4:5]
	s_mov_b32 m0, s37
	ds_read_b128 v[242:245], v163 offset:23552
	global_load_lds_dwordx4 v130, s[4:5]
	s_waitcnt vmcnt(8) lgkmcnt(0)
	s_barrier
	s_setprio 1
	v_mfma_f32_16x16x32_bf16 v[60:63], v[140:143], v[214:217], 0
	v_mfma_f32_16x16x32_bf16 v[60:63], v[166:169], v[218:221], v[60:63]
	v_mfma_f32_16x16x32_bf16 v[44:47], v[140:143], v[222:225], 0
	v_mfma_f32_16x16x32_bf16 v[44:47], v[166:169], v[226:229], v[44:47]
	v_mfma_f32_16x16x32_bf16 v[28:31], v[140:143], v[230:233], 0
	v_mfma_f32_16x16x32_bf16 v[28:31], v[166:169], v[234:237], v[28:31]
	v_mfma_f32_16x16x32_bf16 v[12:15], v[140:143], v[238:241], 0
	v_mfma_f32_16x16x32_bf16 v[12:15], v[166:169], v[242:245], v[12:15]
	v_mfma_f32_16x16x32_bf16 v[56:59], v[170:173], v[214:217], 0
	v_mfma_f32_16x16x32_bf16 v[56:59], v[174:177], v[218:221], v[56:59]
	v_mfma_f32_16x16x32_bf16 v[40:43], v[170:173], v[222:225], 0
	v_mfma_f32_16x16x32_bf16 v[40:43], v[174:177], v[226:229], v[40:43]
	v_mfma_f32_16x16x32_bf16 v[24:27], v[170:173], v[230:233], 0
	v_mfma_f32_16x16x32_bf16 v[24:27], v[174:177], v[234:237], v[24:27]
	v_mfma_f32_16x16x32_bf16 v[8:11], v[170:173], v[238:241], 0
	v_mfma_f32_16x16x32_bf16 v[8:11], v[174:177], v[242:245], v[8:11]
	v_mfma_f32_16x16x32_bf16 v[52:55], v[178:181], v[214:217], 0
	v_mfma_f32_16x16x32_bf16 v[52:55], v[182:185], v[218:221], v[52:55]
	v_mfma_f32_16x16x32_bf16 v[36:39], v[178:181], v[222:225], 0
	v_mfma_f32_16x16x32_bf16 v[36:39], v[182:185], v[226:229], v[36:39]
	v_mfma_f32_16x16x32_bf16 v[20:23], v[178:181], v[230:233], 0
	v_mfma_f32_16x16x32_bf16 v[20:23], v[182:185], v[234:237], v[20:23]
	v_mfma_f32_16x16x32_bf16 v[4:7], v[178:181], v[238:241], 0
	v_mfma_f32_16x16x32_bf16 v[4:7], v[182:185], v[242:245], v[4:7]
	v_mfma_f32_16x16x32_bf16 v[48:51], v[186:189], v[214:217], 0
	v_mfma_f32_16x16x32_bf16 v[48:51], v[210:213], v[218:221], v[48:51]
	v_mfma_f32_16x16x32_bf16 v[32:35], v[186:189], v[222:225], 0
	v_mfma_f32_16x16x32_bf16 v[32:35], v[210:213], v[226:229], v[32:35]
	v_mfma_f32_16x16x32_bf16 v[16:19], v[186:189], v[230:233], 0
	v_mfma_f32_16x16x32_bf16 v[16:19], v[210:213], v[234:237], v[16:19]
	v_mfma_f32_16x16x32_bf16 v[0:3], v[186:189], v[238:241], 0
	v_mfma_f32_16x16x32_bf16 v[0:3], v[210:213], v[242:245], v[0:3]
	s_setprio 0
	s_barrier
; #define PG8_STAGE(bufoff, gbase, voff) do { _Pragma("unroll") for (int _i = 0; _i < 2; ++_i) \
;         __builtin_amdgcn_global_load_lds((const unsigned*)((const char*)(gbase) + (voff)[_i]), (PG8_LAS unsigned*)(lds + (bufoff) + ldsw + _i * 8192), 16, 0, 0); } while (0)
; #define PG8_LDA(dst, b, h) do { _Pragma("unroll") for (int m = 0; m < 4; ++m) _Pragma("unroll") for (int k = 0; k < 2; ++k) dst[m][k] = *(const PG8_LAS bf16x8*)(lds + PG8_SA(b, h) + aoff + m * 2048 + k * 1024); } while (0)
; #define PG8_LDB(dst, b, h) do { _Pragma("unroll") for (int n = 0; n < 2; ++n) _Pragma("unroll") for (int k = 0; k < 2; ++k) dst[n][k] = *(const PG8_LAS bf16x8*)(lds + PG8_SB(b, h) + boff + n * 2048 + k * 1024); } while (0)
; #define PG8_MMA(ai, bj, At, Bt) do { __builtin_amdgcn_s_setprio(1); _Pragma("unroll") for (int m = 0; m < 4; ++m) _Pragma("unroll") for (int n = 0; n < 2; ++n) _Pragma("unroll") for (int k = 0; k < 2; ++k) \
;         acc[ai][bj][m][n] = __builtin_amdgcn_mfma_f32_16x16x32_bf16(Bt[n][k], At[m][k], acc[ai][bj][m][n], 0, 0, 0); __builtin_amdgcn_s_setprio(0); } while (0)
; #define PG8_WAIT_V(n) asm volatile("s_waitcnt vmcnt(" #n ")" ::: "memory")
; #define PG8_WAIT_L(n) asm volatile("s_waitcnt lgkmcnt(" #n ")" ::: "memory")
; #define PG8_BAR __builtin_amdgcn_s_barrier()
; #define PG8_SCHED __builtin_amdgcn_sched_barrier(0)
; template <class Epi, class Sched, bool ALIGN_EPI = false, bool SP2 = false>
; __device__ __forceinline__ void gemm_phase(PG8_LAS unsigned char* lds, const Gemm g, const Sched& S, const Epi& E) {
;     ...
;             PG8_LDB(B0, 1, 0); PG8_LDB(B1, 1, 1); PG8_SCHED; PG8_LDA(At, 1, 0); PG8_STAGE(PG8_SA(0, 1), a2 + hstep, voffA);
;             PG8_WAIT_V(8); PG8_WAIT_L(0); PG8_BAR; PG8_MMA(0, 0, At, B0); PG8_MMA(0, 1, At, B1); PG8_BAR; PG8_SCHED;
;             PG8_LDA(At, 1, 1); PG8_STAGE(PG8_SB(1, 0), b3, voffB); PG8_STAGE(PG8_SB(1, 1), b3 + hstep, voffB); PG8_STAGE(PG8_SA(1, 0), a3, voffA);
;             PG8_WAIT_V(8); PG8_WAIT_L(0); PG8_BAR; PG8_MMA(1, 0, At, B0); PG8_MMA(1, 1, At, B1); PG8_BAR; PG8_SCHED;
	s_add_u32 s4, s4, 0x40000
	s_addc_u32 s5, s5, 0
	s_mov_b32 m0, s38
	ds_read_b128 v[140:143], v254 offset:32768
	ds_read_b128 v[166:169], v254 offset:33792
	ds_read_b128 v[170:173], v254 offset:34816
	ds_read_b128 v[174:177], v254 offset:35840
	ds_read_b128 v[178:181], v254 offset:49152
	ds_read_b128 v[182:185], v254 offset:50176
	ds_read_b128 v[186:189], v254 offset:51200
	ds_read_b128 v[210:213], v254 offset:52224
	global_load_lds_dwordx4 v134, s[4:5]
	s_mov_b32 m0, s39
	ds_read_b128 v[214:217], v163 offset:32768
	ds_read_b128 v[218:221], v163 offset:33792
	ds_read_b128 v[222:225], v163 offset:34816
	ds_read_b128 v[226:229], v163 offset:35840
	ds_read_b128 v[230:233], v163 offset:36864
	ds_read_b128 v[234:237], v163 offset:37888
	ds_read_b128 v[238:241], v163 offset:38912
	ds_read_b128 v[242:245], v163 offset:39936
	global_load_lds_dwordx4 v130, s[4:5]
	s_waitcnt vmcnt(8) lgkmcnt(0)
	s_barrier
	s_setprio 1
	v_mfma_f32_16x16x32_bf16 v[124:127], v[140:143], v[214:217], v[124:127]
	v_mfma_f32_16x16x32_bf16 v[124:127], v[166:169], v[218:221], v[124:127]
	v_mfma_f32_16x16x32_bf16 v[108:111], v[140:143], v[222:225], v[108:111]
	v_mfma_f32_16x16x32_bf16 v[108:111], v[166:169], v[226:229], v[108:111]
	v_mfma_f32_16x16x32_bf16 v[92:95], v[140:143], v[230:233], v[92:95]
	v_mfma_f32_16x16x32_bf16 v[92:95], v[166:169], v[234:237], v[92:95]
	v_mfma_f32_16x16x32_bf16 v[76:79], v[140:143], v[238:241], v[76:79]
	v_mfma_f32_16x16x32_bf16 v[76:79], v[166:169], v[242:245], v[76:79]
	v_mfma_f32_16x16x32_bf16 v[120:123], v[170:173], v[214:217], v[120:123]
	v_mfma_f32_16x16x32_bf16 v[120:123], v[174:177], v[218:221], v[120:123]
	v_mfma_f32_16x16x32_bf16 v[104:107], v[170:173], v[222:225], v[104:107]
	v_mfma_f32_16x16x32_bf16 v[104:107], v[174:177], v[226:229], v[104:107]
	v_mfma_f32_16x16x32_bf16 v[88:91], v[170:173], v[230:233], v[88:91]
	v_mfma_f32_16x16x32_bf16 v[88:91], v[174:177], v[234:237], v[88:91]
	v_mfma_f32_16x16x32_bf16 v[72:75], v[170:173], v[238:241], v[72:75]
	v_mfma_f32_16x16x32_bf16 v[72:75], v[174:177], v[242:245], v[72:75]
	v_mfma_f32_16x16x32_bf16 v[116:119], v[178:181], v[214:217], v[116:119]
	v_mfma_f32_16x16x32_bf16 v[116:119], v[182:185], v[218:221], v[116:119]
	v_mfma_f32_16x16x32_bf16 v[100:103], v[178:181], v[222:225], v[100:103]
	v_mfma_f32_16x16x32_bf16 v[100:103], v[182:185], v[226:229], v[100:103]
	v_mfma_f32_16x16x32_bf16 v[84:87], v[178:181], v[230:233], v[84:87]
	v_mfma_f32_16x16x32_bf16 v[84:87], v[182:185], v[234:237], v[84:87]
	v_mfma_f32_16x16x32_bf16 v[68:71], v[178:181], v[238:241], v[68:71]
	v_mfma_f32_16x16x32_bf16 v[68:71], v[182:185], v[242:245], v[68:71]
	v_mfma_f32_16x16x32_bf16 v[112:115], v[186:189], v[214:217], v[112:115]
	v_mfma_f32_16x16x32_bf16 v[112:115], v[210:213], v[218:221], v[112:115]
	v_mfma_f32_16x16x32_bf16 v[96:99], v[186:189], v[222:225], v[96:99]
	v_mfma_f32_16x16x32_bf16 v[96:99], v[210:213], v[226:229], v[96:99]
	v_mfma_f32_16x16x32_bf16 v[80:83], v[186:189], v[230:233], v[80:83]
	v_mfma_f32_16x16x32_bf16 v[80:83], v[210:213], v[234:237], v[80:83]
	v_mfma_f32_16x16x32_bf16 v[64:67], v[186:189], v[238:241], v[64:67]
	v_mfma_f32_16x16x32_bf16 v[64:67], v[210:213], v[242:245], v[64:67]
	s_setprio 0
	s_barrier
	s_mov_b32 m0, s43
	s_add_u32 s2, s2, 0x40080
	s_addc_u32 s3, s3, 0
	s_add_u32 s98, s2, 0xfffc0000
	s_addc_u32 s99, s3, -1
	ds_read_b128 v[214:217], v163 offset:49152
	ds_read_b128 v[218:221], v163 offset:50176
	global_load_lds_dwordx4 v132, s[98:99]
	s_mov_b32 m0, s44
	ds_read_b128 v[222:225], v163 offset:51200
	ds_read_b128 v[226:229], v163 offset:52224
	global_load_lds_dwordx4 v128, s[98:99]
	s_mov_b32 m0, s48
	ds_read_b128 v[230:233], v163 offset:53248
	global_load_lds_dwordx4 v132, s[2:3]
	s_mov_b32 m0, s49
	ds_read_b128 v[234:237], v163 offset:54272
	global_load_lds_dwordx4 v128, s[2:3]
	s_mov_b32 m0, s45
	s_add_u32 s100, s4, 0xfffc0080
	s_addc_u32 s101, s5, -1
	ds_read_b128 v[238:241], v163 offset:55296
	global_load_lds_dwordx4 v134, s[100:101]
	s_mov_b32 m0, s47
	ds_read_b128 v[242:245], v163 offset:56320
	global_load_lds_dwordx4 v130, s[100:101]
	s_waitcnt vmcnt(8) lgkmcnt(0)
	s_barrier
	s_setprio 1
	v_mfma_f32_16x16x32_bf16 v[60:63], v[140:143], v[214:217], v[60:63]
	v_mfma_f32_16x16x32_bf16 v[60:63], v[166:169], v[218:221], v[60:63]
	v_mfma_f32_16x16x32_bf16 v[44:47], v[140:143], v[222:225], v[44:47]
	v_mfma_f32_16x16x32_bf16 v[44:47], v[166:169], v[226:229], v[44:47]
	v_mfma_f32_16x16x32_bf16 v[28:31], v[140:143], v[230:233], v[28:31]
	v_mfma_f32_16x16x32_bf16 v[28:31], v[166:169], v[234:237], v[28:31]
	v_mfma_f32_16x16x32_bf16 v[12:15], v[140:143], v[238:241], v[12:15]
	v_mfma_f32_16x16x32_bf16 v[12:15], v[166:169], v[242:245], v[12:15]
	v_mfma_f32_16x16x32_bf16 v[56:59], v[170:173], v[214:217], v[56:59]
	v_mfma_f32_16x16x32_bf16 v[56:59], v[174:177], v[218:221], v[56:59]
	v_mfma_f32_16x16x32_bf16 v[40:43], v[170:173], v[222:225], v[40:43]
	v_mfma_f32_16x16x32_bf16 v[40:43], v[174:177], v[226:229], v[40:43]
	v_mfma_f32_16x16x32_bf16 v[24:27], v[170:173], v[230:233], v[24:27]
	v_mfma_f32_16x16x32_bf16 v[24:27], v[174:177], v[234:237], v[24:27]
	v_mfma_f32_16x16x32_bf16 v[8:11], v[170:173], v[238:241], v[8:11]
	v_mfma_f32_16x16x32_bf16 v[8:11], v[174:177], v[242:245], v[8:11]
	v_mfma_f32_16x16x32_bf16 v[52:55], v[178:181], v[214:217], v[52:55]
	v_mfma_f32_16x16x32_bf16 v[52:55], v[182:185], v[218:221], v[52:55]
	v_mfma_f32_16x16x32_bf16 v[36:39], v[178:181], v[222:225], v[36:39]
	v_mfma_f32_16x16x32_bf16 v[36:39], v[182:185], v[226:229], v[36:39]
	v_mfma_f32_16x16x32_bf16 v[20:23], v[178:181], v[230:233], v[20:23]
	v_mfma_f32_16x16x32_bf16 v[20:23], v[182:185], v[234:237], v[20:23]
	v_mfma_f32_16x16x32_bf16 v[4:7], v[178:181], v[238:241], v[4:7]
	v_mfma_f32_16x16x32_bf16 v[4:7], v[182:185], v[242:245], v[4:7]
	v_mfma_f32_16x16x32_bf16 v[48:51], v[186:189], v[214:217], v[48:51]
	v_mfma_f32_16x16x32_bf16 v[48:51], v[210:213], v[218:221], v[48:51]
	v_mfma_f32_16x16x32_bf16 v[32:35], v[186:189], v[222:225], v[32:35]
	v_mfma_f32_16x16x32_bf16 v[32:35], v[210:213], v[226:229], v[32:35]
	v_mfma_f32_16x16x32_bf16 v[16:19], v[186:189], v[230:233], v[16:19]
	v_mfma_f32_16x16x32_bf16 v[16:19], v[210:213], v[234:237], v[16:19]
	v_mfma_f32_16x16x32_bf16 v[0:3], v[186:189], v[238:241], v[0:3]
	v_mfma_f32_16x16x32_bf16 v[0:3], v[210:213], v[242:245], v[0:3]
	s_setprio 0
	s_barrier
	s_add_i32 s55, s55, 2
	s_add_u32 s0, s0, 0x100
	s_addc_u32 s1, s1, 0
	s_add_u32 s53, s53, 0x100
	s_addc_u32 s54, s54, 0
	s_cmp_gt_u32 s55, 13
; #define PG8_STAGE(bufoff, gbase, voff) do { _Pragma("unroll") for (int _i = 0; _i < 2; ++_i) \
;         __builtin_amdgcn_global_load_lds((const unsigned*)((const char*)(gbase) + (voff)[_i]), (PG8_LAS unsigned*)(lds + (bufoff) + ldsw + _i * 8192), 16, 0, 0); } while (0)
; #define PG8_LDA(dst, b, h) do { _Pragma("unroll") for (int m = 0; m < 4; ++m) _Pragma("unroll") for (int k = 0; k < 2; ++k) dst[m][k] = *(const PG8_LAS bf16x8*)(lds + PG8_SA(b, h) + aoff + m * 2048 + k * 1024); } while (0)
; #define PG8_LDB(dst, b, h) do { _Pragma("unroll") for (int n = 0; n < 2; ++n) _Pragma("unroll") for (int k = 0; k < 2; ++k) dst[n][k] = *(const PG8_LAS bf16x8*)(lds + PG8_SB(b, h) + boff + n * 2048 + k * 1024); } while (0)
; #define PG8_MMA(ai, bj, At, Bt) do { __builtin_amdgcn_s_setprio(1); _Pragma("unroll") for (int m = 0; m < 4; ++m) _Pragma("unroll") for (int n = 0; n < 2; ++n) _Pragma("unroll") for (int k = 0; k < 2; ++k) \
;         acc[ai][bj][m][n] = __builtin_amdgcn_mfma_f32_16x16x32_bf16(Bt[n][k], At[m][k], acc[ai][bj][m][n], 0, 0, 0); __builtin_amdgcn_s_setprio(0); } while (0)
; #define PG8_WAIT_V(n) asm volatile("s_waitcnt vmcnt(" #n ")" ::: "memory")
; #define PG8_WAIT_L(n) asm volatile("s_waitcnt lgkmcnt(" #n ")" ::: "memory")
; #define PG8_BAR __builtin_amdgcn_s_barrier()
; #define PG8_SCHED __builtin_amdgcn_sched_barrier(0)
; template <class Epi, class Sched, bool ALIGN_EPI = false, bool SP2 = false>
; __device__ __forceinline__ void gemm_phase(PG8_LAS unsigned char* lds, const Gemm g, const Sched& S, const Epi& E) {
;     ...
;             const bool last = (t == nt - 2);
;             const char* a1 = cA + (size_t)(t + 1) * kstep;
;             const char* a2 = last ? nA : cA + (size_t)(t + 2) * kstep; const char* b2 = last ? nB : cB + (size_t)(t + 2) * kstep;
;             const char* a3 = a2 + kstep; const char* b3 = b2 + kstep;
;     ...
;             PG8_LDB(B0, 0, 0); PG8_LDB(B1, 0, 1); PG8_SCHED; PG8_LDA(At, 0, 0); PG8_STAGE(PG8_SA(1, 1), a1 + hstep, voffA);
;             PG8_WAIT_V(8); PG8_WAIT_L(0); PG8_BAR; PG8_MMA(0, 0, At, B0); PG8_MMA(0, 1, At, B1); PG8_BAR; PG8_SCHED;
;             PG8_LDA(At, 0, 1); PG8_STAGE(PG8_SB(0, 0), b2, voffB); PG8_STAGE(PG8_SB(0, 1), b2 + hstep, voffB); PG8_STAGE(PG8_SA(0, 0), a2, voffA);
;             PG8_WAIT_V(8); PG8_WAIT_L(0); PG8_BAR; PG8_MMA(1, 0, At, B0); PG8_MMA(1, 1, At, B1); PG8_BAR; PG8_SCHED;
.LBB0_1042:
	s_add_u32 s2, s0, 0xfffc0080
	s_addc_u32 s3, s1, -1
	s_cmp_eq_u32 s55, 12
	s_cselect_b32 s5, s23, s3
	s_cselect_b32 s4, s51, s2
	s_cselect_b32 s3, s21, s54
	s_cselect_b32 s2, s52, s53
	s_add_i32 m0, s31, 0xc000
	ds_read_b128 v[140:143], v254
	ds_read_b128 v[166:169], v254 offset:1024
	ds_read_b128 v[170:173], v254 offset:2048
	ds_read_b128 v[174:177], v254 offset:3072
	ds_read_b128 v[178:181], v254 offset:16384
	ds_read_b128 v[182:185], v254 offset:17408
	ds_read_b128 v[186:189], v254 offset:18432
	ds_read_b128 v[210:213], v254 offset:19456
	global_load_lds_dwordx4 v136, s[0:1]
	s_add_i32 m0, s31, 0xe000
	ds_read_b128 v[214:217], v163
	ds_read_b128 v[218:221], v163 offset:1024
	ds_read_b128 v[222:225], v163 offset:2048
	ds_read_b128 v[226:229], v163 offset:3072
	ds_read_b128 v[230:233], v163 offset:4096
	ds_read_b128 v[234:237], v163 offset:5120
	ds_read_b128 v[238:241], v163 offset:6144
	ds_read_b128 v[242:245], v163 offset:7168
	global_load_lds_dwordx4 v138, s[0:1]
	s_waitcnt vmcnt(8) lgkmcnt(0)
	s_barrier
	s_setprio 1
	v_mfma_f32_16x16x32_bf16 v[124:127], v[140:143], v[214:217], v[124:127]
	v_mfma_f32_16x16x32_bf16 v[124:127], v[166:169], v[218:221], v[124:127]
	v_mfma_f32_16x16x32_bf16 v[108:111], v[140:143], v[222:225], v[108:111]
	v_mfma_f32_16x16x32_bf16 v[108:111], v[166:169], v[226:229], v[108:111]
	v_mfma_f32_16x16x32_bf16 v[92:95], v[140:143], v[230:233], v[92:95]
	v_mfma_f32_16x16x32_bf16 v[92:95], v[166:169], v[234:237], v[92:95]
	v_mfma_f32_16x16x32_bf16 v[76:79], v[140:143], v[238:241], v[76:79]
	v_mfma_f32_16x16x32_bf16 v[76:79], v[166:169], v[242:245], v[76:79]
	v_mfma_f32_16x16x32_bf16 v[120:123], v[170:173], v[214:217], v[120:123]
	v_mfma_f32_16x16x32_bf16 v[120:123], v[174:177], v[218:221], v[120:123]
	v_mfma_f32_16x16x32_bf16 v[104:107], v[170:173], v[222:225], v[104:107]
	v_mfma_f32_16x16x32_bf16 v[104:107], v[174:177], v[226:229], v[104:107]
	v_mfma_f32_16x16x32_bf16 v[88:91], v[170:173], v[230:233], v[88:91]
	v_mfma_f32_16x16x32_bf16 v[88:91], v[174:177], v[234:237], v[88:91]
	v_mfma_f32_16x16x32_bf16 v[72:75], v[170:173], v[238:241], v[72:75]
	v_mfma_f32_16x16x32_bf16 v[72:75], v[174:177], v[242:245], v[72:75]
	v_mfma_f32_16x16x32_bf16 v[116:119], v[178:181], v[214:217], v[116:119]
	v_mfma_f32_16x16x32_bf16 v[116:119], v[182:185], v[218:221], v[116:119]
	v_mfma_f32_16x16x32_bf16 v[100:103], v[178:181], v[222:225], v[100:103]
	v_mfma_f32_16x16x32_bf16 v[100:103], v[182:185], v[226:229], v[100:103]
	v_mfma_f32_16x16x32_bf16 v[84:87], v[178:181], v[230:233], v[84:87]
	v_mfma_f32_16x16x32_bf16 v[84:87], v[182:185], v[234:237], v[84:87]
	v_mfma_f32_16x16x32_bf16 v[68:71], v[178:181], v[238:241], v[68:71]
	v_mfma_f32_16x16x32_bf16 v[68:71], v[182:185], v[242:245], v[68:71]
	v_mfma_f32_16x16x32_bf16 v[112:115], v[186:189], v[214:217], v[112:115]
	v_mfma_f32_16x16x32_bf16 v[112:115], v[210:213], v[218:221], v[112:115]
	v_mfma_f32_16x16x32_bf16 v[96:99], v[186:189], v[222:225], v[96:99]
	v_mfma_f32_16x16x32_bf16 v[96:99], v[210:213], v[226:229], v[96:99]
	v_mfma_f32_16x16x32_bf16 v[80:83], v[186:189], v[230:233], v[80:83]
	v_mfma_f32_16x16x32_bf16 v[80:83], v[210:213], v[234:237], v[80:83]
	v_mfma_f32_16x16x32_bf16 v[64:67], v[186:189], v[238:241], v[64:67]
	v_mfma_f32_16x16x32_bf16 v[64:67], v[210:213], v[242:245], v[64:67]
	s_setprio 0
	s_barrier
	s_mov_b32 m0, s33
	s_add_u32 s56, s2, 0x40000
	s_addc_u32 s57, s3, 0
	ds_read_b128 v[214:217], v163 offset:16384
	ds_read_b128 v[218:221], v163 offset:17408
	global_load_lds_dwordx4 v132, s[2:3]
	s_mov_b32 m0, s34
	ds_read_b128 v[222:225], v163 offset:18432
	ds_read_b128 v[226:229], v163 offset:19456
	global_load_lds_dwordx4 v128, s[2:3]
	s_mov_b32 m0, s35
	ds_read_b128 v[230:233], v163 offset:20480
	global_load_lds_dwordx4 v132, s[56:57]
	s_mov_b32 m0, s36
	ds_read_b128 v[234:237], v163 offset:21504
	global_load_lds_dwordx4 v128, s[56:57]
	s_mov_b32 m0, s31
	ds_read_b128 v[238:241], v163 offset:22528
	global_load_lds_dwordx4 v134, s[4:5]
	s_mov_b32 m0, s37
	ds_read_b128 v[242:245], v163 offset:23552
	global_load_lds_dwordx4 v130, s[4:5]
	s_waitcnt vmcnt(8) lgkmcnt(0)
	s_barrier
	s_setprio 1
	v_mfma_f32_16x16x32_bf16 v[60:63], v[140:143], v[214:217], v[60:63]
	v_mfma_f32_16x16x32_bf16 v[60:63], v[166:169], v[218:221], v[60:63]
	v_mfma_f32_16x16x32_bf16 v[44:47], v[140:143], v[222:225], v[44:47]
	v_mfma_f32_16x16x32_bf16 v[44:47], v[166:169], v[226:229], v[44:47]
	v_mfma_f32_16x16x32_bf16 v[28:31], v[140:143], v[230:233], v[28:31]
	v_mfma_f32_16x16x32_bf16 v[28:31], v[166:169], v[234:237], v[28:31]
	v_mfma_f32_16x16x32_bf16 v[12:15], v[140:143], v[238:241], v[12:15]
	v_mfma_f32_16x16x32_bf16 v[12:15], v[166:169], v[242:245], v[12:15]
	v_mfma_f32_16x16x32_bf16 v[56:59], v[170:173], v[214:217], v[56:59]
	v_mfma_f32_16x16x32_bf16 v[56:59], v[174:177], v[218:221], v[56:59]
	v_mfma_f32_16x16x32_bf16 v[40:43], v[170:173], v[222:225], v[40:43]
	v_mfma_f32_16x16x32_bf16 v[40:43], v[174:177], v[226:229], v[40:43]
	v_mfma_f32_16x16x32_bf16 v[24:27], v[170:173], v[230:233], v[24:27]
	v_mfma_f32_16x16x32_bf16 v[24:27], v[174:177], v[234:237], v[24:27]
	v_mfma_f32_16x16x32_bf16 v[8:11], v[170:173], v[238:241], v[8:11]
	v_mfma_f32_16x16x32_bf16 v[8:11], v[174:177], v[242:245], v[8:11]
	v_mfma_f32_16x16x32_bf16 v[52:55], v[178:181], v[214:217], v[52:55]
	v_mfma_f32_16x16x32_bf16 v[52:55], v[182:185], v[218:221], v[52:55]
	v_mfma_f32_16x16x32_bf16 v[36:39], v[178:181], v[222:225], v[36:39]
	v_mfma_f32_16x16x32_bf16 v[36:39], v[182:185], v[226:229], v[36:39]
	v_mfma_f32_16x16x32_bf16 v[20:23], v[178:181], v[230:233], v[20:23]
	v_mfma_f32_16x16x32_bf16 v[20:23], v[182:185], v[234:237], v[20:23]
	v_mfma_f32_16x16x32_bf16 v[4:7], v[178:181], v[238:241], v[4:7]
	v_mfma_f32_16x16x32_bf16 v[4:7], v[182:185], v[242:245], v[4:7]
	v_mfma_f32_16x16x32_bf16 v[48:51], v[186:189], v[214:217], v[48:51]
	v_mfma_f32_16x16x32_bf16 v[48:51], v[210:213], v[218:221], v[48:51]
	v_mfma_f32_16x16x32_bf16 v[32:35], v[186:189], v[222:225], v[32:35]
	v_mfma_f32_16x16x32_bf16 v[32:35], v[210:213], v[226:229], v[32:35]
	v_mfma_f32_16x16x32_bf16 v[16:19], v[186:189], v[230:233], v[16:19]
	v_mfma_f32_16x16x32_bf16 v[16:19], v[210:213], v[234:237], v[16:19]
	v_mfma_f32_16x16x32_bf16 v[0:3], v[186:189], v[238:241], v[0:3]
	v_mfma_f32_16x16x32_bf16 v[0:3], v[210:213], v[242:245], v[0:3]
	s_setprio 0
	s_barrier
; #define PG8_STAGE(bufoff, gbase, voff) do { _Pragma("unroll") for (int _i = 0; _i < 2; ++_i) \
;         __builtin_amdgcn_global_load_lds((const unsigned*)((const char*)(gbase) + (voff)[_i]), (PG8_LAS unsigned*)(lds + (bufoff) + ldsw + _i * 8192), 16, 0, 0); } while (0)
; #define PG8_LDA(dst, b, h) do { _Pragma("unroll") for (int m = 0; m < 4; ++m) _Pragma("unroll") for (int k = 0; k < 2; ++k) dst[m][k] = *(const PG8_LAS bf16x8*)(lds + PG8_SA(b, h) + aoff + m * 2048 + k * 1024); } while (0)
; #define PG8_LDB(dst, b, h) do { _Pragma("unroll") for (int n = 0; n < 2; ++n) _Pragma("unroll") for (int k = 0; k < 2; ++k) dst[n][k] = *(const PG8_LAS bf16x8*)(lds + PG8_SB(b, h) + boff + n * 2048 + k * 1024); } while (0)
; #define PG8_MMA(ai, bj, At, Bt) do { __builtin_amdgcn_s_setprio(1); _Pragma("unroll") for (int m = 0; m < 4; ++m) _Pragma("unroll") for (int n = 0; n < 2; ++n) _Pragma("unroll") for (int k = 0; k < 2; ++k) \
;         acc[ai][bj][m][n] = __builtin_amdgcn_mfma_f32_16x16x32_bf16(Bt[n][k], At[m][k], acc[ai][bj][m][n], 0, 0, 0); __builtin_amdgcn_s_setprio(0); } while (0)
; #define PG8_WAIT_V(n) asm volatile("s_waitcnt vmcnt(" #n ")" ::: "memory")
; #define PG8_WAIT_L(n) asm volatile("s_waitcnt lgkmcnt(" #n ")" ::: "memory")
; #define PG8_BAR __builtin_amdgcn_s_barrier()
; #define PG8_SCHED __builtin_amdgcn_sched_barrier(0)
; template <class Epi, class Sched, bool ALIGN_EPI = false, bool SP2 = false>
; __device__ __forceinline__ void gemm_phase(PG8_LAS unsigned char* lds, const Gemm g, const Sched& S, const Epi& E) {
;     ...
;         for (int t = 0; t < nt; t += 2) {
;     ...
;             PG8_LDB(B0, 1, 0); PG8_LDB(B1, 1, 1); PG8_SCHED; PG8_LDA(At, 1, 0); PG8_STAGE(PG8_SA(0, 1), a2 + hstep, voffA);
;             PG8_WAIT_V(8); PG8_WAIT_L(0); PG8_BAR; PG8_MMA(0, 0, At, B0); PG8_MMA(0, 1, At, B1); PG8_BAR; PG8_SCHED;
;             PG8_LDA(At, 1, 1); PG8_STAGE(PG8_SB(1, 0), b3, voffB); PG8_STAGE(PG8_SB(1, 1), b3 + hstep, voffB); PG8_STAGE(PG8_SA(1, 0), a3, voffA);
;             PG8_WAIT_V(8); PG8_WAIT_L(0); PG8_BAR; PG8_MMA(1, 0, At, B0); PG8_MMA(1, 1, At, B1); PG8_BAR; PG8_SCHED;
;     ...
;         if constexpr (ALIGN_EPI) { if (wr == 0) PG8_BAR; }
	s_add_u32 s4, s4, 0x40000
	s_addc_u32 s5, s5, 0
	s_mov_b32 m0, s38
	ds_read_b128 v[140:143], v254 offset:32768
	ds_read_b128 v[166:169], v254 offset:33792
	ds_read_b128 v[170:173], v254 offset:34816
	ds_read_b128 v[174:177], v254 offset:35840
	ds_read_b128 v[178:181], v254 offset:49152
	ds_read_b128 v[182:185], v254 offset:50176
	ds_read_b128 v[186:189], v254 offset:51200
	ds_read_b128 v[210:213], v254 offset:52224
	global_load_lds_dwordx4 v134, s[4:5]
	s_mov_b32 m0, s39
	ds_read_b128 v[214:217], v163 offset:32768
	ds_read_b128 v[218:221], v163 offset:33792
	ds_read_b128 v[222:225], v163 offset:34816
	ds_read_b128 v[226:229], v163 offset:35840
	ds_read_b128 v[230:233], v163 offset:36864
	ds_read_b128 v[234:237], v163 offset:37888
	ds_read_b128 v[238:241], v163 offset:38912
	ds_read_b128 v[242:245], v163 offset:39936
	global_load_lds_dwordx4 v130, s[4:5]
	s_waitcnt vmcnt(8) lgkmcnt(0)
	s_barrier
	s_setprio 1
	v_mfma_f32_16x16x32_bf16 v[124:127], v[140:143], v[214:217], v[124:127]
	v_mfma_f32_16x16x32_bf16 v[124:127], v[166:169], v[218:221], v[124:127]
	v_mfma_f32_16x16x32_bf16 v[108:111], v[140:143], v[222:225], v[108:111]
	v_mfma_f32_16x16x32_bf16 v[108:111], v[166:169], v[226:229], v[108:111]
	v_mfma_f32_16x16x32_bf16 v[92:95], v[140:143], v[230:233], v[92:95]
	v_mfma_f32_16x16x32_bf16 v[92:95], v[166:169], v[234:237], v[92:95]
	v_mfma_f32_16x16x32_bf16 v[76:79], v[140:143], v[238:241], v[76:79]
	v_mfma_f32_16x16x32_bf16 v[76:79], v[166:169], v[242:245], v[76:79]
	v_mfma_f32_16x16x32_bf16 v[120:123], v[170:173], v[214:217], v[120:123]
	v_mfma_f32_16x16x32_bf16 v[120:123], v[174:177], v[218:221], v[120:123]
	v_mfma_f32_16x16x32_bf16 v[104:107], v[170:173], v[222:225], v[104:107]
	v_mfma_f32_16x16x32_bf16 v[104:107], v[174:177], v[226:229], v[104:107]
	v_mfma_f32_16x16x32_bf16 v[88:91], v[170:173], v[230:233], v[88:91]
	v_mfma_f32_16x16x32_bf16 v[88:91], v[174:177], v[234:237], v[88:91]
	v_mfma_f32_16x16x32_bf16 v[72:75], v[170:173], v[238:241], v[72:75]
	v_mfma_f32_16x16x32_bf16 v[72:75], v[174:177], v[242:245], v[72:75]
	v_mfma_f32_16x16x32_bf16 v[116:119], v[178:181], v[214:217], v[116:119]
	v_mfma_f32_16x16x32_bf16 v[116:119], v[182:185], v[218:221], v[116:119]
	v_mfma_f32_16x16x32_bf16 v[100:103], v[178:181], v[222:225], v[100:103]
	v_mfma_f32_16x16x32_bf16 v[100:103], v[182:185], v[226:229], v[100:103]
	v_mfma_f32_16x16x32_bf16 v[84:87], v[178:181], v[230:233], v[84:87]
	v_mfma_f32_16x16x32_bf16 v[84:87], v[182:185], v[234:237], v[84:87]
	v_mfma_f32_16x16x32_bf16 v[68:71], v[178:181], v[238:241], v[68:71]
	v_mfma_f32_16x16x32_bf16 v[68:71], v[182:185], v[242:245], v[68:71]
	v_mfma_f32_16x16x32_bf16 v[112:115], v[186:189], v[214:217], v[112:115]
	v_mfma_f32_16x16x32_bf16 v[112:115], v[210:213], v[218:221], v[112:115]
	v_mfma_f32_16x16x32_bf16 v[96:99], v[186:189], v[222:225], v[96:99]
	v_mfma_f32_16x16x32_bf16 v[96:99], v[210:213], v[226:229], v[96:99]
	v_mfma_f32_16x16x32_bf16 v[80:83], v[186:189], v[230:233], v[80:83]
	v_mfma_f32_16x16x32_bf16 v[80:83], v[210:213], v[234:237], v[80:83]
	v_mfma_f32_16x16x32_bf16 v[64:67], v[186:189], v[238:241], v[64:67]
	v_mfma_f32_16x16x32_bf16 v[64:67], v[210:213], v[242:245], v[64:67]
	s_setprio 0
	s_barrier
	s_mov_b32 m0, s43
	s_add_u32 s2, s2, 0x40080
	s_addc_u32 s3, s3, 0
	s_add_u32 s98, s2, 0xfffc0000
	s_addc_u32 s99, s3, -1
	ds_read_b128 v[214:217], v163 offset:49152
	ds_read_b128 v[218:221], v163 offset:50176
	global_load_lds_dwordx4 v132, s[98:99]
	s_mov_b32 m0, s44
	ds_read_b128 v[222:225], v163 offset:51200
	ds_read_b128 v[226:229], v163 offset:52224
	global_load_lds_dwordx4 v128, s[98:99]
	s_mov_b32 m0, s48
	ds_read_b128 v[230:233], v163 offset:53248
	global_load_lds_dwordx4 v132, s[2:3]
	s_mov_b32 m0, s49
	ds_read_b128 v[234:237], v163 offset:54272
	global_load_lds_dwordx4 v128, s[2:3]
	s_mov_b32 m0, s45
	s_add_u32 s100, s4, 0xfffc0080
	s_addc_u32 s101, s5, -1
	ds_read_b128 v[238:241], v163 offset:55296
	global_load_lds_dwordx4 v134, s[100:101]
	s_mov_b32 m0, s47
	ds_read_b128 v[242:245], v163 offset:56320
	global_load_lds_dwordx4 v130, s[100:101]
	s_waitcnt vmcnt(8) lgkmcnt(0)
	s_barrier
	s_setprio 1
	v_mfma_f32_16x16x32_bf16 v[60:63], v[140:143], v[214:217], v[60:63]
	v_mfma_f32_16x16x32_bf16 v[60:63], v[166:169], v[218:221], v[60:63]
	v_mfma_f32_16x16x32_bf16 v[44:47], v[140:143], v[222:225], v[44:47]
	v_mfma_f32_16x16x32_bf16 v[44:47], v[166:169], v[226:229], v[44:47]
	v_mfma_f32_16x16x32_bf16 v[28:31], v[140:143], v[230:233], v[28:31]
	v_mfma_f32_16x16x32_bf16 v[28:31], v[166:169], v[234:237], v[28:31]
	v_mfma_f32_16x16x32_bf16 v[12:15], v[140:143], v[238:241], v[12:15]
	v_mfma_f32_16x16x32_bf16 v[12:15], v[166:169], v[242:245], v[12:15]
	v_mfma_f32_16x16x32_bf16 v[56:59], v[170:173], v[214:217], v[56:59]
	v_mfma_f32_16x16x32_bf16 v[56:59], v[174:177], v[218:221], v[56:59]
	v_mfma_f32_16x16x32_bf16 v[40:43], v[170:173], v[222:225], v[40:43]
	v_mfma_f32_16x16x32_bf16 v[40:43], v[174:177], v[226:229], v[40:43]
	v_mfma_f32_16x16x32_bf16 v[24:27], v[170:173], v[230:233], v[24:27]
	v_mfma_f32_16x16x32_bf16 v[24:27], v[174:177], v[234:237], v[24:27]
	v_mfma_f32_16x16x32_bf16 v[8:11], v[170:173], v[238:241], v[8:11]
	v_mfma_f32_16x16x32_bf16 v[8:11], v[174:177], v[242:245], v[8:11]
	v_mfma_f32_16x16x32_bf16 v[52:55], v[178:181], v[214:217], v[52:55]
	v_mfma_f32_16x16x32_bf16 v[52:55], v[182:185], v[218:221], v[52:55]
	v_mfma_f32_16x16x32_bf16 v[36:39], v[178:181], v[222:225], v[36:39]
	v_mfma_f32_16x16x32_bf16 v[36:39], v[182:185], v[226:229], v[36:39]
	v_mfma_f32_16x16x32_bf16 v[20:23], v[178:181], v[230:233], v[20:23]
	v_mfma_f32_16x16x32_bf16 v[20:23], v[182:185], v[234:237], v[20:23]
	v_mfma_f32_16x16x32_bf16 v[4:7], v[178:181], v[238:241], v[4:7]
	v_mfma_f32_16x16x32_bf16 v[4:7], v[182:185], v[242:245], v[4:7]
	v_mfma_f32_16x16x32_bf16 v[48:51], v[186:189], v[214:217], v[48:51]
	v_mfma_f32_16x16x32_bf16 v[48:51], v[210:213], v[218:221], v[48:51]
	v_mfma_f32_16x16x32_bf16 v[32:35], v[186:189], v[222:225], v[32:35]
	v_mfma_f32_16x16x32_bf16 v[32:35], v[210:213], v[226:229], v[32:35]
	v_mfma_f32_16x16x32_bf16 v[16:19], v[186:189], v[230:233], v[16:19]
	v_mfma_f32_16x16x32_bf16 v[16:19], v[210:213], v[234:237], v[16:19]
	v_mfma_f32_16x16x32_bf16 v[0:3], v[186:189], v[238:241], v[0:3]
	v_mfma_f32_16x16x32_bf16 v[0:3], v[210:213], v[242:245], v[0:3]
	s_setprio 0
	s_barrier
	s_add_i32 s55, s55, 2
	s_add_u32 s0, s0, 0x100
	s_addc_u32 s1, s1, 0
	s_add_u32 s53, s53, 0x100
	s_addc_u32 s54, s54, 0
	s_cmp_gt_u32 s55, 13
	s_cbranch_scc0 .LBB0_1042
	s_and_b64 vcc, exec, s[18:19]
	s_cbranch_vccz .LBB0_1045
	s_barrier
